# saddr + MMA segment head trimmed (setprio hoisted above barrier, redundant lgkmcnt wait dropped)
# baseline (speedup 1.0000x reference)
.LBB0_170:
	ds_read_b128 v[136:139], v191
	ds_read_b128 v[158:161], v191 offset:1024
	ds_read_b128 v[162:165], v191 offset:2048
	ds_read_b128 v[166:169], v191 offset:3072
	ds_read_b128 v[170:173], v192
	ds_read_b128 v[174:177], v192 offset:1024
	ds_read_b128 v[178:181], v192 offset:2048
	ds_read_b128 v[194:197], v192 offset:3072
	s_add_u32 s0, s42, 0xfff00080
	s_addc_u32 s50, s43, -1
	s_cmp_eq_u32 s70, 60
	s_cselect_b32 s53, s23, s50
	s_cselect_b32 s52, s41, s0
	s_cselect_b32 s51, s21, s68
	s_cselect_b32 s50, s66, s67
	s_add_i32 m0, s31, 0xc000
	ds_read_b128 v[198:201], v193
	ds_read_b128 v[202:205], v193 offset:1024
	ds_read_b128 v[206:209], v193 offset:2048
	ds_read_b128 v[210:213], v193 offset:3072
	ds_read_b128 v[214:217], v193 offset:4096
	ds_read_b128 v[218:221], v193 offset:5120
	ds_read_b128 v[222:225], v193 offset:6144
	ds_read_b128 v[226:229], v193 offset:7168
	global_load_lds_dwordx4 v152, s[42:43]
	s_add_i32 m0, s31, 0xe000
	s_nop 0
	global_load_lds_dwordx4 v154, s[42:43]
	s_waitcnt vmcnt(8)
	s_waitcnt lgkmcnt(0)
	s_setprio 1
	s_barrier
	v_mfma_f32_16x16x32_bf16 v[132:135], v[136:139], v[198:201], v[132:135]
	v_mfma_f32_16x16x32_bf16 v[128:131], v[162:165], v[198:201], v[128:131]
	v_mfma_f32_16x16x32_bf16 v[116:119], v[136:139], v[206:209], v[116:119]
	v_mfma_f32_16x16x32_bf16 v[112:115], v[162:165], v[206:209], v[112:115]
	v_mfma_f32_16x16x32_bf16 v[100:103], v[136:139], v[214:217], v[100:103]
	v_mfma_f32_16x16x32_bf16 v[96:99], v[162:165], v[214:217], v[96:99]
	v_mfma_f32_16x16x32_bf16 v[84:87], v[136:139], v[222:225], v[84:87]
	v_mfma_f32_16x16x32_bf16 v[80:83], v[162:165], v[222:225], v[80:83]
	v_mfma_f32_16x16x32_bf16 v[132:135], v[158:161], v[202:205], v[132:135]
	v_mfma_f32_16x16x32_bf16 v[128:131], v[166:169], v[202:205], v[128:131]
	v_mfma_f32_16x16x32_bf16 v[116:119], v[158:161], v[210:213], v[116:119]
	v_mfma_f32_16x16x32_bf16 v[112:115], v[166:169], v[210:213], v[112:115]
	v_mfma_f32_16x16x32_bf16 v[100:103], v[158:161], v[218:221], v[100:103]
	v_mfma_f32_16x16x32_bf16 v[96:99], v[166:169], v[218:221], v[96:99]
	v_mfma_f32_16x16x32_bf16 v[84:87], v[158:161], v[226:229], v[84:87]
	v_mfma_f32_16x16x32_bf16 v[80:83], v[166:169], v[226:229], v[80:83]
	s_setprio 0
	s_setprio 1
	v_mfma_f32_16x16x32_bf16 v[124:127], v[170:173], v[198:201], v[124:127]
	v_mfma_f32_16x16x32_bf16 v[120:123], v[178:181], v[198:201], v[120:123]
	v_mfma_f32_16x16x32_bf16 v[108:111], v[170:173], v[206:209], v[108:111]
	v_mfma_f32_16x16x32_bf16 v[104:107], v[178:181], v[206:209], v[104:107]
	v_mfma_f32_16x16x32_bf16 v[92:95], v[170:173], v[214:217], v[92:95]
	v_mfma_f32_16x16x32_bf16 v[88:91], v[178:181], v[214:217], v[88:91]
	v_mfma_f32_16x16x32_bf16 v[76:79], v[170:173], v[222:225], v[76:79]
	v_mfma_f32_16x16x32_bf16 v[72:75], v[178:181], v[222:225], v[72:75]
	v_mfma_f32_16x16x32_bf16 v[124:127], v[174:177], v[202:205], v[124:127]
	v_mfma_f32_16x16x32_bf16 v[120:123], v[194:197], v[202:205], v[120:123]
	v_mfma_f32_16x16x32_bf16 v[108:111], v[174:177], v[210:213], v[108:111]
	v_mfma_f32_16x16x32_bf16 v[104:107], v[194:197], v[210:213], v[104:107]
	v_mfma_f32_16x16x32_bf16 v[92:95], v[174:177], v[218:221], v[92:95]
	v_mfma_f32_16x16x32_bf16 v[88:91], v[194:197], v[218:221], v[88:91]
	v_mfma_f32_16x16x32_bf16 v[76:79], v[174:177], v[226:229], v[76:79]
	v_mfma_f32_16x16x32_bf16 v[72:75], v[194:197], v[226:229], v[72:75]
	s_setprio 0
	s_barrier
	s_add_i32 s0, s61, s19
	s_mov_b32 m0, s0
	ds_read_b128 v[198:201], v193 offset:16384
	ds_read_b128 v[202:205], v193 offset:17408
	ds_read_b128 v[206:209], v193 offset:18432
	ds_read_b128 v[210:213], v193 offset:19456
	ds_read_b128 v[214:217], v193 offset:20480
	ds_read_b128 v[218:221], v193 offset:21504
	ds_read_b128 v[222:225], v193 offset:22528
	ds_read_b128 v[226:229], v193 offset:23552
	global_load_lds_dwordx4 v142, s[50:51]
	s_add_i32 m0, s0, 0x2000
	s_add_u32 s72, s50, 0x100000
	s_addc_u32 s73, s51, 0
	s_add_i32 s0, s62, s19
	global_load_lds_dwordx4 v146, s[50:51]
	s_mov_b32 m0, s0
	s_nop 0
	global_load_lds_dwordx4 v142, s[72:73]
	s_add_i32 m0, s0, 0x2000
	s_nop 0
	global_load_lds_dwordx4 v146, s[72:73]
	s_mov_b32 m0, s31
	s_nop 0
	global_load_lds_dwordx4 v140, s[52:53]
	s_mov_b32 m0, s35
	s_nop 0
	global_load_lds_dwordx4 v144, s[52:53]
	s_waitcnt vmcnt(8)
	s_waitcnt lgkmcnt(0)
	s_setprio 1
	s_barrier
	v_mfma_f32_16x16x32_bf16 v[68:71], v[136:139], v[198:201], v[68:71]
	v_mfma_f32_16x16x32_bf16 v[64:67], v[162:165], v[198:201], v[64:67]
	v_mfma_f32_16x16x32_bf16 v[52:55], v[136:139], v[206:209], v[52:55]
	v_mfma_f32_16x16x32_bf16 v[48:51], v[162:165], v[206:209], v[48:51]
	v_mfma_f32_16x16x32_bf16 v[36:39], v[136:139], v[214:217], v[36:39]
	v_mfma_f32_16x16x32_bf16 v[32:35], v[162:165], v[214:217], v[32:35]
	v_mfma_f32_16x16x32_bf16 v[20:23], v[136:139], v[222:225], v[20:23]
	v_mfma_f32_16x16x32_bf16 v[16:19], v[162:165], v[222:225], v[16:19]
	v_mfma_f32_16x16x32_bf16 v[68:71], v[158:161], v[202:205], v[68:71]
	v_mfma_f32_16x16x32_bf16 v[64:67], v[166:169], v[202:205], v[64:67]
	v_mfma_f32_16x16x32_bf16 v[52:55], v[158:161], v[210:213], v[52:55]
	v_mfma_f32_16x16x32_bf16 v[48:51], v[166:169], v[210:213], v[48:51]
	v_mfma_f32_16x16x32_bf16 v[36:39], v[158:161], v[218:221], v[36:39]
	v_mfma_f32_16x16x32_bf16 v[32:35], v[166:169], v[218:221], v[32:35]
	v_mfma_f32_16x16x32_bf16 v[20:23], v[158:161], v[226:229], v[20:23]
	v_mfma_f32_16x16x32_bf16 v[16:19], v[166:169], v[226:229], v[16:19]
	s_setprio 0
	s_setprio 1
	v_mfma_f32_16x16x32_bf16 v[60:63], v[170:173], v[198:201], v[60:63]
	v_mfma_f32_16x16x32_bf16 v[56:59], v[178:181], v[198:201], v[56:59]
	v_mfma_f32_16x16x32_bf16 v[44:47], v[170:173], v[206:209], v[44:47]
	v_mfma_f32_16x16x32_bf16 v[40:43], v[178:181], v[206:209], v[40:43]
	v_mfma_f32_16x16x32_bf16 v[28:31], v[170:173], v[214:217], v[28:31]
	v_mfma_f32_16x16x32_bf16 v[24:27], v[178:181], v[214:217], v[24:27]
	v_mfma_f32_16x16x32_bf16 v[12:15], v[170:173], v[222:225], v[12:15]
	v_mfma_f32_16x16x32_bf16 v[6:9], v[178:181], v[222:225], v[8:11]
	v_mfma_f32_16x16x32_bf16 v[60:63], v[174:177], v[202:205], v[60:63]
	v_mfma_f32_16x16x32_bf16 v[56:59], v[194:197], v[202:205], v[56:59]
	v_mfma_f32_16x16x32_bf16 v[44:47], v[174:177], v[210:213], v[44:47]
	v_mfma_f32_16x16x32_bf16 v[40:43], v[194:197], v[210:213], v[40:43]
	v_mfma_f32_16x16x32_bf16 v[28:31], v[174:177], v[218:221], v[28:31]
	v_mfma_f32_16x16x32_bf16 v[24:27], v[194:197], v[218:221], v[24:27]
	v_mfma_f32_16x16x32_bf16 v[12:15], v[174:177], v[226:229], v[12:15]
	v_mfma_f32_16x16x32_bf16 v[6:9], v[194:197], v[226:229], v[6:9]
	s_setprio 0
	s_barrier
	s_add_i32 s0, 0, 0x18000
	v_add_u32_e32 v5, s0, v1
	s_add_i32 s71, 0, 0x1c000
	ds_read_b128 v[136:139], v5
	ds_read_b128 v[158:161], v5 offset:1024
	ds_read_b128 v[162:165], v5 offset:2048
	ds_read_b128 v[166:169], v5 offset:3072
	v_add_u32_e32 v5, s71, v1
	ds_read_b128 v[170:173], v5
	ds_read_b128 v[174:177], v5 offset:1024
	ds_read_b128 v[178:181], v5 offset:2048
	ds_read_b128 v[194:197], v5 offset:3072
	s_add_u32 s98, s52, 0x100000
	s_addc_u32 s99, s53, 0
	s_mov_b32 m0, s45
	ds_read_b128 v[198:201], v193 offset:32768
	ds_read_b128 v[202:205], v193 offset:33792
	ds_read_b128 v[206:209], v193 offset:34816
	ds_read_b128 v[210:213], v193 offset:35840
	ds_read_b128 v[214:217], v193 offset:36864
	ds_read_b128 v[218:221], v193 offset:37888
	ds_read_b128 v[222:225], v193 offset:38912
	ds_read_b128 v[226:229], v193 offset:39936
	global_load_lds_dwordx4 v140, s[98:99]
	s_mov_b32 m0, s46
	s_nop 0
	global_load_lds_dwordx4 v144, s[98:99]
	s_waitcnt vmcnt(8)
	s_waitcnt lgkmcnt(0)
	s_setprio 1
	s_barrier
	v_mfma_f32_16x16x32_bf16 v[132:135], v[136:139], v[198:201], v[132:135]
	v_mfma_f32_16x16x32_bf16 v[128:131], v[162:165], v[198:201], v[128:131]
	v_mfma_f32_16x16x32_bf16 v[116:119], v[136:139], v[206:209], v[116:119]
	v_mfma_f32_16x16x32_bf16 v[112:115], v[162:165], v[206:209], v[112:115]
	v_mfma_f32_16x16x32_bf16 v[100:103], v[136:139], v[214:217], v[100:103]
	v_mfma_f32_16x16x32_bf16 v[96:99], v[162:165], v[214:217], v[96:99]
	v_mfma_f32_16x16x32_bf16 v[84:87], v[136:139], v[222:225], v[84:87]
	v_mfma_f32_16x16x32_bf16 v[80:83], v[162:165], v[222:225], v[80:83]
	v_mfma_f32_16x16x32_bf16 v[132:135], v[158:161], v[202:205], v[132:135]
	v_mfma_f32_16x16x32_bf16 v[128:131], v[166:169], v[202:205], v[128:131]
	v_mfma_f32_16x16x32_bf16 v[116:119], v[158:161], v[210:213], v[116:119]
	v_mfma_f32_16x16x32_bf16 v[112:115], v[166:169], v[210:213], v[112:115]
	v_mfma_f32_16x16x32_bf16 v[100:103], v[158:161], v[218:221], v[100:103]
	v_mfma_f32_16x16x32_bf16 v[96:99], v[166:169], v[218:221], v[96:99]
	v_mfma_f32_16x16x32_bf16 v[84:87], v[158:161], v[226:229], v[84:87]
	v_mfma_f32_16x16x32_bf16 v[80:83], v[166:169], v[226:229], v[80:83]
	s_setprio 0
	s_setprio 1
	v_mfma_f32_16x16x32_bf16 v[124:127], v[170:173], v[198:201], v[124:127]
	v_mfma_f32_16x16x32_bf16 v[120:123], v[178:181], v[198:201], v[120:123]
	v_mfma_f32_16x16x32_bf16 v[108:111], v[170:173], v[206:209], v[108:111]
	v_mfma_f32_16x16x32_bf16 v[104:107], v[178:181], v[206:209], v[104:107]
	v_mfma_f32_16x16x32_bf16 v[92:95], v[170:173], v[214:217], v[92:95]
	v_mfma_f32_16x16x32_bf16 v[88:91], v[178:181], v[214:217], v[88:91]
	v_mfma_f32_16x16x32_bf16 v[76:79], v[170:173], v[222:225], v[76:79]
	v_mfma_f32_16x16x32_bf16 v[72:75], v[178:181], v[222:225], v[72:75]
	v_mfma_f32_16x16x32_bf16 v[124:127], v[174:177], v[202:205], v[124:127]
	v_mfma_f32_16x16x32_bf16 v[120:123], v[194:197], v[202:205], v[120:123]
	v_mfma_f32_16x16x32_bf16 v[108:111], v[174:177], v[210:213], v[108:111]
	v_mfma_f32_16x16x32_bf16 v[104:107], v[194:197], v[210:213], v[104:107]
	v_mfma_f32_16x16x32_bf16 v[92:95], v[174:177], v[218:221], v[92:95]
	v_mfma_f32_16x16x32_bf16 v[88:91], v[194:197], v[218:221], v[88:91]
	v_mfma_f32_16x16x32_bf16 v[76:79], v[174:177], v[226:229], v[76:79]
	v_mfma_f32_16x16x32_bf16 v[72:75], v[194:197], v[226:229], v[72:75]
	s_setprio 0
	s_barrier
	s_add_i32 s0, s0, s19
	s_add_i32 m0, s0, 0xffffff80
	ds_read_b128 v[198:201], v193 offset:49152
	ds_read_b128 v[202:205], v193 offset:50176
	ds_read_b128 v[206:209], v193 offset:51200
	ds_read_b128 v[210:213], v193 offset:52224
	ds_read_b128 v[214:217], v193 offset:53248
	ds_read_b128 v[218:221], v193 offset:54272
	ds_read_b128 v[222:225], v193 offset:55296
	ds_read_b128 v[226:229], v193 offset:56320
	global_load_lds_dwordx4 v142, s[50:51] offset:128
	s_add_i32 m0, s0, 0x1f80
	s_add_i32 s0, s71, s19
	global_load_lds_dwordx4 v146, s[50:51] offset:128
	s_add_u32 s50, s50, 0x100080
	s_addc_u32 s51, s51, 0
	s_mov_b32 m0, s0
	s_nop 0
	global_load_lds_dwordx4 v142, s[50:51]
	s_add_i32 m0, s0, 0x2000
	s_nop 0
	global_load_lds_dwordx4 v146, s[50:51]
	s_add_i32 m0, s56, 0xffffff80
	s_nop 0
	global_load_lds_dwordx4 v140, s[52:53] offset:128
	s_add_i32 m0, s57, 0xffffff80
	s_nop 0
	global_load_lds_dwordx4 v144, s[52:53] offset:128
	s_waitcnt vmcnt(8)
	s_waitcnt lgkmcnt(0)
	s_setprio 1
	s_barrier
	v_mfma_f32_16x16x32_bf16 v[68:71], v[136:139], v[198:201], v[68:71]
	v_mfma_f32_16x16x32_bf16 v[64:67], v[162:165], v[198:201], v[64:67]
	v_mfma_f32_16x16x32_bf16 v[52:55], v[136:139], v[206:209], v[52:55]
	v_mfma_f32_16x16x32_bf16 v[48:51], v[162:165], v[206:209], v[48:51]
	v_mfma_f32_16x16x32_bf16 v[36:39], v[136:139], v[214:217], v[36:39]
	v_mfma_f32_16x16x32_bf16 v[32:35], v[162:165], v[214:217], v[32:35]
	v_mfma_f32_16x16x32_bf16 v[20:23], v[136:139], v[222:225], v[20:23]
	v_mfma_f32_16x16x32_bf16 v[16:19], v[162:165], v[222:225], v[16:19]
	v_mfma_f32_16x16x32_bf16 v[68:71], v[158:161], v[202:205], v[68:71]
	v_mfma_f32_16x16x32_bf16 v[64:67], v[166:169], v[202:205], v[64:67]
	v_mfma_f32_16x16x32_bf16 v[52:55], v[158:161], v[210:213], v[52:55]
	v_mfma_f32_16x16x32_bf16 v[48:51], v[166:169], v[210:213], v[48:51]
	v_mfma_f32_16x16x32_bf16 v[36:39], v[158:161], v[218:221], v[36:39]
	v_mfma_f32_16x16x32_bf16 v[32:35], v[166:169], v[218:221], v[32:35]
	v_mfma_f32_16x16x32_bf16 v[20:23], v[158:161], v[226:229], v[20:23]
	v_mfma_f32_16x16x32_bf16 v[16:19], v[166:169], v[226:229], v[16:19]
	s_setprio 0
	s_setprio 1
	v_mfma_f32_16x16x32_bf16 v[60:63], v[170:173], v[198:201], v[60:63]
	v_mfma_f32_16x16x32_bf16 v[56:59], v[178:181], v[198:201], v[56:59]
	v_mfma_f32_16x16x32_bf16 v[44:47], v[170:173], v[206:209], v[44:47]
	v_mfma_f32_16x16x32_bf16 v[40:43], v[178:181], v[206:209], v[40:43]
	v_mfma_f32_16x16x32_bf16 v[28:31], v[170:173], v[214:217], v[28:31]
	v_mfma_f32_16x16x32_bf16 v[24:27], v[178:181], v[214:217], v[24:27]
	v_mfma_f32_16x16x32_bf16 v[10:13], v[170:173], v[222:225], v[12:15]
	v_mfma_f32_16x16x32_bf16 v[6:9], v[178:181], v[222:225], v[6:9]
	v_mfma_f32_16x16x32_bf16 v[60:63], v[174:177], v[202:205], v[60:63]
	v_mfma_f32_16x16x32_bf16 v[56:59], v[194:197], v[202:205], v[56:59]
	v_mfma_f32_16x16x32_bf16 v[44:47], v[174:177], v[210:213], v[44:47]
	v_mfma_f32_16x16x32_bf16 v[40:43], v[194:197], v[210:213], v[40:43]
	v_mfma_f32_16x16x32_bf16 v[28:31], v[174:177], v[218:221], v[28:31]
	v_mfma_f32_16x16x32_bf16 v[24:27], v[194:197], v[218:221], v[24:27]
	v_mfma_f32_16x16x32_bf16 v[12:15], v[174:177], v[226:229], v[10:13]
	v_mfma_f32_16x16x32_bf16 v[8:11], v[194:197], v[226:229], v[6:9]
	s_setprio 0
	s_barrier
	s_add_i32 s70, s70, 2
	s_add_u32 s42, s42, 0x100
	s_addc_u32 s43, s43, 0
	s_add_u32 s67, s67, 0x100
	s_addc_u32 s68, s68, 0
	s_cmp_gt_u32 s70, 61
	s_cbranch_scc0 .LBB0_170
	s_and_b64 vcc, exec, s[16:17]
	s_cbranch_vccz .LBB0_173
	s_barrier

.LBB0_342:
	ds_read_b128 v[132:135], v209
	ds_read_b128 v[136:139], v209 offset:1024
	ds_read_b128 v[140:143], v209 offset:2048
	ds_read_b128 v[144:147], v209 offset:3072
	ds_read_b128 v[148:151], v210
	ds_read_b128 v[152:155], v210 offset:1024
	ds_read_b128 v[156:159], v210 offset:2048
	ds_read_b128 v[160:163], v210 offset:3072
	s_add_u32 s0, s26, 0xffd50080
	s_addc_u32 s28, s27, -1
	s_cmpk_eq_i32 s62, 0xa8
	s_cselect_b32 s31, s7, s28
	s_cselect_b32 s30, s6, s0
	s_cselect_b32 s29, s25, s61
	s_cselect_b32 s28, s24, s60
	s_add_i32 m0, s43, 0xc000
	ds_read_b128 v[164:167], v211
	ds_read_b128 v[168:171], v211 offset:1024
	ds_read_b128 v[172:175], v211 offset:2048
	ds_read_b128 v[176:179], v211 offset:3072
	ds_read_b128 v[196:199], v211 offset:4096
	ds_read_b128 v[200:203], v211 offset:5120
	ds_read_b128 v[204:207], v211 offset:6144
	ds_read_b128 v[214:217], v211 offset:7168
	global_load_lds_dwordx4 v188, s[26:27]
	s_add_i32 m0, s43, 0xe000
	s_nop 0
	global_load_lds_dwordx4 v190, s[26:27]
	s_waitcnt vmcnt(8)
	s_waitcnt lgkmcnt(0)
	s_setprio 1
	s_barrier
	v_mfma_f32_16x16x32_bf16 v[128:131], v[132:135], v[164:167], v[128:131]
	v_mfma_f32_16x16x32_bf16 v[124:127], v[140:143], v[164:167], v[124:127]
	v_mfma_f32_16x16x32_bf16 v[112:115], v[132:135], v[172:175], v[112:115]
	v_mfma_f32_16x16x32_bf16 v[108:111], v[140:143], v[172:175], v[108:111]
	v_mfma_f32_16x16x32_bf16 v[96:99], v[132:135], v[196:199], v[96:99]
	v_mfma_f32_16x16x32_bf16 v[92:95], v[140:143], v[196:199], v[92:95]
	v_mfma_f32_16x16x32_bf16 v[80:83], v[132:135], v[204:207], v[80:83]
	v_mfma_f32_16x16x32_bf16 v[76:79], v[140:143], v[204:207], v[76:79]
	v_mfma_f32_16x16x32_bf16 v[128:131], v[136:139], v[168:171], v[128:131]
	v_mfma_f32_16x16x32_bf16 v[124:127], v[144:147], v[168:171], v[124:127]
	v_mfma_f32_16x16x32_bf16 v[112:115], v[136:139], v[176:179], v[112:115]
	v_mfma_f32_16x16x32_bf16 v[108:111], v[144:147], v[176:179], v[108:111]
	v_mfma_f32_16x16x32_bf16 v[96:99], v[136:139], v[200:203], v[96:99]
	v_mfma_f32_16x16x32_bf16 v[92:95], v[144:147], v[200:203], v[92:95]
	v_mfma_f32_16x16x32_bf16 v[80:83], v[136:139], v[214:217], v[80:83]
	v_mfma_f32_16x16x32_bf16 v[76:79], v[144:147], v[214:217], v[76:79]
	s_setprio 0
	s_setprio 1
	v_mfma_f32_16x16x32_bf16 v[120:123], v[148:151], v[164:167], v[120:123]
	v_mfma_f32_16x16x32_bf16 v[116:119], v[156:159], v[164:167], v[116:119]
	v_mfma_f32_16x16x32_bf16 v[104:107], v[148:151], v[172:175], v[104:107]
	v_mfma_f32_16x16x32_bf16 v[100:103], v[156:159], v[172:175], v[100:103]
	v_mfma_f32_16x16x32_bf16 v[88:91], v[148:151], v[196:199], v[88:91]
	v_mfma_f32_16x16x32_bf16 v[84:87], v[156:159], v[196:199], v[84:87]
	v_mfma_f32_16x16x32_bf16 v[72:75], v[148:151], v[204:207], v[72:75]
	v_mfma_f32_16x16x32_bf16 v[68:71], v[156:159], v[204:207], v[68:71]
	v_mfma_f32_16x16x32_bf16 v[120:123], v[152:155], v[168:171], v[120:123]
	v_mfma_f32_16x16x32_bf16 v[116:119], v[160:163], v[168:171], v[116:119]
	v_mfma_f32_16x16x32_bf16 v[104:107], v[152:155], v[176:179], v[104:107]
	v_mfma_f32_16x16x32_bf16 v[100:103], v[160:163], v[176:179], v[100:103]
	v_mfma_f32_16x16x32_bf16 v[88:91], v[152:155], v[200:203], v[88:91]
	v_mfma_f32_16x16x32_bf16 v[84:87], v[160:163], v[200:203], v[84:87]
	v_mfma_f32_16x16x32_bf16 v[72:75], v[152:155], v[214:217], v[72:75]
	v_mfma_f32_16x16x32_bf16 v[68:71], v[160:163], v[214:217], v[68:71]
	s_setprio 0
	s_barrier
	s_add_i32 s0, s53, s42
	s_mov_b32 m0, s0
	ds_read_b128 v[164:167], v211 offset:16384
	ds_read_b128 v[168:171], v211 offset:17408
	ds_read_b128 v[172:175], v211 offset:18432
	ds_read_b128 v[176:179], v211 offset:19456
	ds_read_b128 v[196:199], v211 offset:20480
	ds_read_b128 v[200:203], v211 offset:21504
	ds_read_b128 v[204:207], v211 offset:22528
	ds_read_b128 v[214:217], v211 offset:23552
	global_load_lds_dwordx4 v182, s[28:29]
	s_add_i32 m0, s0, 0x2000
	s_add_u32 s64, s28, 0x2b0000
	s_addc_u32 s65, s29, 0
	s_add_i32 s0, s54, s42
	global_load_lds_dwordx4 v186, s[28:29]
	s_mov_b32 m0, s0
	s_nop 0
	global_load_lds_dwordx4 v182, s[64:65]
	s_add_i32 m0, s0, 0x2000
	s_nop 0
	global_load_lds_dwordx4 v186, s[64:65]
	s_mov_b32 m0, s43
	s_nop 0
	global_load_lds_dwordx4 v180, s[30:31]
	s_mov_b32 m0, s45
	s_nop 0
	global_load_lds_dwordx4 v184, s[30:31]
	s_waitcnt vmcnt(8)
	s_waitcnt lgkmcnt(0)
	s_setprio 1
	s_barrier
	v_mfma_f32_16x16x32_bf16 v[64:67], v[132:135], v[164:167], v[64:67]
	v_mfma_f32_16x16x32_bf16 v[60:63], v[140:143], v[164:167], v[60:63]
	v_mfma_f32_16x16x32_bf16 v[48:51], v[132:135], v[172:175], v[48:51]
	v_mfma_f32_16x16x32_bf16 v[44:47], v[140:143], v[172:175], v[44:47]
	v_mfma_f32_16x16x32_bf16 v[32:35], v[132:135], v[196:199], v[32:35]
	v_mfma_f32_16x16x32_bf16 v[28:31], v[140:143], v[196:199], v[28:31]
	v_mfma_f32_16x16x32_bf16 v[16:19], v[132:135], v[204:207], v[16:19]
	v_mfma_f32_16x16x32_bf16 v[12:15], v[140:143], v[204:207], v[12:15]
	v_mfma_f32_16x16x32_bf16 v[64:67], v[136:139], v[168:171], v[64:67]
	v_mfma_f32_16x16x32_bf16 v[60:63], v[144:147], v[168:171], v[60:63]
	v_mfma_f32_16x16x32_bf16 v[48:51], v[136:139], v[176:179], v[48:51]
	v_mfma_f32_16x16x32_bf16 v[44:47], v[144:147], v[176:179], v[44:47]
	v_mfma_f32_16x16x32_bf16 v[32:35], v[136:139], v[200:203], v[32:35]
	v_mfma_f32_16x16x32_bf16 v[28:31], v[144:147], v[200:203], v[28:31]
	v_mfma_f32_16x16x32_bf16 v[16:19], v[136:139], v[214:217], v[16:19]
	v_mfma_f32_16x16x32_bf16 v[12:15], v[144:147], v[214:217], v[12:15]
	s_setprio 0
	s_setprio 1
	v_mfma_f32_16x16x32_bf16 v[56:59], v[148:151], v[164:167], v[56:59]
	v_mfma_f32_16x16x32_bf16 v[52:55], v[156:159], v[164:167], v[52:55]
	v_mfma_f32_16x16x32_bf16 v[40:43], v[148:151], v[172:175], v[40:43]
	v_mfma_f32_16x16x32_bf16 v[36:39], v[156:159], v[172:175], v[36:39]
	v_mfma_f32_16x16x32_bf16 v[24:27], v[148:151], v[196:199], v[24:27]
	v_mfma_f32_16x16x32_bf16 v[20:23], v[156:159], v[196:199], v[20:23]
	v_mfma_f32_16x16x32_bf16 v[8:11], v[148:151], v[204:207], v[8:11]
	v_mfma_f32_16x16x32_bf16 v[4:7], v[156:159], v[204:207], v[4:7]
	v_mfma_f32_16x16x32_bf16 v[56:59], v[152:155], v[168:171], v[56:59]
	v_mfma_f32_16x16x32_bf16 v[52:55], v[160:163], v[168:171], v[52:55]
	v_mfma_f32_16x16x32_bf16 v[40:43], v[152:155], v[176:179], v[40:43]
	v_mfma_f32_16x16x32_bf16 v[36:39], v[160:163], v[176:179], v[36:39]
	v_mfma_f32_16x16x32_bf16 v[24:27], v[152:155], v[200:203], v[24:27]
	v_mfma_f32_16x16x32_bf16 v[20:23], v[160:163], v[200:203], v[20:23]
	v_mfma_f32_16x16x32_bf16 v[8:11], v[152:155], v[214:217], v[8:11]
	v_mfma_f32_16x16x32_bf16 v[4:7], v[160:163], v[214:217], v[4:7]
	s_setprio 0
	s_barrier
	s_add_i32 s0, 0, 0x18000
	s_add_i32 s63, 0, 0x1c000
	v_add_u32_e32 v144, s0, v3
	v_add_u32_e32 v160, s63, v3
	ds_read_b128 v[132:135], v144
	ds_read_b128 v[136:139], v144 offset:1024
	ds_read_b128 v[140:143], v144 offset:2048
	ds_read_b128 v[144:147], v144 offset:3072
	ds_read_b128 v[148:151], v160
	ds_read_b128 v[152:155], v160 offset:1024
	ds_read_b128 v[156:159], v160 offset:2048
	ds_read_b128 v[160:163], v160 offset:3072
	s_add_u32 s98, s30, 0x2b0000
	s_addc_u32 s99, s31, 0
	s_mov_b32 m0, s46
	ds_read_b128 v[164:167], v211 offset:32768
	ds_read_b128 v[168:171], v211 offset:33792
	ds_read_b128 v[172:175], v211 offset:34816
	ds_read_b128 v[176:179], v211 offset:35840
	ds_read_b128 v[196:199], v211 offset:36864
	ds_read_b128 v[200:203], v211 offset:37888
	ds_read_b128 v[204:207], v211 offset:38912
	ds_read_b128 v[214:217], v211 offset:39936
	global_load_lds_dwordx4 v180, s[98:99]
	s_mov_b32 m0, s47
	s_nop 0
	global_load_lds_dwordx4 v184, s[98:99]
	s_waitcnt vmcnt(8)
	s_waitcnt lgkmcnt(0)
	s_setprio 1
	s_barrier
	v_mfma_f32_16x16x32_bf16 v[128:131], v[132:135], v[164:167], v[128:131]
	v_mfma_f32_16x16x32_bf16 v[124:127], v[140:143], v[164:167], v[124:127]
	v_mfma_f32_16x16x32_bf16 v[112:115], v[132:135], v[172:175], v[112:115]
	v_mfma_f32_16x16x32_bf16 v[108:111], v[140:143], v[172:175], v[108:111]
	v_mfma_f32_16x16x32_bf16 v[96:99], v[132:135], v[196:199], v[96:99]
	v_mfma_f32_16x16x32_bf16 v[92:95], v[140:143], v[196:199], v[92:95]
	v_mfma_f32_16x16x32_bf16 v[80:83], v[132:135], v[204:207], v[80:83]
	v_mfma_f32_16x16x32_bf16 v[76:79], v[140:143], v[204:207], v[76:79]
	v_mfma_f32_16x16x32_bf16 v[128:131], v[136:139], v[168:171], v[128:131]
	v_mfma_f32_16x16x32_bf16 v[124:127], v[144:147], v[168:171], v[124:127]
	v_mfma_f32_16x16x32_bf16 v[112:115], v[136:139], v[176:179], v[112:115]
	v_mfma_f32_16x16x32_bf16 v[108:111], v[144:147], v[176:179], v[108:111]
	v_mfma_f32_16x16x32_bf16 v[96:99], v[136:139], v[200:203], v[96:99]
	v_mfma_f32_16x16x32_bf16 v[92:95], v[144:147], v[200:203], v[92:95]
	v_mfma_f32_16x16x32_bf16 v[80:83], v[136:139], v[214:217], v[80:83]
	v_mfma_f32_16x16x32_bf16 v[76:79], v[144:147], v[214:217], v[76:79]
	s_setprio 0
	s_setprio 1
	v_mfma_f32_16x16x32_bf16 v[120:123], v[148:151], v[164:167], v[120:123]
	v_mfma_f32_16x16x32_bf16 v[116:119], v[156:159], v[164:167], v[116:119]
	v_mfma_f32_16x16x32_bf16 v[104:107], v[148:151], v[172:175], v[104:107]
	v_mfma_f32_16x16x32_bf16 v[100:103], v[156:159], v[172:175], v[100:103]
	v_mfma_f32_16x16x32_bf16 v[88:91], v[148:151], v[196:199], v[88:91]
	v_mfma_f32_16x16x32_bf16 v[84:87], v[156:159], v[196:199], v[84:87]
	v_mfma_f32_16x16x32_bf16 v[72:75], v[148:151], v[204:207], v[72:75]
	v_mfma_f32_16x16x32_bf16 v[68:71], v[156:159], v[204:207], v[68:71]
	v_mfma_f32_16x16x32_bf16 v[120:123], v[152:155], v[168:171], v[120:123]
	v_mfma_f32_16x16x32_bf16 v[116:119], v[160:163], v[168:171], v[116:119]
	v_mfma_f32_16x16x32_bf16 v[104:107], v[152:155], v[176:179], v[104:107]
	v_mfma_f32_16x16x32_bf16 v[100:103], v[160:163], v[176:179], v[100:103]
	v_mfma_f32_16x16x32_bf16 v[88:91], v[152:155], v[200:203], v[88:91]
	v_mfma_f32_16x16x32_bf16 v[84:87], v[160:163], v[200:203], v[84:87]
	v_mfma_f32_16x16x32_bf16 v[72:75], v[152:155], v[214:217], v[72:75]
	v_mfma_f32_16x16x32_bf16 v[68:71], v[160:163], v[214:217], v[68:71]
	s_setprio 0
	s_barrier
	s_add_i32 s0, s0, s42
	s_add_i32 m0, s0, 0xffffff80
	ds_read_b128 v[164:167], v211 offset:49152
	ds_read_b128 v[168:171], v211 offset:50176
	ds_read_b128 v[172:175], v211 offset:51200
	ds_read_b128 v[176:179], v211 offset:52224
	ds_read_b128 v[196:199], v211 offset:53248
	ds_read_b128 v[200:203], v211 offset:54272
	ds_read_b128 v[204:207], v211 offset:55296
	ds_read_b128 v[214:217], v211 offset:56320
	global_load_lds_dwordx4 v182, s[28:29] offset:128
	s_add_i32 m0, s0, 0x1f80
	s_add_i32 s0, s63, s42
	global_load_lds_dwordx4 v186, s[28:29] offset:128
	s_add_u32 s28, s28, 0x2b0080
	s_addc_u32 s29, s29, 0
	s_mov_b32 m0, s0
	s_nop 0
	global_load_lds_dwordx4 v182, s[28:29]
	s_add_i32 m0, s0, 0x2000
	s_nop 0
	global_load_lds_dwordx4 v186, s[28:29]
	s_add_i32 m0, s51, 0xffffff80
	s_nop 0
	global_load_lds_dwordx4 v180, s[30:31] offset:128
	s_add_i32 m0, s52, 0xffffff80
	s_nop 0
	global_load_lds_dwordx4 v184, s[30:31] offset:128
	s_waitcnt vmcnt(8)
	s_waitcnt lgkmcnt(0)
	s_setprio 1
	s_barrier
	v_mfma_f32_16x16x32_bf16 v[64:67], v[132:135], v[164:167], v[64:67]
	v_mfma_f32_16x16x32_bf16 v[60:63], v[140:143], v[164:167], v[60:63]
	v_mfma_f32_16x16x32_bf16 v[48:51], v[132:135], v[172:175], v[48:51]
	v_mfma_f32_16x16x32_bf16 v[44:47], v[140:143], v[172:175], v[44:47]
	v_mfma_f32_16x16x32_bf16 v[32:35], v[132:135], v[196:199], v[32:35]
	v_mfma_f32_16x16x32_bf16 v[28:31], v[140:143], v[196:199], v[28:31]
	v_mfma_f32_16x16x32_bf16 v[16:19], v[132:135], v[204:207], v[16:19]
	v_mfma_f32_16x16x32_bf16 v[12:15], v[140:143], v[204:207], v[12:15]
	v_mfma_f32_16x16x32_bf16 v[64:67], v[136:139], v[168:171], v[64:67]
	v_mfma_f32_16x16x32_bf16 v[60:63], v[144:147], v[168:171], v[60:63]
	v_mfma_f32_16x16x32_bf16 v[48:51], v[136:139], v[176:179], v[48:51]
	v_mfma_f32_16x16x32_bf16 v[44:47], v[144:147], v[176:179], v[44:47]
	v_mfma_f32_16x16x32_bf16 v[32:35], v[136:139], v[200:203], v[32:35]
	v_mfma_f32_16x16x32_bf16 v[28:31], v[144:147], v[200:203], v[28:31]
	v_mfma_f32_16x16x32_bf16 v[16:19], v[136:139], v[214:217], v[16:19]
	v_mfma_f32_16x16x32_bf16 v[12:15], v[144:147], v[214:217], v[12:15]
	s_setprio 0
	s_setprio 1
	v_mfma_f32_16x16x32_bf16 v[56:59], v[148:151], v[164:167], v[56:59]
	v_mfma_f32_16x16x32_bf16 v[52:55], v[156:159], v[164:167], v[52:55]
	v_mfma_f32_16x16x32_bf16 v[40:43], v[148:151], v[172:175], v[40:43]
	v_mfma_f32_16x16x32_bf16 v[36:39], v[156:159], v[172:175], v[36:39]
	v_mfma_f32_16x16x32_bf16 v[24:27], v[148:151], v[196:199], v[24:27]
	v_mfma_f32_16x16x32_bf16 v[20:23], v[156:159], v[196:199], v[20:23]
	v_mfma_f32_16x16x32_bf16 v[8:11], v[148:151], v[204:207], v[8:11]
	v_mfma_f32_16x16x32_bf16 v[4:7], v[156:159], v[204:207], v[4:7]
	v_mfma_f32_16x16x32_bf16 v[56:59], v[152:155], v[168:171], v[56:59]
	v_mfma_f32_16x16x32_bf16 v[52:55], v[160:163], v[168:171], v[52:55]
	v_mfma_f32_16x16x32_bf16 v[40:43], v[152:155], v[176:179], v[40:43]
	v_mfma_f32_16x16x32_bf16 v[36:39], v[160:163], v[176:179], v[36:39]
	v_mfma_f32_16x16x32_bf16 v[24:27], v[152:155], v[200:203], v[24:27]
	v_mfma_f32_16x16x32_bf16 v[20:23], v[160:163], v[200:203], v[20:23]
	v_mfma_f32_16x16x32_bf16 v[8:11], v[152:155], v[214:217], v[8:11]
	v_mfma_f32_16x16x32_bf16 v[4:7], v[160:163], v[214:217], v[4:7]
	s_setprio 0
	s_barrier
	s_add_i32 s62, s62, 2
	s_add_u32 s26, s26, 0x100
	s_addc_u32 s27, s27, 0
	s_add_u32 s60, s60, 0x100
	s_addc_u32 s61, s61, 0
	s_cmpk_gt_u32 s62, 0xa9
	s_cbranch_scc0 .LBB0_342
	s_and_b64 vcc, exec, s[22:23]
	s_cbranch_vccz .LBB0_345
	s_barrier

.LBB0_429:
	ds_read_b128 v[150:153], v156
	ds_read_b128 v[162:165], v156 offset:1024
	ds_read_b128 v[166:169], v156 offset:2048
	ds_read_b128 v[170:173], v156 offset:3072
	ds_read_b128 v[174:177], v157
	ds_read_b128 v[178:181], v157 offset:1024
	ds_read_b128 v[182:185], v157 offset:2048
	ds_read_b128 v[186:189], v157 offset:3072
	s_add_u32 s0, s50, 0xfff00080
	s_addc_u32 s52, s51, -1
	s_cmp_eq_u32 s72, 60
	s_cselect_b32 s55, s27, s52
	s_cselect_b32 s54, s67, s0
	s_cselect_b32 s53, s25, s71
	s_cselect_b32 s52, s68, s70
	s_add_i32 m0, s43, 0xc000
	ds_read_b128 v[190:193], v158
	ds_read_b128 v[194:197], v158 offset:1024
	ds_read_b128 v[198:201], v158 offset:2048
	ds_read_b128 v[202:205], v158 offset:3072
	ds_read_b128 v[206:209], v158 offset:4096
	ds_read_b128 v[210:213], v158 offset:5120
	ds_read_b128 v[214:217], v158 offset:6144
	ds_read_b128 v[218:221], v158 offset:7168
	global_load_lds_dwordx4 v142, s[50:51]
	s_add_i32 m0, s43, 0xe000
	s_nop 0
	global_load_lds_dwordx4 v144, s[50:51]
	s_waitcnt vmcnt(8)
	s_waitcnt lgkmcnt(0)
	s_setprio 1
	s_barrier
	v_mfma_f32_16x16x32_bf16 v[128:131], v[150:153], v[190:193], v[128:131]
	v_mfma_f32_16x16x32_bf16 v[124:127], v[166:169], v[190:193], v[124:127]
	v_mfma_f32_16x16x32_bf16 v[112:115], v[150:153], v[198:201], v[112:115]
	v_mfma_f32_16x16x32_bf16 v[108:111], v[166:169], v[198:201], v[108:111]
	v_mfma_f32_16x16x32_bf16 v[96:99], v[150:153], v[206:209], v[96:99]
	v_mfma_f32_16x16x32_bf16 v[92:95], v[166:169], v[206:209], v[92:95]
	v_mfma_f32_16x16x32_bf16 v[80:83], v[150:153], v[214:217], v[80:83]
	v_mfma_f32_16x16x32_bf16 v[76:79], v[166:169], v[214:217], v[76:79]
	v_mfma_f32_16x16x32_bf16 v[128:131], v[162:165], v[194:197], v[128:131]
	v_mfma_f32_16x16x32_bf16 v[124:127], v[170:173], v[194:197], v[124:127]
	v_mfma_f32_16x16x32_bf16 v[112:115], v[162:165], v[202:205], v[112:115]
	v_mfma_f32_16x16x32_bf16 v[108:111], v[170:173], v[202:205], v[108:111]
	v_mfma_f32_16x16x32_bf16 v[96:99], v[162:165], v[210:213], v[96:99]
	v_mfma_f32_16x16x32_bf16 v[92:95], v[170:173], v[210:213], v[92:95]
	v_mfma_f32_16x16x32_bf16 v[80:83], v[162:165], v[218:221], v[80:83]
	v_mfma_f32_16x16x32_bf16 v[76:79], v[170:173], v[218:221], v[76:79]
	s_setprio 0
	s_setprio 1
	v_mfma_f32_16x16x32_bf16 v[120:123], v[174:177], v[190:193], v[120:123]
	v_mfma_f32_16x16x32_bf16 v[116:119], v[182:185], v[190:193], v[116:119]
	v_mfma_f32_16x16x32_bf16 v[104:107], v[174:177], v[198:201], v[104:107]
	v_mfma_f32_16x16x32_bf16 v[100:103], v[182:185], v[198:201], v[100:103]
	v_mfma_f32_16x16x32_bf16 v[88:91], v[174:177], v[206:209], v[88:91]
	v_mfma_f32_16x16x32_bf16 v[84:87], v[182:185], v[206:209], v[84:87]
	v_mfma_f32_16x16x32_bf16 v[72:75], v[174:177], v[214:217], v[72:75]
	v_mfma_f32_16x16x32_bf16 v[68:71], v[182:185], v[214:217], v[68:71]
	v_mfma_f32_16x16x32_bf16 v[120:123], v[178:181], v[194:197], v[120:123]
	v_mfma_f32_16x16x32_bf16 v[116:119], v[186:189], v[194:197], v[116:119]
	v_mfma_f32_16x16x32_bf16 v[104:107], v[178:181], v[202:205], v[104:107]
	v_mfma_f32_16x16x32_bf16 v[100:103], v[186:189], v[202:205], v[100:103]
	v_mfma_f32_16x16x32_bf16 v[88:91], v[178:181], v[210:213], v[88:91]
	v_mfma_f32_16x16x32_bf16 v[84:87], v[186:189], v[210:213], v[84:87]
	v_mfma_f32_16x16x32_bf16 v[72:75], v[178:181], v[218:221], v[72:75]
	v_mfma_f32_16x16x32_bf16 v[68:71], v[186:189], v[218:221], v[68:71]
	s_setprio 0
	s_barrier
	s_add_i32 s0, s62, s41
	s_mov_b32 m0, s0
	ds_read_b128 v[190:193], v158 offset:16384
	ds_read_b128 v[194:197], v158 offset:17408
	ds_read_b128 v[198:201], v158 offset:18432
	ds_read_b128 v[202:205], v158 offset:19456
	ds_read_b128 v[206:209], v158 offset:20480
	ds_read_b128 v[210:213], v158 offset:21504
	ds_read_b128 v[214:217], v158 offset:22528
	ds_read_b128 v[218:221], v158 offset:23552
	global_load_lds_dwordx4 v136, s[52:53]
	s_add_i32 m0, s0, 0x2000
	s_add_u32 s74, s52, 0x100000
	s_addc_u32 s75, s53, 0
	s_add_i32 s0, s63, s41
	global_load_lds_dwordx4 v140, s[52:53]
	s_mov_b32 m0, s0
	s_nop 0
	global_load_lds_dwordx4 v136, s[74:75]
	s_add_i32 m0, s0, 0x2000
	s_nop 0
	global_load_lds_dwordx4 v140, s[74:75]
	s_mov_b32 m0, s43
	s_nop 0
	global_load_lds_dwordx4 v134, s[54:55]
	s_mov_b32 m0, s48
	s_nop 0
	global_load_lds_dwordx4 v138, s[54:55]
	s_waitcnt vmcnt(8)
	s_waitcnt lgkmcnt(0)
	s_setprio 1
	s_barrier
	v_mfma_f32_16x16x32_bf16 v[64:67], v[150:153], v[190:193], v[64:67]
	v_mfma_f32_16x16x32_bf16 v[60:63], v[166:169], v[190:193], v[60:63]
	v_mfma_f32_16x16x32_bf16 v[48:51], v[150:153], v[198:201], v[48:51]
	v_mfma_f32_16x16x32_bf16 v[44:47], v[166:169], v[198:201], v[44:47]
	v_mfma_f32_16x16x32_bf16 v[32:35], v[150:153], v[206:209], v[32:35]
	v_mfma_f32_16x16x32_bf16 v[28:31], v[166:169], v[206:209], v[28:31]
	v_mfma_f32_16x16x32_bf16 v[16:19], v[150:153], v[214:217], v[16:19]
	v_mfma_f32_16x16x32_bf16 v[12:15], v[166:169], v[214:217], v[12:15]
	v_mfma_f32_16x16x32_bf16 v[64:67], v[162:165], v[194:197], v[64:67]
	v_mfma_f32_16x16x32_bf16 v[60:63], v[170:173], v[194:197], v[60:63]
	v_mfma_f32_16x16x32_bf16 v[48:51], v[162:165], v[202:205], v[48:51]
	v_mfma_f32_16x16x32_bf16 v[44:47], v[170:173], v[202:205], v[44:47]
	v_mfma_f32_16x16x32_bf16 v[32:35], v[162:165], v[210:213], v[32:35]
	v_mfma_f32_16x16x32_bf16 v[28:31], v[170:173], v[210:213], v[28:31]
	v_mfma_f32_16x16x32_bf16 v[16:19], v[162:165], v[218:221], v[16:19]
	v_mfma_f32_16x16x32_bf16 v[12:15], v[170:173], v[218:221], v[12:15]
	s_setprio 0
	s_setprio 1
	v_mfma_f32_16x16x32_bf16 v[56:59], v[174:177], v[190:193], v[56:59]
	v_mfma_f32_16x16x32_bf16 v[52:55], v[182:185], v[190:193], v[52:55]
	v_mfma_f32_16x16x32_bf16 v[40:43], v[174:177], v[198:201], v[40:43]
	v_mfma_f32_16x16x32_bf16 v[36:39], v[182:185], v[198:201], v[36:39]
	v_mfma_f32_16x16x32_bf16 v[24:27], v[174:177], v[206:209], v[24:27]
	v_mfma_f32_16x16x32_bf16 v[20:23], v[182:185], v[206:209], v[20:23]
	v_mfma_f32_16x16x32_bf16 v[8:11], v[174:177], v[214:217], v[8:11]
	v_mfma_f32_16x16x32_bf16 v[4:7], v[182:185], v[214:217], v[4:7]
	v_mfma_f32_16x16x32_bf16 v[56:59], v[178:181], v[194:197], v[56:59]
	v_mfma_f32_16x16x32_bf16 v[52:55], v[186:189], v[194:197], v[52:55]
	v_mfma_f32_16x16x32_bf16 v[40:43], v[178:181], v[202:205], v[40:43]
	v_mfma_f32_16x16x32_bf16 v[36:39], v[186:189], v[202:205], v[36:39]
	v_mfma_f32_16x16x32_bf16 v[24:27], v[178:181], v[210:213], v[24:27]
	v_mfma_f32_16x16x32_bf16 v[20:23], v[186:189], v[210:213], v[20:23]
	v_mfma_f32_16x16x32_bf16 v[8:11], v[178:181], v[218:221], v[8:11]
	v_mfma_f32_16x16x32_bf16 v[4:7], v[186:189], v[218:221], v[4:7]
	s_setprio 0
	s_barrier
	s_add_i32 s0, 0, 0x18000
	v_add_u32_e32 v161, s0, v133
	s_add_i32 s73, 0, 0x1c000
	ds_read_b128 v[150:153], v161
	ds_read_b128 v[162:165], v161 offset:1024
	ds_read_b128 v[166:169], v161 offset:2048
	ds_read_b128 v[170:173], v161 offset:3072
	v_add_u32_e32 v161, s73, v133
	ds_read_b128 v[174:177], v161
	ds_read_b128 v[178:181], v161 offset:1024
	ds_read_b128 v[182:185], v161 offset:2048
	ds_read_b128 v[186:189], v161 offset:3072
	s_add_u32 s98, s54, 0x100000
	s_addc_u32 s99, s55, 0
	s_mov_b32 m0, s49
	ds_read_b128 v[190:193], v158 offset:32768
	ds_read_b128 v[194:197], v158 offset:33792
	ds_read_b128 v[198:201], v158 offset:34816
	ds_read_b128 v[202:205], v158 offset:35840
	ds_read_b128 v[206:209], v158 offset:36864
	ds_read_b128 v[210:213], v158 offset:37888
	ds_read_b128 v[214:217], v158 offset:38912
	ds_read_b128 v[218:221], v158 offset:39936
	global_load_lds_dwordx4 v134, s[98:99]
	s_mov_b32 m0, s56
	s_nop 0
	global_load_lds_dwordx4 v138, s[98:99]
	s_waitcnt vmcnt(8)
	s_waitcnt lgkmcnt(0)
	s_setprio 1
	s_barrier
	v_mfma_f32_16x16x32_bf16 v[128:131], v[150:153], v[190:193], v[128:131]
	v_mfma_f32_16x16x32_bf16 v[124:127], v[166:169], v[190:193], v[124:127]
	v_mfma_f32_16x16x32_bf16 v[112:115], v[150:153], v[198:201], v[112:115]
	v_mfma_f32_16x16x32_bf16 v[108:111], v[166:169], v[198:201], v[108:111]
	v_mfma_f32_16x16x32_bf16 v[96:99], v[150:153], v[206:209], v[96:99]
	v_mfma_f32_16x16x32_bf16 v[92:95], v[166:169], v[206:209], v[92:95]
	v_mfma_f32_16x16x32_bf16 v[80:83], v[150:153], v[214:217], v[80:83]
	v_mfma_f32_16x16x32_bf16 v[76:79], v[166:169], v[214:217], v[76:79]
	v_mfma_f32_16x16x32_bf16 v[128:131], v[162:165], v[194:197], v[128:131]
	v_mfma_f32_16x16x32_bf16 v[124:127], v[170:173], v[194:197], v[124:127]
	v_mfma_f32_16x16x32_bf16 v[112:115], v[162:165], v[202:205], v[112:115]
	v_mfma_f32_16x16x32_bf16 v[108:111], v[170:173], v[202:205], v[108:111]
	v_mfma_f32_16x16x32_bf16 v[96:99], v[162:165], v[210:213], v[96:99]
	v_mfma_f32_16x16x32_bf16 v[92:95], v[170:173], v[210:213], v[92:95]
	v_mfma_f32_16x16x32_bf16 v[80:83], v[162:165], v[218:221], v[80:83]
	v_mfma_f32_16x16x32_bf16 v[76:79], v[170:173], v[218:221], v[76:79]
	s_setprio 0
	s_setprio 1
	v_mfma_f32_16x16x32_bf16 v[120:123], v[174:177], v[190:193], v[120:123]
	v_mfma_f32_16x16x32_bf16 v[116:119], v[182:185], v[190:193], v[116:119]
	v_mfma_f32_16x16x32_bf16 v[104:107], v[174:177], v[198:201], v[104:107]
	v_mfma_f32_16x16x32_bf16 v[100:103], v[182:185], v[198:201], v[100:103]
	v_mfma_f32_16x16x32_bf16 v[88:91], v[174:177], v[206:209], v[88:91]
	v_mfma_f32_16x16x32_bf16 v[84:87], v[182:185], v[206:209], v[84:87]
	v_mfma_f32_16x16x32_bf16 v[72:75], v[174:177], v[214:217], v[72:75]
	v_mfma_f32_16x16x32_bf16 v[68:71], v[182:185], v[214:217], v[68:71]
	v_mfma_f32_16x16x32_bf16 v[120:123], v[178:181], v[194:197], v[120:123]
	v_mfma_f32_16x16x32_bf16 v[116:119], v[186:189], v[194:197], v[116:119]
	v_mfma_f32_16x16x32_bf16 v[104:107], v[178:181], v[202:205], v[104:107]
	v_mfma_f32_16x16x32_bf16 v[100:103], v[186:189], v[202:205], v[100:103]
	v_mfma_f32_16x16x32_bf16 v[88:91], v[178:181], v[210:213], v[88:91]
	v_mfma_f32_16x16x32_bf16 v[84:87], v[186:189], v[210:213], v[84:87]
	v_mfma_f32_16x16x32_bf16 v[72:75], v[178:181], v[218:221], v[72:75]
	v_mfma_f32_16x16x32_bf16 v[68:71], v[186:189], v[218:221], v[68:71]
	s_setprio 0
	s_barrier
	s_add_i32 s0, s0, s41
	s_add_i32 m0, s0, 0xffffff80
	ds_read_b128 v[190:193], v158 offset:49152
	ds_read_b128 v[194:197], v158 offset:50176
	ds_read_b128 v[198:201], v158 offset:51200
	ds_read_b128 v[202:205], v158 offset:52224
	ds_read_b128 v[206:209], v158 offset:53248
	ds_read_b128 v[210:213], v158 offset:54272
	ds_read_b128 v[214:217], v158 offset:55296
	ds_read_b128 v[218:221], v158 offset:56320
	global_load_lds_dwordx4 v136, s[52:53] offset:128
	s_add_i32 m0, s0, 0x1f80
	s_add_i32 s0, s73, s41
	global_load_lds_dwordx4 v140, s[52:53] offset:128
	s_add_u32 s52, s52, 0x100080
	s_addc_u32 s53, s53, 0
	s_mov_b32 m0, s0
	s_nop 0
	global_load_lds_dwordx4 v136, s[52:53]
	s_add_i32 m0, s0, 0x2000
	s_nop 0
	global_load_lds_dwordx4 v140, s[52:53]
	s_add_i32 m0, s59, 0xffffff80
	s_nop 0
	global_load_lds_dwordx4 v134, s[54:55] offset:128
	s_add_i32 m0, s60, 0xffffff80
	s_nop 0
	global_load_lds_dwordx4 v138, s[54:55] offset:128
	s_waitcnt vmcnt(8)
	s_waitcnt lgkmcnt(0)
	s_setprio 1
	s_barrier
	v_mfma_f32_16x16x32_bf16 v[64:67], v[150:153], v[190:193], v[64:67]
	v_mfma_f32_16x16x32_bf16 v[60:63], v[166:169], v[190:193], v[60:63]
	v_mfma_f32_16x16x32_bf16 v[48:51], v[150:153], v[198:201], v[48:51]
	v_mfma_f32_16x16x32_bf16 v[44:47], v[166:169], v[198:201], v[44:47]
	v_mfma_f32_16x16x32_bf16 v[32:35], v[150:153], v[206:209], v[32:35]
	v_mfma_f32_16x16x32_bf16 v[28:31], v[166:169], v[206:209], v[28:31]
	v_mfma_f32_16x16x32_bf16 v[16:19], v[150:153], v[214:217], v[16:19]
	v_mfma_f32_16x16x32_bf16 v[12:15], v[166:169], v[214:217], v[12:15]
	v_mfma_f32_16x16x32_bf16 v[64:67], v[162:165], v[194:197], v[64:67]
	v_mfma_f32_16x16x32_bf16 v[60:63], v[170:173], v[194:197], v[60:63]
	v_mfma_f32_16x16x32_bf16 v[48:51], v[162:165], v[202:205], v[48:51]
	v_mfma_f32_16x16x32_bf16 v[44:47], v[170:173], v[202:205], v[44:47]
	v_mfma_f32_16x16x32_bf16 v[32:35], v[162:165], v[210:213], v[32:35]
	v_mfma_f32_16x16x32_bf16 v[28:31], v[170:173], v[210:213], v[28:31]
	v_mfma_f32_16x16x32_bf16 v[16:19], v[162:165], v[218:221], v[16:19]
	v_mfma_f32_16x16x32_bf16 v[12:15], v[170:173], v[218:221], v[12:15]
	s_setprio 0
	s_setprio 1
	v_mfma_f32_16x16x32_bf16 v[56:59], v[174:177], v[190:193], v[56:59]
	v_mfma_f32_16x16x32_bf16 v[52:55], v[182:185], v[190:193], v[52:55]
	v_mfma_f32_16x16x32_bf16 v[40:43], v[174:177], v[198:201], v[40:43]
	v_mfma_f32_16x16x32_bf16 v[36:39], v[182:185], v[198:201], v[36:39]
	v_mfma_f32_16x16x32_bf16 v[24:27], v[174:177], v[206:209], v[24:27]
	v_mfma_f32_16x16x32_bf16 v[20:23], v[182:185], v[206:209], v[20:23]
	v_mfma_f32_16x16x32_bf16 v[8:11], v[174:177], v[214:217], v[8:11]
	v_mfma_f32_16x16x32_bf16 v[4:7], v[182:185], v[214:217], v[4:7]
	v_mfma_f32_16x16x32_bf16 v[56:59], v[178:181], v[194:197], v[56:59]
	v_mfma_f32_16x16x32_bf16 v[52:55], v[186:189], v[194:197], v[52:55]
	v_mfma_f32_16x16x32_bf16 v[40:43], v[178:181], v[202:205], v[40:43]
	v_mfma_f32_16x16x32_bf16 v[36:39], v[186:189], v[202:205], v[36:39]
	v_mfma_f32_16x16x32_bf16 v[24:27], v[178:181], v[210:213], v[24:27]
	v_mfma_f32_16x16x32_bf16 v[20:23], v[186:189], v[210:213], v[20:23]
	v_mfma_f32_16x16x32_bf16 v[8:11], v[178:181], v[218:221], v[8:11]
	v_mfma_f32_16x16x32_bf16 v[4:7], v[186:189], v[218:221], v[4:7]
	s_setprio 0
	s_barrier
	s_add_i32 s72, s72, 2
	s_add_u32 s50, s50, 0x100
	s_addc_u32 s51, s51, 0
	s_add_u32 s70, s70, 0x100
	s_addc_u32 s71, s71, 0
	s_cmp_gt_u32 s72, 61
	s_cbranch_scc0 .LBB0_429
	s_and_b64 vcc, exec, s[22:23]
	s_cbranch_vccz .LBB0_432
	s_barrier

.LBB0_1032:
	v_add_u32_e32 v5, s60, v3
	ds_read_b128 v[140:143], v5
	ds_read_b128 v[144:147], v5 offset:1024
	ds_read_b128 v[148:151], v5 offset:2048
	ds_read_b128 v[152:155], v5 offset:3072
	v_add_u32_e32 v5, s61, v3
	ds_read_b128 v[156:159], v5
	ds_read_b128 v[160:163], v5 offset:1024
	ds_read_b128 v[164:167], v5 offset:2048
	ds_read_b128 v[168:171], v5 offset:3072
	s_add_u32 s42, s40, 0xfff80080
	s_addc_u32 s43, s41, -1
	s_cmp_eq_u32 s67, 28
	s_cselect_b32 s51, s5, s43
	s_cselect_b32 s50, s7, s42
	s_cselect_b32 s43, s25, s66
	s_cselect_b32 s42, s27, s65
	s_add_i32 m0, s47, 0xc000
	ds_read_b128 v[172:175], v246
	ds_read_b128 v[176:179], v246 offset:1024
	ds_read_b128 v[180:183], v246 offset:2048
	ds_read_b128 v[184:187], v246 offset:3072
	ds_read_b128 v[188:191], v246 offset:4096
	ds_read_b128 v[192:195], v246 offset:5120
	ds_read_b128 v[196:199], v246 offset:6144
	ds_read_b128 v[200:203], v246 offset:7168
	global_load_lds_dwordx4 v216, s[40:41]
	s_add_i32 m0, s47, 0xe000
	s_nop 0
	global_load_lds_dwordx4 v218, s[40:41]
	s_waitcnt vmcnt(8)
	s_waitcnt lgkmcnt(0)
	s_setprio 1
	s_barrier
	v_mfma_f32_16x16x32_bf16 v[136:139], v[140:143], v[172:175], v[136:139]
	v_mfma_f32_16x16x32_bf16 v[132:135], v[148:151], v[172:175], v[132:135]
	v_mfma_f32_16x16x32_bf16 v[128:131], v[140:143], v[180:183], v[128:131]
	v_mfma_f32_16x16x32_bf16 v[124:127], v[148:151], v[180:183], v[124:127]
	v_mfma_f32_16x16x32_bf16 v[120:123], v[140:143], v[188:191], v[120:123]
	v_mfma_f32_16x16x32_bf16 v[116:119], v[148:151], v[188:191], v[116:119]
	v_mfma_f32_16x16x32_bf16 v[112:115], v[140:143], v[196:199], v[112:115]
	v_mfma_f32_16x16x32_bf16 v[108:111], v[148:151], v[196:199], v[108:111]
	v_mfma_f32_16x16x32_bf16 v[136:139], v[144:147], v[176:179], v[136:139]
	v_mfma_f32_16x16x32_bf16 v[132:135], v[152:155], v[176:179], v[132:135]
	v_mfma_f32_16x16x32_bf16 v[128:131], v[144:147], v[184:187], v[128:131]
	v_mfma_f32_16x16x32_bf16 v[124:127], v[152:155], v[184:187], v[124:127]
	v_mfma_f32_16x16x32_bf16 v[120:123], v[144:147], v[192:195], v[120:123]
	v_mfma_f32_16x16x32_bf16 v[116:119], v[152:155], v[192:195], v[116:119]
	v_mfma_f32_16x16x32_bf16 v[112:115], v[144:147], v[200:203], v[112:115]
	v_mfma_f32_16x16x32_bf16 v[108:111], v[152:155], v[200:203], v[108:111]
	s_setprio 0
	s_setprio 1
	v_mfma_f32_16x16x32_bf16 v[104:107], v[156:159], v[172:175], v[104:107]
	v_mfma_f32_16x16x32_bf16 v[100:103], v[164:167], v[172:175], v[100:103]
	v_mfma_f32_16x16x32_bf16 v[96:99], v[156:159], v[180:183], v[96:99]
	v_mfma_f32_16x16x32_bf16 v[92:95], v[164:167], v[180:183], v[92:95]
	v_mfma_f32_16x16x32_bf16 v[88:91], v[156:159], v[188:191], v[88:91]
	v_mfma_f32_16x16x32_bf16 v[84:87], v[164:167], v[188:191], v[84:87]
	v_mfma_f32_16x16x32_bf16 v[80:83], v[156:159], v[196:199], v[80:83]
	v_mfma_f32_16x16x32_bf16 v[76:79], v[164:167], v[196:199], v[76:79]
	v_mfma_f32_16x16x32_bf16 v[104:107], v[160:163], v[176:179], v[104:107]
	v_mfma_f32_16x16x32_bf16 v[100:103], v[168:171], v[176:179], v[100:103]
	v_mfma_f32_16x16x32_bf16 v[96:99], v[160:163], v[184:187], v[96:99]
	v_mfma_f32_16x16x32_bf16 v[92:95], v[168:171], v[184:187], v[92:95]
	v_mfma_f32_16x16x32_bf16 v[88:91], v[160:163], v[192:195], v[88:91]
	v_mfma_f32_16x16x32_bf16 v[84:87], v[168:171], v[192:195], v[84:87]
	v_mfma_f32_16x16x32_bf16 v[80:83], v[160:163], v[200:203], v[80:83]
	v_mfma_f32_16x16x32_bf16 v[76:79], v[168:171], v[200:203], v[76:79]
	s_setprio 0
	s_barrier
	s_add_i32 s68, s60, s46
	s_mov_b32 m0, s68
	ds_read_b128 v[172:175], v246 offset:16384
	ds_read_b128 v[176:179], v246 offset:17408
	ds_read_b128 v[180:183], v246 offset:18432
	ds_read_b128 v[184:187], v246 offset:19456
	ds_read_b128 v[188:191], v246 offset:20480
	ds_read_b128 v[192:195], v246 offset:21504
	ds_read_b128 v[196:199], v246 offset:22528
	ds_read_b128 v[200:203], v246 offset:23552
	global_load_lds_dwordx4 v210, s[42:43]
	s_add_i32 m0, s68, 0x2000
	s_add_u32 s70, s42, 0x80000
	s_addc_u32 s71, s43, 0
	s_add_i32 s68, s61, s46
	global_load_lds_dwordx4 v214, s[42:43]
	s_mov_b32 m0, s68
	s_nop 0
	global_load_lds_dwordx4 v210, s[70:71]
	s_add_i32 m0, s68, 0x2000
	s_nop 0
	global_load_lds_dwordx4 v214, s[70:71]
	s_mov_b32 m0, s47
	s_nop 0
	global_load_lds_dwordx4 v208, s[50:51]
	s_mov_b32 m0, s48
	s_nop 0
	global_load_lds_dwordx4 v212, s[50:51]
	s_waitcnt vmcnt(8)
	s_waitcnt lgkmcnt(0)
	s_setprio 1
	s_barrier
	v_mfma_f32_16x16x32_bf16 v[72:75], v[140:143], v[172:175], v[72:75]
	v_mfma_f32_16x16x32_bf16 v[68:71], v[148:151], v[172:175], v[68:71]
	v_mfma_f32_16x16x32_bf16 v[64:67], v[140:143], v[180:183], v[64:67]
	v_mfma_f32_16x16x32_bf16 v[60:63], v[148:151], v[180:183], v[60:63]
	v_mfma_f32_16x16x32_bf16 v[56:59], v[140:143], v[188:191], v[56:59]
	v_mfma_f32_16x16x32_bf16 v[52:55], v[148:151], v[188:191], v[52:55]
	v_mfma_f32_16x16x32_bf16 v[48:51], v[140:143], v[196:199], v[48:51]
	v_mfma_f32_16x16x32_bf16 v[44:47], v[148:151], v[196:199], v[44:47]
	v_mfma_f32_16x16x32_bf16 v[72:75], v[144:147], v[176:179], v[72:75]
	v_mfma_f32_16x16x32_bf16 v[68:71], v[152:155], v[176:179], v[68:71]
	v_mfma_f32_16x16x32_bf16 v[64:67], v[144:147], v[184:187], v[64:67]
	v_mfma_f32_16x16x32_bf16 v[60:63], v[152:155], v[184:187], v[60:63]
	v_mfma_f32_16x16x32_bf16 v[56:59], v[144:147], v[192:195], v[56:59]
	v_mfma_f32_16x16x32_bf16 v[52:55], v[152:155], v[192:195], v[52:55]
	v_mfma_f32_16x16x32_bf16 v[48:51], v[144:147], v[200:203], v[48:51]
	v_mfma_f32_16x16x32_bf16 v[44:47], v[152:155], v[200:203], v[44:47]
	s_setprio 0
	s_setprio 1
	v_mfma_f32_16x16x32_bf16 v[40:43], v[156:159], v[172:175], v[40:43]
	v_mfma_f32_16x16x32_bf16 v[36:39], v[164:167], v[172:175], v[36:39]
	v_mfma_f32_16x16x32_bf16 v[32:35], v[156:159], v[180:183], v[32:35]
	v_mfma_f32_16x16x32_bf16 v[28:31], v[164:167], v[180:183], v[28:31]
	v_mfma_f32_16x16x32_bf16 v[24:27], v[156:159], v[188:191], v[24:27]
	v_mfma_f32_16x16x32_bf16 v[20:23], v[164:167], v[188:191], v[20:23]
	v_mfma_f32_16x16x32_bf16 v[16:19], v[156:159], v[196:199], v[16:19]
	v_mfma_f32_16x16x32_bf16 v[12:15], v[164:167], v[196:199], v[12:15]
	v_mfma_f32_16x16x32_bf16 v[40:43], v[160:163], v[176:179], v[40:43]
	v_mfma_f32_16x16x32_bf16 v[36:39], v[168:171], v[176:179], v[36:39]
	v_mfma_f32_16x16x32_bf16 v[32:35], v[160:163], v[184:187], v[32:35]
	v_mfma_f32_16x16x32_bf16 v[28:31], v[168:171], v[184:187], v[28:31]
	v_mfma_f32_16x16x32_bf16 v[24:27], v[160:163], v[192:195], v[24:27]
	v_mfma_f32_16x16x32_bf16 v[20:23], v[168:171], v[192:195], v[20:23]
	v_mfma_f32_16x16x32_bf16 v[16:19], v[160:163], v[200:203], v[16:19]
	v_mfma_f32_16x16x32_bf16 v[12:15], v[168:171], v[200:203], v[12:15]
	s_setprio 0
	s_barrier
	s_add_i32 s68, 0, 0x18000
	v_add_u32_e32 v5, s68, v3
	s_add_i32 s70, 0, 0x1c000
	ds_read_b128 v[140:143], v5
	ds_read_b128 v[144:147], v5 offset:1024
	ds_read_b128 v[148:151], v5 offset:2048
	ds_read_b128 v[152:155], v5 offset:3072
	v_add_u32_e32 v5, s70, v3
	ds_read_b128 v[156:159], v5
	ds_read_b128 v[160:163], v5 offset:1024
	ds_read_b128 v[164:167], v5 offset:2048
	ds_read_b128 v[168:171], v5 offset:3072
	s_add_u32 s98, s50, 0x80000
	s_addc_u32 s99, s51, 0
	s_mov_b64 s[100:101], s[50:51]
	s_mov_b32 m0, s49
	ds_read_b128 v[172:175], v246 offset:32768
	ds_read_b128 v[176:179], v246 offset:33792
	ds_read_b128 v[180:183], v246 offset:34816
	ds_read_b128 v[184:187], v246 offset:35840
	ds_read_b128 v[188:191], v246 offset:36864
	ds_read_b128 v[192:195], v246 offset:37888
	ds_read_b128 v[196:199], v246 offset:38912
	ds_read_b128 v[200:203], v246 offset:39936
	global_load_lds_dwordx4 v208, s[98:99]
	s_mov_b32 m0, s52
	s_nop 0
	global_load_lds_dwordx4 v212, s[98:99]
	s_waitcnt vmcnt(8)
	s_waitcnt lgkmcnt(0)
	s_setprio 1
	s_barrier
	v_mfma_f32_16x16x32_bf16 v[136:139], v[140:143], v[172:175], v[136:139]
	v_mfma_f32_16x16x32_bf16 v[132:135], v[148:151], v[172:175], v[132:135]
	v_mfma_f32_16x16x32_bf16 v[128:131], v[140:143], v[180:183], v[128:131]
	v_mfma_f32_16x16x32_bf16 v[124:127], v[148:151], v[180:183], v[124:127]
	v_mfma_f32_16x16x32_bf16 v[120:123], v[140:143], v[188:191], v[120:123]
	v_mfma_f32_16x16x32_bf16 v[116:119], v[148:151], v[188:191], v[116:119]
	v_mfma_f32_16x16x32_bf16 v[112:115], v[140:143], v[196:199], v[112:115]
	v_mfma_f32_16x16x32_bf16 v[108:111], v[148:151], v[196:199], v[108:111]
	v_mfma_f32_16x16x32_bf16 v[136:139], v[144:147], v[176:179], v[136:139]
	v_mfma_f32_16x16x32_bf16 v[132:135], v[152:155], v[176:179], v[132:135]
	v_mfma_f32_16x16x32_bf16 v[128:131], v[144:147], v[184:187], v[128:131]
	v_mfma_f32_16x16x32_bf16 v[124:127], v[152:155], v[184:187], v[124:127]
	v_mfma_f32_16x16x32_bf16 v[120:123], v[144:147], v[192:195], v[120:123]
	v_mfma_f32_16x16x32_bf16 v[116:119], v[152:155], v[192:195], v[116:119]
	v_mfma_f32_16x16x32_bf16 v[112:115], v[144:147], v[200:203], v[112:115]
	v_mfma_f32_16x16x32_bf16 v[108:111], v[152:155], v[200:203], v[108:111]
	s_setprio 0
	s_setprio 1
	v_mfma_f32_16x16x32_bf16 v[104:107], v[156:159], v[172:175], v[104:107]
	v_mfma_f32_16x16x32_bf16 v[100:103], v[164:167], v[172:175], v[100:103]
	v_mfma_f32_16x16x32_bf16 v[96:99], v[156:159], v[180:183], v[96:99]
	v_mfma_f32_16x16x32_bf16 v[92:95], v[164:167], v[180:183], v[92:95]
	v_mfma_f32_16x16x32_bf16 v[88:91], v[156:159], v[188:191], v[88:91]
	v_mfma_f32_16x16x32_bf16 v[84:87], v[164:167], v[188:191], v[84:87]
	v_mfma_f32_16x16x32_bf16 v[80:83], v[156:159], v[196:199], v[80:83]
	v_mfma_f32_16x16x32_bf16 v[76:79], v[164:167], v[196:199], v[76:79]
	v_mfma_f32_16x16x32_bf16 v[104:107], v[160:163], v[176:179], v[104:107]
	v_mfma_f32_16x16x32_bf16 v[100:103], v[168:171], v[176:179], v[100:103]
	v_mfma_f32_16x16x32_bf16 v[96:99], v[160:163], v[184:187], v[96:99]
	v_mfma_f32_16x16x32_bf16 v[92:95], v[168:171], v[184:187], v[92:95]
	v_mfma_f32_16x16x32_bf16 v[88:91], v[160:163], v[192:195], v[88:91]
	v_mfma_f32_16x16x32_bf16 v[84:87], v[168:171], v[192:195], v[84:87]
	v_mfma_f32_16x16x32_bf16 v[80:83], v[160:163], v[200:203], v[80:83]
	v_mfma_f32_16x16x32_bf16 v[76:79], v[168:171], v[200:203], v[76:79]
	s_setprio 0
	s_barrier
	s_add_i32 s50, s68, s46
	s_add_i32 m0, s50, 0xffffff80
	ds_read_b128 v[172:175], v246 offset:49152
	ds_read_b128 v[176:179], v246 offset:50176
	ds_read_b128 v[180:183], v246 offset:51200
	ds_read_b128 v[184:187], v246 offset:52224
	ds_read_b128 v[188:191], v246 offset:53248
	ds_read_b128 v[192:195], v246 offset:54272
	ds_read_b128 v[196:199], v246 offset:55296
	ds_read_b128 v[200:203], v246 offset:56320
	global_load_lds_dwordx4 v210, s[42:43] offset:128
	s_add_i32 m0, s50, 0x1f80
	s_add_i32 s50, s70, s46
	global_load_lds_dwordx4 v214, s[42:43] offset:128
	s_add_u32 s42, s42, 0x80080
	s_addc_u32 s43, s43, 0
	s_mov_b32 m0, s50
	s_nop 0
	global_load_lds_dwordx4 v210, s[42:43]
	s_add_i32 m0, s50, 0x2000
	s_nop 0
	global_load_lds_dwordx4 v214, s[42:43]
	s_add_i32 m0, s58, 0xffffff80
	s_nop 0
	global_load_lds_dwordx4 v208, s[100:101] offset:128
	s_add_i32 m0, s59, 0xffffff80
	s_nop 0
	global_load_lds_dwordx4 v212, s[100:101] offset:128
	s_waitcnt vmcnt(8)
	s_waitcnt lgkmcnt(0)
	s_setprio 1
	s_barrier
	v_mfma_f32_16x16x32_bf16 v[72:75], v[140:143], v[172:175], v[72:75]
	v_mfma_f32_16x16x32_bf16 v[68:71], v[148:151], v[172:175], v[68:71]
	v_mfma_f32_16x16x32_bf16 v[64:67], v[140:143], v[180:183], v[64:67]
	v_mfma_f32_16x16x32_bf16 v[60:63], v[148:151], v[180:183], v[60:63]
	v_mfma_f32_16x16x32_bf16 v[56:59], v[140:143], v[188:191], v[56:59]
	v_mfma_f32_16x16x32_bf16 v[52:55], v[148:151], v[188:191], v[52:55]
	v_mfma_f32_16x16x32_bf16 v[48:51], v[140:143], v[196:199], v[48:51]
	v_mfma_f32_16x16x32_bf16 v[44:47], v[148:151], v[196:199], v[44:47]
	v_mfma_f32_16x16x32_bf16 v[72:75], v[144:147], v[176:179], v[72:75]
	v_mfma_f32_16x16x32_bf16 v[68:71], v[152:155], v[176:179], v[68:71]
	v_mfma_f32_16x16x32_bf16 v[64:67], v[144:147], v[184:187], v[64:67]
	v_mfma_f32_16x16x32_bf16 v[60:63], v[152:155], v[184:187], v[60:63]
	v_mfma_f32_16x16x32_bf16 v[56:59], v[144:147], v[192:195], v[56:59]
	v_mfma_f32_16x16x32_bf16 v[52:55], v[152:155], v[192:195], v[52:55]
	v_mfma_f32_16x16x32_bf16 v[48:51], v[144:147], v[200:203], v[48:51]
	v_mfma_f32_16x16x32_bf16 v[44:47], v[152:155], v[200:203], v[44:47]
	s_setprio 0
	s_setprio 1
	v_mfma_f32_16x16x32_bf16 v[40:43], v[156:159], v[172:175], v[40:43]
	v_mfma_f32_16x16x32_bf16 v[36:39], v[164:167], v[172:175], v[36:39]
	v_mfma_f32_16x16x32_bf16 v[32:35], v[156:159], v[180:183], v[32:35]
	v_mfma_f32_16x16x32_bf16 v[28:31], v[164:167], v[180:183], v[28:31]
	v_mfma_f32_16x16x32_bf16 v[24:27], v[156:159], v[188:191], v[24:27]
	v_mfma_f32_16x16x32_bf16 v[20:23], v[164:167], v[188:191], v[20:23]
	v_mfma_f32_16x16x32_bf16 v[16:19], v[156:159], v[196:199], v[16:19]
	v_mfma_f32_16x16x32_bf16 v[12:15], v[164:167], v[196:199], v[12:15]
	v_mfma_f32_16x16x32_bf16 v[40:43], v[160:163], v[176:179], v[40:43]
	v_mfma_f32_16x16x32_bf16 v[36:39], v[168:171], v[176:179], v[36:39]
	v_mfma_f32_16x16x32_bf16 v[32:35], v[160:163], v[184:187], v[32:35]
	v_mfma_f32_16x16x32_bf16 v[28:31], v[168:171], v[184:187], v[28:31]
	v_mfma_f32_16x16x32_bf16 v[24:27], v[160:163], v[192:195], v[24:27]
	v_mfma_f32_16x16x32_bf16 v[20:23], v[168:171], v[192:195], v[20:23]
	v_mfma_f32_16x16x32_bf16 v[16:19], v[160:163], v[200:203], v[16:19]
	v_mfma_f32_16x16x32_bf16 v[12:15], v[168:171], v[200:203], v[12:15]
	s_setprio 0
	s_barrier
	s_add_i32 s67, s67, 2
	s_add_u32 s40, s40, 0x100
	s_addc_u32 s41, s41, 0
	s_add_u32 s65, s65, 0x100
	s_addc_u32 s66, s66, 0
	s_cmp_gt_u32 s67, 29
	s_cbranch_scc0 .LBB0_1032
	s_and_b64 vcc, exec, s[22:23]
	s_cbranch_vccz .LBB0_1035
	s_barrier

.LBB0_1203:
	ds_read_b128 v[132:135], v187
	ds_read_b128 v[136:139], v187 offset:1024
	ds_read_b128 v[140:143], v187 offset:2048
	ds_read_b128 v[144:147], v187 offset:3072
	ds_read_b128 v[148:151], v188
	ds_read_b128 v[152:155], v188 offset:1024
	ds_read_b128 v[172:175], v188 offset:2048
	ds_read_b128 v[176:179], v188 offset:3072
	s_add_u32 s0, s42, 0xfff00080
	s_addc_u32 s50, s43, -1
	s_cmp_eq_u32 s65, 60
	s_cselect_b32 s53, s25, s50
	s_cselect_b32 s52, s31, s0
	s_cselect_b32 s51, s23, s64
	s_cselect_b32 s50, s62, s63
	s_add_i32 m0, s41, 0xc000
	ds_read_b128 v[180:183], v189
	ds_read_b128 v[192:195], v189 offset:1024
	ds_read_b128 v[196:199], v189 offset:2048
	ds_read_b128 v[200:203], v189 offset:3072
	ds_read_b128 v[204:207], v189 offset:4096
	ds_read_b128 v[208:211], v189 offset:5120
	ds_read_b128 v[212:215], v189 offset:6144
	ds_read_b128 v[216:219], v189 offset:7168
	global_load_lds_dwordx4 v164, s[42:43]
	s_add_i32 m0, s41, 0xe000
	s_nop 0
	global_load_lds_dwordx4 v166, s[42:43]
	s_waitcnt vmcnt(8)
	s_waitcnt lgkmcnt(0)
	s_setprio 1
	s_barrier
	v_mfma_f32_16x16x32_bf16 v[128:131], v[132:135], v[180:183], v[128:131]
	v_mfma_f32_16x16x32_bf16 v[124:127], v[140:143], v[180:183], v[124:127]
	v_mfma_f32_16x16x32_bf16 v[112:115], v[132:135], v[196:199], v[112:115]
	v_mfma_f32_16x16x32_bf16 v[108:111], v[140:143], v[196:199], v[108:111]
	v_mfma_f32_16x16x32_bf16 v[96:99], v[132:135], v[204:207], v[96:99]
	v_mfma_f32_16x16x32_bf16 v[92:95], v[140:143], v[204:207], v[92:95]
	v_mfma_f32_16x16x32_bf16 v[80:83], v[132:135], v[212:215], v[80:83]
	v_mfma_f32_16x16x32_bf16 v[76:79], v[140:143], v[212:215], v[76:79]
	v_mfma_f32_16x16x32_bf16 v[128:131], v[136:139], v[192:195], v[128:131]
	v_mfma_f32_16x16x32_bf16 v[124:127], v[144:147], v[192:195], v[124:127]
	v_mfma_f32_16x16x32_bf16 v[112:115], v[136:139], v[200:203], v[112:115]
	v_mfma_f32_16x16x32_bf16 v[108:111], v[144:147], v[200:203], v[108:111]
	v_mfma_f32_16x16x32_bf16 v[96:99], v[136:139], v[208:211], v[96:99]
	v_mfma_f32_16x16x32_bf16 v[92:95], v[144:147], v[208:211], v[92:95]
	v_mfma_f32_16x16x32_bf16 v[80:83], v[136:139], v[216:219], v[80:83]
	v_mfma_f32_16x16x32_bf16 v[76:79], v[144:147], v[216:219], v[76:79]
	s_setprio 0
	s_setprio 1
	v_mfma_f32_16x16x32_bf16 v[120:123], v[148:151], v[180:183], v[120:123]
	v_mfma_f32_16x16x32_bf16 v[116:119], v[172:175], v[180:183], v[116:119]
	v_mfma_f32_16x16x32_bf16 v[104:107], v[148:151], v[196:199], v[104:107]
	v_mfma_f32_16x16x32_bf16 v[100:103], v[172:175], v[196:199], v[100:103]
	v_mfma_f32_16x16x32_bf16 v[88:91], v[148:151], v[204:207], v[88:91]
	v_mfma_f32_16x16x32_bf16 v[84:87], v[172:175], v[204:207], v[84:87]
	v_mfma_f32_16x16x32_bf16 v[72:75], v[148:151], v[212:215], v[72:75]
	v_mfma_f32_16x16x32_bf16 v[68:71], v[172:175], v[212:215], v[68:71]
	v_mfma_f32_16x16x32_bf16 v[120:123], v[152:155], v[192:195], v[120:123]
	v_mfma_f32_16x16x32_bf16 v[116:119], v[176:179], v[192:195], v[116:119]
	v_mfma_f32_16x16x32_bf16 v[104:107], v[152:155], v[200:203], v[104:107]
	v_mfma_f32_16x16x32_bf16 v[100:103], v[176:179], v[200:203], v[100:103]
	v_mfma_f32_16x16x32_bf16 v[88:91], v[152:155], v[208:211], v[88:91]
	v_mfma_f32_16x16x32_bf16 v[84:87], v[176:179], v[208:211], v[84:87]
	v_mfma_f32_16x16x32_bf16 v[72:75], v[152:155], v[216:219], v[72:75]
	v_mfma_f32_16x16x32_bf16 v[68:71], v[176:179], v[216:219], v[68:71]
	s_setprio 0
	s_barrier
	s_add_i32 s0, s59, s46
	s_mov_b32 m0, s0
	ds_read_b128 v[180:183], v189 offset:16384
	ds_read_b128 v[192:195], v189 offset:17408
	ds_read_b128 v[196:199], v189 offset:18432
	ds_read_b128 v[200:203], v189 offset:19456
	ds_read_b128 v[204:207], v189 offset:20480
	ds_read_b128 v[208:211], v189 offset:21504
	ds_read_b128 v[212:215], v189 offset:22528
	ds_read_b128 v[216:219], v189 offset:23552
	global_load_lds_dwordx4 v158, s[50:51]
	s_add_i32 m0, s0, 0x2000
	s_add_u32 s66, s50, 0x100000
	s_addc_u32 s67, s51, 0
	s_add_i32 s0, s60, s46
	global_load_lds_dwordx4 v162, s[50:51]
	s_mov_b32 m0, s0
	s_nop 0
	global_load_lds_dwordx4 v158, s[66:67]
	s_add_i32 m0, s0, 0x2000
	s_nop 0
	global_load_lds_dwordx4 v162, s[66:67]
	s_mov_b32 m0, s41
	s_nop 0
	global_load_lds_dwordx4 v156, s[52:53]
	s_mov_b32 m0, s47
	s_nop 0
	global_load_lds_dwordx4 v160, s[52:53]
	s_waitcnt vmcnt(8)
	s_waitcnt lgkmcnt(0)
	s_setprio 1
	s_barrier
	v_mfma_f32_16x16x32_bf16 v[64:67], v[132:135], v[180:183], v[64:67]
	v_mfma_f32_16x16x32_bf16 v[60:63], v[140:143], v[180:183], v[60:63]
	v_mfma_f32_16x16x32_bf16 v[48:51], v[132:135], v[196:199], v[48:51]
	v_mfma_f32_16x16x32_bf16 v[44:47], v[140:143], v[196:199], v[44:47]
	v_mfma_f32_16x16x32_bf16 v[32:35], v[132:135], v[204:207], v[32:35]
	v_mfma_f32_16x16x32_bf16 v[28:31], v[140:143], v[204:207], v[28:31]
	v_mfma_f32_16x16x32_bf16 v[16:19], v[132:135], v[212:215], v[16:19]
	v_mfma_f32_16x16x32_bf16 v[12:15], v[140:143], v[212:215], v[12:15]
	v_mfma_f32_16x16x32_bf16 v[64:67], v[136:139], v[192:195], v[64:67]
	v_mfma_f32_16x16x32_bf16 v[60:63], v[144:147], v[192:195], v[60:63]
	v_mfma_f32_16x16x32_bf16 v[48:51], v[136:139], v[200:203], v[48:51]
	v_mfma_f32_16x16x32_bf16 v[44:47], v[144:147], v[200:203], v[44:47]
	v_mfma_f32_16x16x32_bf16 v[32:35], v[136:139], v[208:211], v[32:35]
	v_mfma_f32_16x16x32_bf16 v[28:31], v[144:147], v[208:211], v[28:31]
	v_mfma_f32_16x16x32_bf16 v[16:19], v[136:139], v[216:219], v[16:19]
	v_mfma_f32_16x16x32_bf16 v[12:15], v[144:147], v[216:219], v[12:15]
	s_setprio 0
	s_setprio 1
	v_mfma_f32_16x16x32_bf16 v[56:59], v[148:151], v[180:183], v[56:59]
	v_mfma_f32_16x16x32_bf16 v[52:55], v[172:175], v[180:183], v[52:55]
	v_mfma_f32_16x16x32_bf16 v[40:43], v[148:151], v[196:199], v[40:43]
	v_mfma_f32_16x16x32_bf16 v[36:39], v[172:175], v[196:199], v[36:39]
	v_mfma_f32_16x16x32_bf16 v[24:27], v[148:151], v[204:207], v[24:27]
	v_mfma_f32_16x16x32_bf16 v[20:23], v[172:175], v[204:207], v[20:23]
	v_mfma_f32_16x16x32_bf16 v[8:11], v[148:151], v[212:215], v[8:11]
	v_mfma_f32_16x16x32_bf16 v[4:7], v[172:175], v[212:215], v[4:7]
	v_mfma_f32_16x16x32_bf16 v[56:59], v[152:155], v[192:195], v[56:59]
	v_mfma_f32_16x16x32_bf16 v[52:55], v[176:179], v[192:195], v[52:55]
	v_mfma_f32_16x16x32_bf16 v[40:43], v[152:155], v[200:203], v[40:43]
	v_mfma_f32_16x16x32_bf16 v[36:39], v[176:179], v[200:203], v[36:39]
	v_mfma_f32_16x16x32_bf16 v[24:27], v[152:155], v[208:211], v[24:27]
	v_mfma_f32_16x16x32_bf16 v[20:23], v[176:179], v[208:211], v[20:23]
	v_mfma_f32_16x16x32_bf16 v[8:11], v[152:155], v[216:219], v[8:11]
	v_mfma_f32_16x16x32_bf16 v[4:7], v[176:179], v[216:219], v[4:7]
	s_setprio 0
	s_barrier
	s_add_i32 s0, 0, 0x18000
	s_add_i32 s66, 0, 0x1c000
	v_add_u32_e32 v144, s0, v3
	v_add_u32_e32 v176, s66, v3
	ds_read_b128 v[132:135], v144
	ds_read_b128 v[136:139], v144 offset:1024
	ds_read_b128 v[140:143], v144 offset:2048
	ds_read_b128 v[144:147], v144 offset:3072
	ds_read_b128 v[148:151], v176
	ds_read_b128 v[152:155], v176 offset:1024
	ds_read_b128 v[172:175], v176 offset:2048
	ds_read_b128 v[176:179], v176 offset:3072
	s_add_u32 s98, s52, 0x100000
	s_addc_u32 s99, s53, 0
	s_mov_b32 m0, s48
	ds_read_b128 v[180:183], v189 offset:32768
	ds_read_b128 v[192:195], v189 offset:33792
	ds_read_b128 v[196:199], v189 offset:34816
	ds_read_b128 v[200:203], v189 offset:35840
	ds_read_b128 v[204:207], v189 offset:36864
	ds_read_b128 v[208:211], v189 offset:37888
	ds_read_b128 v[212:215], v189 offset:38912
	ds_read_b128 v[216:219], v189 offset:39936
	global_load_lds_dwordx4 v156, s[98:99]
	s_mov_b32 m0, s49
	s_nop 0
	global_load_lds_dwordx4 v160, s[98:99]
	s_waitcnt vmcnt(8)
	s_waitcnt lgkmcnt(0)
	s_setprio 1
	s_barrier
	v_mfma_f32_16x16x32_bf16 v[128:131], v[132:135], v[180:183], v[128:131]
	v_mfma_f32_16x16x32_bf16 v[124:127], v[140:143], v[180:183], v[124:127]
	v_mfma_f32_16x16x32_bf16 v[112:115], v[132:135], v[196:199], v[112:115]
	v_mfma_f32_16x16x32_bf16 v[108:111], v[140:143], v[196:199], v[108:111]
	v_mfma_f32_16x16x32_bf16 v[96:99], v[132:135], v[204:207], v[96:99]
	v_mfma_f32_16x16x32_bf16 v[92:95], v[140:143], v[204:207], v[92:95]
	v_mfma_f32_16x16x32_bf16 v[80:83], v[132:135], v[212:215], v[80:83]
	v_mfma_f32_16x16x32_bf16 v[76:79], v[140:143], v[212:215], v[76:79]
	v_mfma_f32_16x16x32_bf16 v[128:131], v[136:139], v[192:195], v[128:131]
	v_mfma_f32_16x16x32_bf16 v[124:127], v[144:147], v[192:195], v[124:127]
	v_mfma_f32_16x16x32_bf16 v[112:115], v[136:139], v[200:203], v[112:115]
	v_mfma_f32_16x16x32_bf16 v[108:111], v[144:147], v[200:203], v[108:111]
	v_mfma_f32_16x16x32_bf16 v[96:99], v[136:139], v[208:211], v[96:99]
	v_mfma_f32_16x16x32_bf16 v[92:95], v[144:147], v[208:211], v[92:95]
	v_mfma_f32_16x16x32_bf16 v[80:83], v[136:139], v[216:219], v[80:83]
	v_mfma_f32_16x16x32_bf16 v[76:79], v[144:147], v[216:219], v[76:79]
	s_setprio 0
	s_setprio 1
	v_mfma_f32_16x16x32_bf16 v[120:123], v[148:151], v[180:183], v[120:123]
	v_mfma_f32_16x16x32_bf16 v[116:119], v[172:175], v[180:183], v[116:119]
	v_mfma_f32_16x16x32_bf16 v[104:107], v[148:151], v[196:199], v[104:107]
	v_mfma_f32_16x16x32_bf16 v[100:103], v[172:175], v[196:199], v[100:103]
	v_mfma_f32_16x16x32_bf16 v[88:91], v[148:151], v[204:207], v[88:91]
	v_mfma_f32_16x16x32_bf16 v[84:87], v[172:175], v[204:207], v[84:87]
	v_mfma_f32_16x16x32_bf16 v[72:75], v[148:151], v[212:215], v[72:75]
	v_mfma_f32_16x16x32_bf16 v[68:71], v[172:175], v[212:215], v[68:71]
	v_mfma_f32_16x16x32_bf16 v[120:123], v[152:155], v[192:195], v[120:123]
	v_mfma_f32_16x16x32_bf16 v[116:119], v[176:179], v[192:195], v[116:119]
	v_mfma_f32_16x16x32_bf16 v[104:107], v[152:155], v[200:203], v[104:107]
	v_mfma_f32_16x16x32_bf16 v[100:103], v[176:179], v[200:203], v[100:103]
	v_mfma_f32_16x16x32_bf16 v[88:91], v[152:155], v[208:211], v[88:91]
	v_mfma_f32_16x16x32_bf16 v[84:87], v[176:179], v[208:211], v[84:87]
	v_mfma_f32_16x16x32_bf16 v[72:75], v[152:155], v[216:219], v[72:75]
	v_mfma_f32_16x16x32_bf16 v[68:71], v[176:179], v[216:219], v[68:71]
	s_setprio 0
	s_barrier
	s_add_i32 s0, s0, s46
	s_add_i32 m0, s0, 0xffffff80
	ds_read_b128 v[180:183], v189 offset:49152
	ds_read_b128 v[192:195], v189 offset:50176
	ds_read_b128 v[196:199], v189 offset:51200
	ds_read_b128 v[200:203], v189 offset:52224
	ds_read_b128 v[204:207], v189 offset:53248
	ds_read_b128 v[208:211], v189 offset:54272
	ds_read_b128 v[212:215], v189 offset:55296
	ds_read_b128 v[216:219], v189 offset:56320
	global_load_lds_dwordx4 v158, s[50:51] offset:128
	s_add_i32 m0, s0, 0x1f80
	s_add_i32 s0, s66, s46
	global_load_lds_dwordx4 v162, s[50:51] offset:128
	s_add_u32 s50, s50, 0x100080
	s_addc_u32 s51, s51, 0
	s_mov_b32 m0, s0
	s_nop 0
	global_load_lds_dwordx4 v158, s[50:51]
	s_add_i32 m0, s0, 0x2000
	s_nop 0
	global_load_lds_dwordx4 v162, s[50:51]
	s_add_i32 m0, s57, 0xffffff80
	s_nop 0
	global_load_lds_dwordx4 v156, s[52:53] offset:128
	s_add_i32 m0, s58, 0xffffff80
	s_nop 0
	global_load_lds_dwordx4 v160, s[52:53] offset:128
	s_waitcnt vmcnt(8)
	s_waitcnt lgkmcnt(0)
	s_setprio 1
	s_barrier
	v_mfma_f32_16x16x32_bf16 v[64:67], v[132:135], v[180:183], v[64:67]
	v_mfma_f32_16x16x32_bf16 v[60:63], v[140:143], v[180:183], v[60:63]
	v_mfma_f32_16x16x32_bf16 v[48:51], v[132:135], v[196:199], v[48:51]
	v_mfma_f32_16x16x32_bf16 v[44:47], v[140:143], v[196:199], v[44:47]
	v_mfma_f32_16x16x32_bf16 v[32:35], v[132:135], v[204:207], v[32:35]
	v_mfma_f32_16x16x32_bf16 v[28:31], v[140:143], v[204:207], v[28:31]
	v_mfma_f32_16x16x32_bf16 v[16:19], v[132:135], v[212:215], v[16:19]
	v_mfma_f32_16x16x32_bf16 v[12:15], v[140:143], v[212:215], v[12:15]
	v_mfma_f32_16x16x32_bf16 v[64:67], v[136:139], v[192:195], v[64:67]
	v_mfma_f32_16x16x32_bf16 v[60:63], v[144:147], v[192:195], v[60:63]
	v_mfma_f32_16x16x32_bf16 v[48:51], v[136:139], v[200:203], v[48:51]
	v_mfma_f32_16x16x32_bf16 v[44:47], v[144:147], v[200:203], v[44:47]
	v_mfma_f32_16x16x32_bf16 v[32:35], v[136:139], v[208:211], v[32:35]
	v_mfma_f32_16x16x32_bf16 v[28:31], v[144:147], v[208:211], v[28:31]
	v_mfma_f32_16x16x32_bf16 v[16:19], v[136:139], v[216:219], v[16:19]
	v_mfma_f32_16x16x32_bf16 v[12:15], v[144:147], v[216:219], v[12:15]
	s_setprio 0
	s_setprio 1
	v_mfma_f32_16x16x32_bf16 v[56:59], v[148:151], v[180:183], v[56:59]
	v_mfma_f32_16x16x32_bf16 v[52:55], v[172:175], v[180:183], v[52:55]
	v_mfma_f32_16x16x32_bf16 v[40:43], v[148:151], v[196:199], v[40:43]
	v_mfma_f32_16x16x32_bf16 v[36:39], v[172:175], v[196:199], v[36:39]
	v_mfma_f32_16x16x32_bf16 v[24:27], v[148:151], v[204:207], v[24:27]
	v_mfma_f32_16x16x32_bf16 v[20:23], v[172:175], v[204:207], v[20:23]
	v_mfma_f32_16x16x32_bf16 v[8:11], v[148:151], v[212:215], v[8:11]
	v_mfma_f32_16x16x32_bf16 v[4:7], v[172:175], v[212:215], v[4:7]
	v_mfma_f32_16x16x32_bf16 v[56:59], v[152:155], v[192:195], v[56:59]
	v_mfma_f32_16x16x32_bf16 v[52:55], v[176:179], v[192:195], v[52:55]
	v_mfma_f32_16x16x32_bf16 v[40:43], v[152:155], v[200:203], v[40:43]
	v_mfma_f32_16x16x32_bf16 v[36:39], v[176:179], v[200:203], v[36:39]
	v_mfma_f32_16x16x32_bf16 v[24:27], v[152:155], v[208:211], v[24:27]
	v_mfma_f32_16x16x32_bf16 v[20:23], v[176:179], v[208:211], v[20:23]
	v_mfma_f32_16x16x32_bf16 v[8:11], v[152:155], v[216:219], v[8:11]
	v_mfma_f32_16x16x32_bf16 v[4:7], v[176:179], v[216:219], v[4:7]
	s_setprio 0
	s_barrier
	s_add_i32 s65, s65, 2
	s_add_u32 s42, s42, 0x100
	s_addc_u32 s43, s43, 0
	s_add_u32 s63, s63, 0x100
	s_addc_u32 s64, s64, 0
	s_cmp_gt_u32 s65, 61
	s_cbranch_scc0 .LBB0_1203
	s_and_b64 vcc, exec, s[20:21]
	s_cbranch_vccz .LBB0_1206
	s_barrier

.LBB0_1288:
	ds_read_b128 v[154:157], v150
	ds_read_b128 v[158:161], v150 offset:1024
	ds_read_b128 v[162:165], v150 offset:2048
	ds_read_b128 v[166:169], v150 offset:3072
	ds_read_b128 v[170:173], v151
	ds_read_b128 v[174:177], v151 offset:1024
	ds_read_b128 v[178:181], v151 offset:2048
	ds_read_b128 v[182:185], v151 offset:3072
	s_add_u32 s0, s42, 0xfff00080
	s_addc_u32 s50, s43, -1
	s_cmp_eq_u32 s70, 12
	s_cselect_b32 s53, s29, s50
	s_cselect_b32 s52, s28, s0
	s_cselect_b32 s51, s5, s41
	s_cselect_b32 s50, s4, s31
	s_add_i32 m0, s17, 0xc000
	ds_read_b128 v[186:189], v152
	ds_read_b128 v[190:193], v152 offset:1024
	ds_read_b128 v[194:197], v152 offset:2048
	ds_read_b128 v[198:201], v152 offset:3072
	ds_read_b128 v[202:205], v152 offset:4096
	ds_read_b128 v[206:209], v152 offset:5120
	ds_read_b128 v[210:213], v152 offset:6144
	ds_read_b128 v[214:217], v152 offset:7168
	global_load_lds_dwordx4 v142, s[42:43]
	s_add_i32 m0, s17, 0xe000
	s_nop 0
	global_load_lds_dwordx4 v144, s[42:43]
	s_waitcnt vmcnt(8)
	s_waitcnt lgkmcnt(0)
	s_setprio 1
	s_barrier
	v_mfma_f32_16x16x32_bf16 v[128:131], v[154:157], v[186:189], v[128:131]
	v_mfma_f32_16x16x32_bf16 v[124:127], v[162:165], v[186:189], v[124:127]
	v_mfma_f32_16x16x32_bf16 v[120:123], v[154:157], v[194:197], v[120:123]
	v_mfma_f32_16x16x32_bf16 v[116:119], v[162:165], v[194:197], v[116:119]
	v_mfma_f32_16x16x32_bf16 v[104:107], v[154:157], v[202:205], v[104:107]
	v_mfma_f32_16x16x32_bf16 v[100:103], v[162:165], v[202:205], v[100:103]
	v_mfma_f32_16x16x32_bf16 v[88:91], v[154:157], v[210:213], v[88:91]
	v_mfma_f32_16x16x32_bf16 v[84:87], v[162:165], v[210:213], v[84:87]
	v_mfma_f32_16x16x32_bf16 v[128:131], v[158:161], v[190:193], v[128:131]
	v_mfma_f32_16x16x32_bf16 v[124:127], v[166:169], v[190:193], v[124:127]
	v_mfma_f32_16x16x32_bf16 v[120:123], v[158:161], v[198:201], v[120:123]
	v_mfma_f32_16x16x32_bf16 v[116:119], v[166:169], v[198:201], v[116:119]
	v_mfma_f32_16x16x32_bf16 v[104:107], v[158:161], v[206:209], v[104:107]
	v_mfma_f32_16x16x32_bf16 v[100:103], v[166:169], v[206:209], v[100:103]
	v_mfma_f32_16x16x32_bf16 v[88:91], v[158:161], v[214:217], v[88:91]
	v_mfma_f32_16x16x32_bf16 v[84:87], v[166:169], v[214:217], v[84:87]
	s_setprio 0
	s_setprio 1
	v_mfma_f32_16x16x32_bf16 v[112:115], v[170:173], v[186:189], v[112:115]
	v_mfma_f32_16x16x32_bf16 v[108:111], v[178:181], v[186:189], v[108:111]
	v_mfma_f32_16x16x32_bf16 v[96:99], v[170:173], v[194:197], v[96:99]
	v_mfma_f32_16x16x32_bf16 v[92:95], v[178:181], v[194:197], v[92:95]
	v_mfma_f32_16x16x32_bf16 v[80:83], v[170:173], v[202:205], v[80:83]
	v_mfma_f32_16x16x32_bf16 v[76:79], v[178:181], v[202:205], v[76:79]
	v_mfma_f32_16x16x32_bf16 v[72:75], v[170:173], v[210:213], v[72:75]
	v_mfma_f32_16x16x32_bf16 v[68:71], v[178:181], v[210:213], v[68:71]
	v_mfma_f32_16x16x32_bf16 v[112:115], v[174:177], v[190:193], v[112:115]
	v_mfma_f32_16x16x32_bf16 v[108:111], v[182:185], v[190:193], v[108:111]
	v_mfma_f32_16x16x32_bf16 v[96:99], v[174:177], v[198:201], v[96:99]
	v_mfma_f32_16x16x32_bf16 v[92:95], v[182:185], v[198:201], v[92:95]
	v_mfma_f32_16x16x32_bf16 v[80:83], v[174:177], v[206:209], v[80:83]
	v_mfma_f32_16x16x32_bf16 v[76:79], v[182:185], v[206:209], v[76:79]
	v_mfma_f32_16x16x32_bf16 v[72:75], v[174:177], v[214:217], v[72:75]
	v_mfma_f32_16x16x32_bf16 v[68:71], v[182:185], v[214:217], v[68:71]
	s_setprio 0
	s_barrier
	s_add_i32 s0, s60, s46
	s_mov_b32 m0, s0
	ds_read_b128 v[186:189], v152 offset:16384
	ds_read_b128 v[190:193], v152 offset:17408
	ds_read_b128 v[194:197], v152 offset:18432
	ds_read_b128 v[198:201], v152 offset:19456
	ds_read_b128 v[202:205], v152 offset:20480
	ds_read_b128 v[206:209], v152 offset:21504
	ds_read_b128 v[210:213], v152 offset:22528
	ds_read_b128 v[214:217], v152 offset:23552
	global_load_lds_dwordx4 v136, s[50:51]
	s_add_i32 m0, s0, 0x2000
	s_add_u32 s72, s50, 0x100000
	s_addc_u32 s73, s51, 0
	s_add_i32 s0, s61, s46
	global_load_lds_dwordx4 v132, s[50:51]
	s_mov_b32 m0, s0
	s_nop 0
	global_load_lds_dwordx4 v136, s[72:73]
	s_add_i32 m0, s0, 0x2000
	s_nop 0
	global_load_lds_dwordx4 v132, s[72:73]
	s_mov_b32 m0, s17
	s_nop 0
	global_load_lds_dwordx4 v138, s[52:53]
	s_mov_b32 m0, s47
	s_nop 0
	global_load_lds_dwordx4 v134, s[52:53]
	s_waitcnt vmcnt(8)
	s_waitcnt lgkmcnt(0)
	s_setprio 1
	s_barrier
	v_mfma_f32_16x16x32_bf16 v[64:67], v[154:157], v[186:189], v[64:67]
	v_mfma_f32_16x16x32_bf16 v[60:63], v[162:165], v[186:189], v[60:63]
	v_mfma_f32_16x16x32_bf16 v[56:59], v[154:157], v[194:197], v[56:59]
	v_mfma_f32_16x16x32_bf16 v[52:55], v[162:165], v[194:197], v[52:55]
	v_mfma_f32_16x16x32_bf16 v[40:43], v[154:157], v[202:205], v[40:43]
	v_mfma_f32_16x16x32_bf16 v[36:39], v[162:165], v[202:205], v[36:39]
	v_mfma_f32_16x16x32_bf16 v[24:27], v[154:157], v[210:213], v[24:27]
	v_mfma_f32_16x16x32_bf16 v[20:23], v[162:165], v[210:213], v[20:23]
	v_mfma_f32_16x16x32_bf16 v[64:67], v[158:161], v[190:193], v[64:67]
	v_mfma_f32_16x16x32_bf16 v[60:63], v[166:169], v[190:193], v[60:63]
	v_mfma_f32_16x16x32_bf16 v[56:59], v[158:161], v[198:201], v[56:59]
	v_mfma_f32_16x16x32_bf16 v[52:55], v[166:169], v[198:201], v[52:55]
	v_mfma_f32_16x16x32_bf16 v[40:43], v[158:161], v[206:209], v[40:43]
	v_mfma_f32_16x16x32_bf16 v[36:39], v[166:169], v[206:209], v[36:39]
	v_mfma_f32_16x16x32_bf16 v[24:27], v[158:161], v[214:217], v[24:27]
	v_mfma_f32_16x16x32_bf16 v[20:23], v[166:169], v[214:217], v[20:23]
	s_setprio 0
	s_setprio 1
	v_mfma_f32_16x16x32_bf16 v[48:51], v[170:173], v[186:189], v[48:51]
	v_mfma_f32_16x16x32_bf16 v[44:47], v[178:181], v[186:189], v[44:47]
	v_mfma_f32_16x16x32_bf16 v[32:35], v[170:173], v[194:197], v[32:35]
	v_mfma_f32_16x16x32_bf16 v[28:31], v[178:181], v[194:197], v[28:31]
	v_mfma_f32_16x16x32_bf16 v[16:19], v[170:173], v[202:205], v[16:19]
	v_mfma_f32_16x16x32_bf16 v[12:15], v[178:181], v[202:205], v[12:15]
	v_mfma_f32_16x16x32_bf16 v[8:11], v[170:173], v[210:213], v[8:11]
	v_mfma_f32_16x16x32_bf16 v[4:7], v[178:181], v[210:213], v[4:7]
	v_mfma_f32_16x16x32_bf16 v[48:51], v[174:177], v[190:193], v[48:51]
	v_mfma_f32_16x16x32_bf16 v[44:47], v[182:185], v[190:193], v[44:47]
	v_mfma_f32_16x16x32_bf16 v[32:35], v[174:177], v[198:201], v[32:35]
	v_mfma_f32_16x16x32_bf16 v[28:31], v[182:185], v[198:201], v[28:31]
	v_mfma_f32_16x16x32_bf16 v[16:19], v[174:177], v[206:209], v[16:19]
	v_mfma_f32_16x16x32_bf16 v[12:15], v[182:185], v[206:209], v[12:15]
	v_mfma_f32_16x16x32_bf16 v[8:11], v[174:177], v[214:217], v[8:11]
	v_mfma_f32_16x16x32_bf16 v[4:7], v[182:185], v[214:217], v[4:7]
	s_setprio 0
	s_barrier
	s_add_i32 s0, 0, 0x18000
	v_add_u32_e32 v140, s0, v3
	s_add_i32 s71, 0, 0x1c000
	ds_read_b128 v[154:157], v140
	ds_read_b128 v[158:161], v140 offset:1024
	ds_read_b128 v[162:165], v140 offset:2048
	ds_read_b128 v[166:169], v140 offset:3072
	v_add_u32_e32 v140, s71, v3
	ds_read_b128 v[170:173], v140
	ds_read_b128 v[174:177], v140 offset:1024
	ds_read_b128 v[178:181], v140 offset:2048
	ds_read_b128 v[182:185], v140 offset:3072
	s_add_u32 s98, s52, 0x100000
	s_addc_u32 s99, s53, 0
	s_mov_b32 m0, s48
	ds_read_b128 v[186:189], v152 offset:32768
	ds_read_b128 v[190:193], v152 offset:33792
	ds_read_b128 v[194:197], v152 offset:34816
	ds_read_b128 v[198:201], v152 offset:35840
	ds_read_b128 v[202:205], v152 offset:36864
	ds_read_b128 v[206:209], v152 offset:37888
	ds_read_b128 v[210:213], v152 offset:38912
	ds_read_b128 v[214:217], v152 offset:39936
	global_load_lds_dwordx4 v138, s[98:99]
	s_mov_b32 m0, s49
	s_nop 0
	global_load_lds_dwordx4 v134, s[98:99]
	s_waitcnt vmcnt(8)
	s_waitcnt lgkmcnt(0)
	s_setprio 1
	s_barrier
	v_mfma_f32_16x16x32_bf16 v[128:131], v[154:157], v[186:189], v[128:131]
	v_mfma_f32_16x16x32_bf16 v[124:127], v[162:165], v[186:189], v[124:127]
	v_mfma_f32_16x16x32_bf16 v[120:123], v[154:157], v[194:197], v[120:123]
	v_mfma_f32_16x16x32_bf16 v[116:119], v[162:165], v[194:197], v[116:119]
	v_mfma_f32_16x16x32_bf16 v[104:107], v[154:157], v[202:205], v[104:107]
	v_mfma_f32_16x16x32_bf16 v[100:103], v[162:165], v[202:205], v[100:103]
	v_mfma_f32_16x16x32_bf16 v[88:91], v[154:157], v[210:213], v[88:91]
	v_mfma_f32_16x16x32_bf16 v[84:87], v[162:165], v[210:213], v[84:87]
	v_mfma_f32_16x16x32_bf16 v[128:131], v[158:161], v[190:193], v[128:131]
	v_mfma_f32_16x16x32_bf16 v[124:127], v[166:169], v[190:193], v[124:127]
	v_mfma_f32_16x16x32_bf16 v[120:123], v[158:161], v[198:201], v[120:123]
	v_mfma_f32_16x16x32_bf16 v[116:119], v[166:169], v[198:201], v[116:119]
	v_mfma_f32_16x16x32_bf16 v[104:107], v[158:161], v[206:209], v[104:107]
	v_mfma_f32_16x16x32_bf16 v[100:103], v[166:169], v[206:209], v[100:103]
	v_mfma_f32_16x16x32_bf16 v[88:91], v[158:161], v[214:217], v[88:91]
	v_mfma_f32_16x16x32_bf16 v[84:87], v[166:169], v[214:217], v[84:87]
	s_setprio 0
	s_setprio 1
	v_mfma_f32_16x16x32_bf16 v[112:115], v[170:173], v[186:189], v[112:115]
	v_mfma_f32_16x16x32_bf16 v[108:111], v[178:181], v[186:189], v[108:111]
	v_mfma_f32_16x16x32_bf16 v[96:99], v[170:173], v[194:197], v[96:99]
	v_mfma_f32_16x16x32_bf16 v[92:95], v[178:181], v[194:197], v[92:95]
	v_mfma_f32_16x16x32_bf16 v[80:83], v[170:173], v[202:205], v[80:83]
	v_mfma_f32_16x16x32_bf16 v[76:79], v[178:181], v[202:205], v[76:79]
	v_mfma_f32_16x16x32_bf16 v[72:75], v[170:173], v[210:213], v[72:75]
	v_mfma_f32_16x16x32_bf16 v[68:71], v[178:181], v[210:213], v[68:71]
	v_mfma_f32_16x16x32_bf16 v[112:115], v[174:177], v[190:193], v[112:115]
	v_mfma_f32_16x16x32_bf16 v[108:111], v[182:185], v[190:193], v[108:111]
	v_mfma_f32_16x16x32_bf16 v[96:99], v[174:177], v[198:201], v[96:99]
	v_mfma_f32_16x16x32_bf16 v[92:95], v[182:185], v[198:201], v[92:95]
	v_mfma_f32_16x16x32_bf16 v[80:83], v[174:177], v[206:209], v[80:83]
	v_mfma_f32_16x16x32_bf16 v[76:79], v[182:185], v[206:209], v[76:79]
	v_mfma_f32_16x16x32_bf16 v[72:75], v[174:177], v[214:217], v[72:75]
	v_mfma_f32_16x16x32_bf16 v[68:71], v[182:185], v[214:217], v[68:71]
	s_setprio 0
	s_barrier
	s_add_i32 s0, s0, s46
	s_add_i32 m0, s0, 0xffffff80
	ds_read_b128 v[186:189], v152 offset:49152
	ds_read_b128 v[190:193], v152 offset:50176
	ds_read_b128 v[194:197], v152 offset:51200
	ds_read_b128 v[198:201], v152 offset:52224
	ds_read_b128 v[202:205], v152 offset:53248
	ds_read_b128 v[206:209], v152 offset:54272
	ds_read_b128 v[210:213], v152 offset:55296
	ds_read_b128 v[214:217], v152 offset:56320
	global_load_lds_dwordx4 v136, s[50:51] offset:128
	s_add_i32 m0, s0, 0x1f80
	s_add_i32 s0, s71, s46
	global_load_lds_dwordx4 v132, s[50:51] offset:128
	s_add_u32 s50, s50, 0x100080
	s_addc_u32 s51, s51, 0
	s_mov_b32 m0, s0
	s_nop 0
	global_load_lds_dwordx4 v136, s[50:51]
	s_add_i32 m0, s0, 0x2000
	s_nop 0
	global_load_lds_dwordx4 v132, s[50:51]
	s_add_i32 m0, s58, 0xffffff80
	s_nop 0
	global_load_lds_dwordx4 v138, s[52:53] offset:128
	s_add_i32 m0, s59, 0xffffff80
	s_nop 0
	global_load_lds_dwordx4 v134, s[52:53] offset:128
	s_waitcnt vmcnt(8)
	s_waitcnt lgkmcnt(0)
	s_setprio 1
	s_barrier
	v_mfma_f32_16x16x32_bf16 v[64:67], v[154:157], v[186:189], v[64:67]
	v_mfma_f32_16x16x32_bf16 v[60:63], v[162:165], v[186:189], v[60:63]
	v_mfma_f32_16x16x32_bf16 v[56:59], v[154:157], v[194:197], v[56:59]
	v_mfma_f32_16x16x32_bf16 v[52:55], v[162:165], v[194:197], v[52:55]
	v_mfma_f32_16x16x32_bf16 v[40:43], v[154:157], v[202:205], v[40:43]
	v_mfma_f32_16x16x32_bf16 v[36:39], v[162:165], v[202:205], v[36:39]
	v_mfma_f32_16x16x32_bf16 v[24:27], v[154:157], v[210:213], v[24:27]
	v_mfma_f32_16x16x32_bf16 v[20:23], v[162:165], v[210:213], v[20:23]
	v_mfma_f32_16x16x32_bf16 v[64:67], v[158:161], v[190:193], v[64:67]
	v_mfma_f32_16x16x32_bf16 v[60:63], v[166:169], v[190:193], v[60:63]
	v_mfma_f32_16x16x32_bf16 v[56:59], v[158:161], v[198:201], v[56:59]
	v_mfma_f32_16x16x32_bf16 v[52:55], v[166:169], v[198:201], v[52:55]
	v_mfma_f32_16x16x32_bf16 v[40:43], v[158:161], v[206:209], v[40:43]
	v_mfma_f32_16x16x32_bf16 v[36:39], v[166:169], v[206:209], v[36:39]
	v_mfma_f32_16x16x32_bf16 v[24:27], v[158:161], v[214:217], v[24:27]
	v_mfma_f32_16x16x32_bf16 v[20:23], v[166:169], v[214:217], v[20:23]
	s_setprio 0
	s_setprio 1
	v_mfma_f32_16x16x32_bf16 v[48:51], v[170:173], v[186:189], v[48:51]
	v_mfma_f32_16x16x32_bf16 v[44:47], v[178:181], v[186:189], v[44:47]
	v_mfma_f32_16x16x32_bf16 v[32:35], v[170:173], v[194:197], v[32:35]
	v_mfma_f32_16x16x32_bf16 v[28:31], v[178:181], v[194:197], v[28:31]
	v_mfma_f32_16x16x32_bf16 v[16:19], v[170:173], v[202:205], v[16:19]
	v_mfma_f32_16x16x32_bf16 v[12:15], v[178:181], v[202:205], v[12:15]
	v_mfma_f32_16x16x32_bf16 v[8:11], v[170:173], v[210:213], v[8:11]
	v_mfma_f32_16x16x32_bf16 v[4:7], v[178:181], v[210:213], v[4:7]
	v_mfma_f32_16x16x32_bf16 v[48:51], v[174:177], v[190:193], v[48:51]
	v_mfma_f32_16x16x32_bf16 v[44:47], v[182:185], v[190:193], v[44:47]
	v_mfma_f32_16x16x32_bf16 v[32:35], v[174:177], v[198:201], v[32:35]
	v_mfma_f32_16x16x32_bf16 v[28:31], v[182:185], v[198:201], v[28:31]
	v_mfma_f32_16x16x32_bf16 v[16:19], v[174:177], v[206:209], v[16:19]
	v_mfma_f32_16x16x32_bf16 v[12:15], v[182:185], v[206:209], v[12:15]
	v_mfma_f32_16x16x32_bf16 v[8:11], v[174:177], v[214:217], v[8:11]
	v_mfma_f32_16x16x32_bf16 v[4:7], v[182:185], v[214:217], v[4:7]
	s_setprio 0
	s_barrier
	s_add_i32 s70, s70, 2
	s_add_u32 s42, s42, 0x100
	s_addc_u32 s43, s43, 0
	s_add_u32 s31, s31, 0x100
	s_addc_u32 s41, s41, 0
	s_cmp_gt_u32 s70, 13
	s_cbranch_scc0 .LBB0_1288
	s_and_b64 vcc, exec, s[14:15]
	s_cbranch_vccz .LBB0_1291
	s_barrier

.LBB0_1415:
	ds_read_b128 v[132:135], v187
	ds_read_b128 v[136:139], v187 offset:1024
	ds_read_b128 v[140:143], v187 offset:2048
	ds_read_b128 v[144:147], v187 offset:3072
	ds_read_b128 v[148:151], v188
	ds_read_b128 v[152:155], v188 offset:1024
	ds_read_b128 v[172:175], v188 offset:2048
	ds_read_b128 v[176:179], v188 offset:3072
	s_add_u32 s0, s42, 0xfffe0080
	s_addc_u32 s50, s43, -1
	s_cmp_eq_u32 s64, 4
	s_cselect_b32 s53, s25, s50
	s_cselect_b32 s52, s31, s0
	s_cselect_b32 s51, s23, s63
	s_cselect_b32 s50, s61, s62
	s_add_i32 m0, s41, 0xc000
	ds_read_b128 v[180:183], v189
	ds_read_b128 v[192:195], v189 offset:1024
	ds_read_b128 v[196:199], v189 offset:2048
	ds_read_b128 v[200:203], v189 offset:3072
	ds_read_b128 v[204:207], v189 offset:4096
	ds_read_b128 v[208:211], v189 offset:5120
	ds_read_b128 v[212:215], v189 offset:6144
	ds_read_b128 v[216:219], v189 offset:7168
	global_load_lds_dwordx4 v164, s[42:43]
	s_add_i32 m0, s41, 0xe000
	s_nop 0
	global_load_lds_dwordx4 v166, s[42:43]
	s_waitcnt vmcnt(8)
	s_waitcnt lgkmcnt(0)
	s_setprio 1
	s_barrier
	v_mfma_f32_16x16x32_bf16 v[128:131], v[132:135], v[180:183], v[128:131]
	v_mfma_f32_16x16x32_bf16 v[124:127], v[140:143], v[180:183], v[124:127]
	v_mfma_f32_16x16x32_bf16 v[112:115], v[132:135], v[196:199], v[112:115]
	v_mfma_f32_16x16x32_bf16 v[108:111], v[140:143], v[196:199], v[108:111]
	v_mfma_f32_16x16x32_bf16 v[96:99], v[132:135], v[204:207], v[96:99]
	v_mfma_f32_16x16x32_bf16 v[92:95], v[140:143], v[204:207], v[92:95]
	v_mfma_f32_16x16x32_bf16 v[80:83], v[132:135], v[212:215], v[80:83]
	v_mfma_f32_16x16x32_bf16 v[76:79], v[140:143], v[212:215], v[76:79]
	v_mfma_f32_16x16x32_bf16 v[128:131], v[136:139], v[192:195], v[128:131]
	v_mfma_f32_16x16x32_bf16 v[124:127], v[144:147], v[192:195], v[124:127]
	v_mfma_f32_16x16x32_bf16 v[112:115], v[136:139], v[200:203], v[112:115]
	v_mfma_f32_16x16x32_bf16 v[108:111], v[144:147], v[200:203], v[108:111]
	v_mfma_f32_16x16x32_bf16 v[96:99], v[136:139], v[208:211], v[96:99]
	v_mfma_f32_16x16x32_bf16 v[92:95], v[144:147], v[208:211], v[92:95]
	v_mfma_f32_16x16x32_bf16 v[80:83], v[136:139], v[216:219], v[80:83]
	v_mfma_f32_16x16x32_bf16 v[76:79], v[144:147], v[216:219], v[76:79]
	s_setprio 0
	s_setprio 1
	v_mfma_f32_16x16x32_bf16 v[120:123], v[148:151], v[180:183], v[120:123]
	v_mfma_f32_16x16x32_bf16 v[116:119], v[172:175], v[180:183], v[116:119]
	v_mfma_f32_16x16x32_bf16 v[104:107], v[148:151], v[196:199], v[104:107]
	v_mfma_f32_16x16x32_bf16 v[100:103], v[172:175], v[196:199], v[100:103]
	v_mfma_f32_16x16x32_bf16 v[88:91], v[148:151], v[204:207], v[88:91]
	v_mfma_f32_16x16x32_bf16 v[84:87], v[172:175], v[204:207], v[84:87]
	v_mfma_f32_16x16x32_bf16 v[72:75], v[148:151], v[212:215], v[72:75]
	v_mfma_f32_16x16x32_bf16 v[68:71], v[172:175], v[212:215], v[68:71]
	v_mfma_f32_16x16x32_bf16 v[120:123], v[152:155], v[192:195], v[120:123]
	v_mfma_f32_16x16x32_bf16 v[116:119], v[176:179], v[192:195], v[116:119]
	v_mfma_f32_16x16x32_bf16 v[104:107], v[152:155], v[200:203], v[104:107]
	v_mfma_f32_16x16x32_bf16 v[100:103], v[176:179], v[200:203], v[100:103]
	v_mfma_f32_16x16x32_bf16 v[88:91], v[152:155], v[208:211], v[88:91]
	v_mfma_f32_16x16x32_bf16 v[84:87], v[176:179], v[208:211], v[84:87]
	v_mfma_f32_16x16x32_bf16 v[72:75], v[152:155], v[216:219], v[72:75]
	v_mfma_f32_16x16x32_bf16 v[68:71], v[176:179], v[216:219], v[68:71]
	s_setprio 0
	s_barrier
	s_add_i32 s0, s58, s45
	s_mov_b32 m0, s0
	ds_read_b128 v[180:183], v189 offset:16384
	ds_read_b128 v[192:195], v189 offset:17408
	ds_read_b128 v[196:199], v189 offset:18432
	ds_read_b128 v[200:203], v189 offset:19456
	ds_read_b128 v[204:207], v189 offset:20480
	ds_read_b128 v[208:211], v189 offset:21504
	ds_read_b128 v[212:215], v189 offset:22528
	ds_read_b128 v[216:219], v189 offset:23552
	global_load_lds_dwordx4 v158, s[50:51]
	s_add_i32 m0, s0, 0x2000
	s_add_u32 s66, s50, 0x20000
	s_addc_u32 s67, s51, 0
	s_add_i32 s0, s59, s45
	global_load_lds_dwordx4 v162, s[50:51]
	s_mov_b32 m0, s0
	s_nop 0
	global_load_lds_dwordx4 v158, s[66:67]
	s_add_i32 m0, s0, 0x2000
	s_nop 0
	global_load_lds_dwordx4 v162, s[66:67]
	s_mov_b32 m0, s41
	s_nop 0
	global_load_lds_dwordx4 v156, s[52:53]
	s_mov_b32 m0, s46
	s_nop 0
	global_load_lds_dwordx4 v160, s[52:53]
	s_waitcnt vmcnt(8)
	s_waitcnt lgkmcnt(0)
	s_setprio 1
	s_barrier
	v_mfma_f32_16x16x32_bf16 v[64:67], v[132:135], v[180:183], v[64:67]
	v_mfma_f32_16x16x32_bf16 v[60:63], v[140:143], v[180:183], v[60:63]
	v_mfma_f32_16x16x32_bf16 v[48:51], v[132:135], v[196:199], v[48:51]
	v_mfma_f32_16x16x32_bf16 v[44:47], v[140:143], v[196:199], v[44:47]
	v_mfma_f32_16x16x32_bf16 v[32:35], v[132:135], v[204:207], v[32:35]
	v_mfma_f32_16x16x32_bf16 v[28:31], v[140:143], v[204:207], v[28:31]
	v_mfma_f32_16x16x32_bf16 v[16:19], v[132:135], v[212:215], v[16:19]
	v_mfma_f32_16x16x32_bf16 v[12:15], v[140:143], v[212:215], v[12:15]
	v_mfma_f32_16x16x32_bf16 v[64:67], v[136:139], v[192:195], v[64:67]
	v_mfma_f32_16x16x32_bf16 v[60:63], v[144:147], v[192:195], v[60:63]
	v_mfma_f32_16x16x32_bf16 v[48:51], v[136:139], v[200:203], v[48:51]
	v_mfma_f32_16x16x32_bf16 v[44:47], v[144:147], v[200:203], v[44:47]
	v_mfma_f32_16x16x32_bf16 v[32:35], v[136:139], v[208:211], v[32:35]
	v_mfma_f32_16x16x32_bf16 v[28:31], v[144:147], v[208:211], v[28:31]
	v_mfma_f32_16x16x32_bf16 v[16:19], v[136:139], v[216:219], v[16:19]
	v_mfma_f32_16x16x32_bf16 v[12:15], v[144:147], v[216:219], v[12:15]
	s_setprio 0
	s_setprio 1
	v_mfma_f32_16x16x32_bf16 v[56:59], v[148:151], v[180:183], v[56:59]
	v_mfma_f32_16x16x32_bf16 v[52:55], v[172:175], v[180:183], v[52:55]
	v_mfma_f32_16x16x32_bf16 v[40:43], v[148:151], v[196:199], v[40:43]
	v_mfma_f32_16x16x32_bf16 v[36:39], v[172:175], v[196:199], v[36:39]
	v_mfma_f32_16x16x32_bf16 v[24:27], v[148:151], v[204:207], v[24:27]
	v_mfma_f32_16x16x32_bf16 v[20:23], v[172:175], v[204:207], v[20:23]
	v_mfma_f32_16x16x32_bf16 v[8:11], v[148:151], v[212:215], v[8:11]
	v_mfma_f32_16x16x32_bf16 v[4:7], v[172:175], v[212:215], v[4:7]
	v_mfma_f32_16x16x32_bf16 v[56:59], v[152:155], v[192:195], v[56:59]
	v_mfma_f32_16x16x32_bf16 v[52:55], v[176:179], v[192:195], v[52:55]
	v_mfma_f32_16x16x32_bf16 v[40:43], v[152:155], v[200:203], v[40:43]
	v_mfma_f32_16x16x32_bf16 v[36:39], v[176:179], v[200:203], v[36:39]
	v_mfma_f32_16x16x32_bf16 v[24:27], v[152:155], v[208:211], v[24:27]
	v_mfma_f32_16x16x32_bf16 v[20:23], v[176:179], v[208:211], v[20:23]
	v_mfma_f32_16x16x32_bf16 v[8:11], v[152:155], v[216:219], v[8:11]
	v_mfma_f32_16x16x32_bf16 v[4:7], v[176:179], v[216:219], v[4:7]
	s_setprio 0
	s_barrier
	s_add_i32 s0, 0, 0x18000
	s_add_i32 s65, 0, 0x1c000
	v_add_u32_e32 v144, s0, v3
	v_add_u32_e32 v176, s65, v3
	ds_read_b128 v[132:135], v144
	ds_read_b128 v[136:139], v144 offset:1024
	ds_read_b128 v[140:143], v144 offset:2048
	ds_read_b128 v[144:147], v144 offset:3072
	ds_read_b128 v[148:151], v176
	ds_read_b128 v[152:155], v176 offset:1024
	ds_read_b128 v[172:175], v176 offset:2048
	ds_read_b128 v[176:179], v176 offset:3072
	s_add_u32 s98, s52, 0x20000
	s_addc_u32 s99, s53, 0
	s_mov_b32 m0, s47
	ds_read_b128 v[180:183], v189 offset:32768
	ds_read_b128 v[192:195], v189 offset:33792
	ds_read_b128 v[196:199], v189 offset:34816
	ds_read_b128 v[200:203], v189 offset:35840
	ds_read_b128 v[204:207], v189 offset:36864
	ds_read_b128 v[208:211], v189 offset:37888
	ds_read_b128 v[212:215], v189 offset:38912
	ds_read_b128 v[216:219], v189 offset:39936
	global_load_lds_dwordx4 v156, s[98:99]
	s_mov_b32 m0, s48
	s_nop 0
	global_load_lds_dwordx4 v160, s[98:99]
	s_waitcnt vmcnt(8)
	s_waitcnt lgkmcnt(0)
	s_setprio 1
	s_barrier
	v_mfma_f32_16x16x32_bf16 v[128:131], v[132:135], v[180:183], v[128:131]
	v_mfma_f32_16x16x32_bf16 v[124:127], v[140:143], v[180:183], v[124:127]
	v_mfma_f32_16x16x32_bf16 v[112:115], v[132:135], v[196:199], v[112:115]
	v_mfma_f32_16x16x32_bf16 v[108:111], v[140:143], v[196:199], v[108:111]
	v_mfma_f32_16x16x32_bf16 v[96:99], v[132:135], v[204:207], v[96:99]
	v_mfma_f32_16x16x32_bf16 v[92:95], v[140:143], v[204:207], v[92:95]
	v_mfma_f32_16x16x32_bf16 v[80:83], v[132:135], v[212:215], v[80:83]
	v_mfma_f32_16x16x32_bf16 v[76:79], v[140:143], v[212:215], v[76:79]
	v_mfma_f32_16x16x32_bf16 v[128:131], v[136:139], v[192:195], v[128:131]
	v_mfma_f32_16x16x32_bf16 v[124:127], v[144:147], v[192:195], v[124:127]
	v_mfma_f32_16x16x32_bf16 v[112:115], v[136:139], v[200:203], v[112:115]
	v_mfma_f32_16x16x32_bf16 v[108:111], v[144:147], v[200:203], v[108:111]
	v_mfma_f32_16x16x32_bf16 v[96:99], v[136:139], v[208:211], v[96:99]
	v_mfma_f32_16x16x32_bf16 v[92:95], v[144:147], v[208:211], v[92:95]
	v_mfma_f32_16x16x32_bf16 v[80:83], v[136:139], v[216:219], v[80:83]
	v_mfma_f32_16x16x32_bf16 v[76:79], v[144:147], v[216:219], v[76:79]
	s_setprio 0
	s_setprio 1
	v_mfma_f32_16x16x32_bf16 v[120:123], v[148:151], v[180:183], v[120:123]
	v_mfma_f32_16x16x32_bf16 v[116:119], v[172:175], v[180:183], v[116:119]
	v_mfma_f32_16x16x32_bf16 v[104:107], v[148:151], v[196:199], v[104:107]
	v_mfma_f32_16x16x32_bf16 v[100:103], v[172:175], v[196:199], v[100:103]
	v_mfma_f32_16x16x32_bf16 v[88:91], v[148:151], v[204:207], v[88:91]
	v_mfma_f32_16x16x32_bf16 v[84:87], v[172:175], v[204:207], v[84:87]
	v_mfma_f32_16x16x32_bf16 v[72:75], v[148:151], v[212:215], v[72:75]
	v_mfma_f32_16x16x32_bf16 v[68:71], v[172:175], v[212:215], v[68:71]
	v_mfma_f32_16x16x32_bf16 v[120:123], v[152:155], v[192:195], v[120:123]
	v_mfma_f32_16x16x32_bf16 v[116:119], v[176:179], v[192:195], v[116:119]
	v_mfma_f32_16x16x32_bf16 v[104:107], v[152:155], v[200:203], v[104:107]
	v_mfma_f32_16x16x32_bf16 v[100:103], v[176:179], v[200:203], v[100:103]
	v_mfma_f32_16x16x32_bf16 v[88:91], v[152:155], v[208:211], v[88:91]
	v_mfma_f32_16x16x32_bf16 v[84:87], v[176:179], v[208:211], v[84:87]
	v_mfma_f32_16x16x32_bf16 v[72:75], v[152:155], v[216:219], v[72:75]
	v_mfma_f32_16x16x32_bf16 v[68:71], v[176:179], v[216:219], v[68:71]
	s_setprio 0
	s_barrier
	s_add_i32 s0, s0, s45
	s_add_i32 m0, s0, 0xffffff80
	ds_read_b128 v[180:183], v189 offset:49152
	ds_read_b128 v[192:195], v189 offset:50176
	ds_read_b128 v[196:199], v189 offset:51200
	ds_read_b128 v[200:203], v189 offset:52224
	ds_read_b128 v[204:207], v189 offset:53248
	ds_read_b128 v[208:211], v189 offset:54272
	ds_read_b128 v[212:215], v189 offset:55296
	ds_read_b128 v[216:219], v189 offset:56320
	global_load_lds_dwordx4 v158, s[50:51] offset:128
	s_add_i32 m0, s0, 0x1f80
	s_add_i32 s0, s65, s45
	global_load_lds_dwordx4 v162, s[50:51] offset:128
	s_add_u32 s50, s50, 0x20080
	s_addc_u32 s51, s51, 0
	s_mov_b32 m0, s0
	s_nop 0
	global_load_lds_dwordx4 v158, s[50:51]
	s_add_i32 m0, s0, 0x2000
	s_nop 0
	global_load_lds_dwordx4 v162, s[50:51]
	s_add_i32 m0, s56, 0xffffff80
	s_nop 0
	global_load_lds_dwordx4 v156, s[52:53] offset:128
	s_add_i32 m0, s57, 0xffffff80
	s_nop 0
	global_load_lds_dwordx4 v160, s[52:53] offset:128
	s_waitcnt vmcnt(8)
	s_waitcnt lgkmcnt(0)
	s_setprio 1
	s_barrier
	v_mfma_f32_16x16x32_bf16 v[64:67], v[132:135], v[180:183], v[64:67]
	v_mfma_f32_16x16x32_bf16 v[60:63], v[140:143], v[180:183], v[60:63]
	v_mfma_f32_16x16x32_bf16 v[48:51], v[132:135], v[196:199], v[48:51]
	v_mfma_f32_16x16x32_bf16 v[44:47], v[140:143], v[196:199], v[44:47]
	v_mfma_f32_16x16x32_bf16 v[32:35], v[132:135], v[204:207], v[32:35]
	v_mfma_f32_16x16x32_bf16 v[28:31], v[140:143], v[204:207], v[28:31]
	v_mfma_f32_16x16x32_bf16 v[16:19], v[132:135], v[212:215], v[16:19]
	v_mfma_f32_16x16x32_bf16 v[12:15], v[140:143], v[212:215], v[12:15]
	v_mfma_f32_16x16x32_bf16 v[64:67], v[136:139], v[192:195], v[64:67]
	v_mfma_f32_16x16x32_bf16 v[60:63], v[144:147], v[192:195], v[60:63]
	v_mfma_f32_16x16x32_bf16 v[48:51], v[136:139], v[200:203], v[48:51]
	v_mfma_f32_16x16x32_bf16 v[44:47], v[144:147], v[200:203], v[44:47]
	v_mfma_f32_16x16x32_bf16 v[32:35], v[136:139], v[208:211], v[32:35]
	v_mfma_f32_16x16x32_bf16 v[28:31], v[144:147], v[208:211], v[28:31]
	v_mfma_f32_16x16x32_bf16 v[16:19], v[136:139], v[216:219], v[16:19]
	v_mfma_f32_16x16x32_bf16 v[12:15], v[144:147], v[216:219], v[12:15]
	s_setprio 0
	s_setprio 1
	v_mfma_f32_16x16x32_bf16 v[56:59], v[148:151], v[180:183], v[56:59]
	v_mfma_f32_16x16x32_bf16 v[52:55], v[172:175], v[180:183], v[52:55]
	v_mfma_f32_16x16x32_bf16 v[40:43], v[148:151], v[196:199], v[40:43]
	v_mfma_f32_16x16x32_bf16 v[36:39], v[172:175], v[196:199], v[36:39]
	v_mfma_f32_16x16x32_bf16 v[24:27], v[148:151], v[204:207], v[24:27]
	v_mfma_f32_16x16x32_bf16 v[20:23], v[172:175], v[204:207], v[20:23]
	v_mfma_f32_16x16x32_bf16 v[8:11], v[148:151], v[212:215], v[8:11]
	v_mfma_f32_16x16x32_bf16 v[4:7], v[172:175], v[212:215], v[4:7]
	v_mfma_f32_16x16x32_bf16 v[56:59], v[152:155], v[192:195], v[56:59]
	v_mfma_f32_16x16x32_bf16 v[52:55], v[176:179], v[192:195], v[52:55]
	v_mfma_f32_16x16x32_bf16 v[40:43], v[152:155], v[200:203], v[40:43]
	v_mfma_f32_16x16x32_bf16 v[36:39], v[176:179], v[200:203], v[36:39]
	v_mfma_f32_16x16x32_bf16 v[24:27], v[152:155], v[208:211], v[24:27]
	v_mfma_f32_16x16x32_bf16 v[20:23], v[176:179], v[208:211], v[20:23]
	v_mfma_f32_16x16x32_bf16 v[8:11], v[152:155], v[216:219], v[8:11]
	v_mfma_f32_16x16x32_bf16 v[4:7], v[176:179], v[216:219], v[4:7]
	s_setprio 0
	s_barrier
	s_add_i32 s64, s64, 2
	s_add_u32 s42, s42, 0x100
	s_addc_u32 s43, s43, 0
	s_add_u32 s62, s62, 0x100
	s_addc_u32 s63, s63, 0
	s_cmp_gt_u32 s64, 5
	s_cbranch_scc0 .LBB0_1415
	s_and_b64 vcc, exec, s[16:17]
	s_cbranch_vccz .LBB0_1418
	s_barrier

.LBB0_1503:
	ds_read_b128 v[132:135], v159
	ds_read_b128 v[164:167], v159 offset:1024
	ds_read_b128 v[168:171], v159 offset:2048
	ds_read_b128 v[172:175], v159 offset:3072
	ds_read_b128 v[176:179], v160
	ds_read_b128 v[180:183], v160 offset:1024
	ds_read_b128 v[184:187], v160 offset:2048
	ds_read_b128 v[188:191], v160 offset:3072
	s_add_u32 s0, s54, 0xfff00080
	s_addc_u32 s56, s55, -1
	s_cmp_eq_u32 s75, 60
	s_cselect_b32 s59, s31, s56
	s_cselect_b32 s58, s71, s0
	s_cselect_b32 s57, s29, s74
	s_cselect_b32 s56, s72, s73
	s_add_i32 m0, s48, 0xc000
	ds_read_b128 v[192:195], v161
	ds_read_b128 v[196:199], v161 offset:1024
	ds_read_b128 v[200:203], v161 offset:2048
	ds_read_b128 v[204:207], v161 offset:3072
	ds_read_b128 v[208:211], v161 offset:4096
	ds_read_b128 v[212:215], v161 offset:5120
	ds_read_b128 v[216:219], v161 offset:6144
	ds_read_b128 v[220:223], v161 offset:7168
	global_load_lds_dwordx4 v148, s[54:55]
	s_add_i32 m0, s48, 0xe000
	s_nop 0
	global_load_lds_dwordx4 v150, s[54:55]
	s_waitcnt vmcnt(8)
	s_waitcnt lgkmcnt(0)
	s_setprio 1
	s_barrier
	v_mfma_f32_16x16x32_bf16 v[136:139], v[132:135], v[192:195], v[136:139]
	v_mfma_f32_16x16x32_bf16 v[128:131], v[168:171], v[192:195], v[128:131]
	v_mfma_f32_16x16x32_bf16 v[116:119], v[132:135], v[200:203], v[116:119]
	v_mfma_f32_16x16x32_bf16 v[112:115], v[168:171], v[200:203], v[112:115]
	v_mfma_f32_16x16x32_bf16 v[100:103], v[132:135], v[208:211], v[100:103]
	v_mfma_f32_16x16x32_bf16 v[96:99], v[168:171], v[208:211], v[96:99]
	v_mfma_f32_16x16x32_bf16 v[84:87], v[132:135], v[216:219], v[84:87]
	v_mfma_f32_16x16x32_bf16 v[80:83], v[168:171], v[216:219], v[80:83]
	v_mfma_f32_16x16x32_bf16 v[136:139], v[164:167], v[196:199], v[136:139]
	v_mfma_f32_16x16x32_bf16 v[128:131], v[172:175], v[196:199], v[128:131]
	v_mfma_f32_16x16x32_bf16 v[116:119], v[164:167], v[204:207], v[116:119]
	v_mfma_f32_16x16x32_bf16 v[112:115], v[172:175], v[204:207], v[112:115]
	v_mfma_f32_16x16x32_bf16 v[100:103], v[164:167], v[212:215], v[100:103]
	v_mfma_f32_16x16x32_bf16 v[96:99], v[172:175], v[212:215], v[96:99]
	v_mfma_f32_16x16x32_bf16 v[84:87], v[164:167], v[220:223], v[84:87]
	v_mfma_f32_16x16x32_bf16 v[80:83], v[172:175], v[220:223], v[80:83]
	s_setprio 0
	s_setprio 1
	v_mfma_f32_16x16x32_bf16 v[124:127], v[176:179], v[192:195], v[124:127]
	v_mfma_f32_16x16x32_bf16 v[120:123], v[184:187], v[192:195], v[120:123]
	v_mfma_f32_16x16x32_bf16 v[108:111], v[176:179], v[200:203], v[108:111]
	v_mfma_f32_16x16x32_bf16 v[104:107], v[184:187], v[200:203], v[104:107]
	v_mfma_f32_16x16x32_bf16 v[92:95], v[176:179], v[208:211], v[92:95]
	v_mfma_f32_16x16x32_bf16 v[88:91], v[184:187], v[208:211], v[88:91]
	v_mfma_f32_16x16x32_bf16 v[76:79], v[176:179], v[216:219], v[76:79]
	v_mfma_f32_16x16x32_bf16 v[72:75], v[184:187], v[216:219], v[72:75]
	v_mfma_f32_16x16x32_bf16 v[124:127], v[180:183], v[196:199], v[124:127]
	v_mfma_f32_16x16x32_bf16 v[120:123], v[188:191], v[196:199], v[120:123]
	v_mfma_f32_16x16x32_bf16 v[108:111], v[180:183], v[204:207], v[108:111]
	v_mfma_f32_16x16x32_bf16 v[104:107], v[188:191], v[204:207], v[104:107]
	v_mfma_f32_16x16x32_bf16 v[92:95], v[180:183], v[212:215], v[92:95]
	v_mfma_f32_16x16x32_bf16 v[88:91], v[188:191], v[212:215], v[88:91]
	v_mfma_f32_16x16x32_bf16 v[76:79], v[180:183], v[220:223], v[76:79]
	v_mfma_f32_16x16x32_bf16 v[72:75], v[188:191], v[220:223], v[72:75]
	s_setprio 0
	s_barrier
	s_add_i32 s0, s65, s47
	s_mov_b32 m0, s0
	ds_read_b128 v[192:195], v161 offset:16384
	ds_read_b128 v[196:199], v161 offset:17408
	ds_read_b128 v[200:203], v161 offset:18432
	ds_read_b128 v[204:207], v161 offset:19456
	ds_read_b128 v[208:211], v161 offset:20480
	ds_read_b128 v[212:215], v161 offset:21504
	ds_read_b128 v[216:219], v161 offset:22528
	ds_read_b128 v[220:223], v161 offset:23552
	global_load_lds_dwordx4 v142, s[56:57]
	s_add_i32 m0, s0, 0x2000
	s_add_u32 s76, s56, 0x100000
	s_addc_u32 s77, s57, 0
	s_add_i32 s0, s66, s47
	global_load_lds_dwordx4 v146, s[56:57]
	s_mov_b32 m0, s0
	s_nop 0
	global_load_lds_dwordx4 v142, s[76:77]
	s_add_i32 m0, s0, 0x2000
	s_nop 0
	global_load_lds_dwordx4 v146, s[76:77]
	s_mov_b32 m0, s48
	s_nop 0
	global_load_lds_dwordx4 v140, s[58:59]
	s_mov_b32 m0, s49
	s_nop 0
	global_load_lds_dwordx4 v144, s[58:59]
	s_waitcnt vmcnt(8)
	s_waitcnt lgkmcnt(0)
	s_setprio 1
	s_barrier
	v_mfma_f32_16x16x32_bf16 v[68:71], v[132:135], v[192:195], v[68:71]
	v_mfma_f32_16x16x32_bf16 v[64:67], v[168:171], v[192:195], v[64:67]
	v_mfma_f32_16x16x32_bf16 v[52:55], v[132:135], v[200:203], v[52:55]
	v_mfma_f32_16x16x32_bf16 v[48:51], v[168:171], v[200:203], v[48:51]
	v_mfma_f32_16x16x32_bf16 v[36:39], v[132:135], v[208:211], v[36:39]
	v_mfma_f32_16x16x32_bf16 v[32:35], v[168:171], v[208:211], v[32:35]
	v_mfma_f32_16x16x32_bf16 v[20:23], v[132:135], v[216:219], v[20:23]
	v_mfma_f32_16x16x32_bf16 v[16:19], v[168:171], v[216:219], v[16:19]
	v_mfma_f32_16x16x32_bf16 v[68:71], v[164:167], v[196:199], v[68:71]
	v_mfma_f32_16x16x32_bf16 v[64:67], v[172:175], v[196:199], v[64:67]
	v_mfma_f32_16x16x32_bf16 v[52:55], v[164:167], v[204:207], v[52:55]
	v_mfma_f32_16x16x32_bf16 v[48:51], v[172:175], v[204:207], v[48:51]
	v_mfma_f32_16x16x32_bf16 v[36:39], v[164:167], v[212:215], v[36:39]
	v_mfma_f32_16x16x32_bf16 v[32:35], v[172:175], v[212:215], v[32:35]
	v_mfma_f32_16x16x32_bf16 v[20:23], v[164:167], v[220:223], v[20:23]
	v_mfma_f32_16x16x32_bf16 v[16:19], v[172:175], v[220:223], v[16:19]
	s_setprio 0
	s_setprio 1
	v_mfma_f32_16x16x32_bf16 v[60:63], v[176:179], v[192:195], v[60:63]
	v_mfma_f32_16x16x32_bf16 v[56:59], v[184:187], v[192:195], v[56:59]
	v_mfma_f32_16x16x32_bf16 v[44:47], v[176:179], v[200:203], v[44:47]
	v_mfma_f32_16x16x32_bf16 v[40:43], v[184:187], v[200:203], v[40:43]
	v_mfma_f32_16x16x32_bf16 v[28:31], v[176:179], v[208:211], v[28:31]
	v_mfma_f32_16x16x32_bf16 v[24:27], v[184:187], v[208:211], v[24:27]
	v_mfma_f32_16x16x32_bf16 v[12:15], v[176:179], v[216:219], v[12:15]
	v_mfma_f32_16x16x32_bf16 v[8:11], v[184:187], v[216:219], v[8:11]
	v_mfma_f32_16x16x32_bf16 v[60:63], v[180:183], v[196:199], v[60:63]
	v_mfma_f32_16x16x32_bf16 v[56:59], v[188:191], v[196:199], v[56:59]
	v_mfma_f32_16x16x32_bf16 v[44:47], v[180:183], v[204:207], v[44:47]
	v_mfma_f32_16x16x32_bf16 v[40:43], v[188:191], v[204:207], v[40:43]
	v_mfma_f32_16x16x32_bf16 v[28:31], v[180:183], v[212:215], v[28:31]
	v_mfma_f32_16x16x32_bf16 v[24:27], v[188:191], v[212:215], v[24:27]
	v_mfma_f32_16x16x32_bf16 v[12:15], v[180:183], v[220:223], v[12:15]
	v_mfma_f32_16x16x32_bf16 v[8:11], v[188:191], v[220:223], v[8:11]
	s_setprio 0
	s_barrier
	s_add_i32 s0, 0, 0x18000
	s_add_i32 s76, 0, 0x1c000
	v_add_u32_e32 v172, s0, v156
	v_add_u32_e32 v188, s76, v156
	ds_read_b128 v[132:135], v172
	ds_read_b128 v[164:167], v172 offset:1024
	ds_read_b128 v[168:171], v172 offset:2048
	ds_read_b128 v[172:175], v172 offset:3072
	ds_read_b128 v[176:179], v188
	ds_read_b128 v[180:183], v188 offset:1024
	ds_read_b128 v[184:187], v188 offset:2048
	ds_read_b128 v[188:191], v188 offset:3072
	s_add_u32 s98, s58, 0x100000
	s_addc_u32 s99, s59, 0
	s_mov_b32 m0, s51
	ds_read_b128 v[192:195], v161 offset:32768
	ds_read_b128 v[196:199], v161 offset:33792
	ds_read_b128 v[200:203], v161 offset:34816
	ds_read_b128 v[204:207], v161 offset:35840
	ds_read_b128 v[208:211], v161 offset:36864
	ds_read_b128 v[212:215], v161 offset:37888
	ds_read_b128 v[216:219], v161 offset:38912
	ds_read_b128 v[220:223], v161 offset:39936
	global_load_lds_dwordx4 v140, s[98:99]
	s_mov_b32 m0, s53
	s_nop 0
	global_load_lds_dwordx4 v144, s[98:99]
	s_waitcnt vmcnt(8)
	s_waitcnt lgkmcnt(0)
	s_setprio 1
	s_barrier
	v_mfma_f32_16x16x32_bf16 v[136:139], v[132:135], v[192:195], v[136:139]
	v_mfma_f32_16x16x32_bf16 v[128:131], v[168:171], v[192:195], v[128:131]
	v_mfma_f32_16x16x32_bf16 v[116:119], v[132:135], v[200:203], v[116:119]
	v_mfma_f32_16x16x32_bf16 v[112:115], v[168:171], v[200:203], v[112:115]
	v_mfma_f32_16x16x32_bf16 v[100:103], v[132:135], v[208:211], v[100:103]
	v_mfma_f32_16x16x32_bf16 v[96:99], v[168:171], v[208:211], v[96:99]
	v_mfma_f32_16x16x32_bf16 v[84:87], v[132:135], v[216:219], v[84:87]
	v_mfma_f32_16x16x32_bf16 v[80:83], v[168:171], v[216:219], v[80:83]
	v_mfma_f32_16x16x32_bf16 v[136:139], v[164:167], v[196:199], v[136:139]
	v_mfma_f32_16x16x32_bf16 v[128:131], v[172:175], v[196:199], v[128:131]
	v_mfma_f32_16x16x32_bf16 v[116:119], v[164:167], v[204:207], v[116:119]
	v_mfma_f32_16x16x32_bf16 v[112:115], v[172:175], v[204:207], v[112:115]
	v_mfma_f32_16x16x32_bf16 v[100:103], v[164:167], v[212:215], v[100:103]
	v_mfma_f32_16x16x32_bf16 v[96:99], v[172:175], v[212:215], v[96:99]
	v_mfma_f32_16x16x32_bf16 v[84:87], v[164:167], v[220:223], v[84:87]
	v_mfma_f32_16x16x32_bf16 v[80:83], v[172:175], v[220:223], v[80:83]
	s_setprio 0
	s_setprio 1
	v_mfma_f32_16x16x32_bf16 v[124:127], v[176:179], v[192:195], v[124:127]
	v_mfma_f32_16x16x32_bf16 v[120:123], v[184:187], v[192:195], v[120:123]
	v_mfma_f32_16x16x32_bf16 v[108:111], v[176:179], v[200:203], v[108:111]
	v_mfma_f32_16x16x32_bf16 v[104:107], v[184:187], v[200:203], v[104:107]
	v_mfma_f32_16x16x32_bf16 v[92:95], v[176:179], v[208:211], v[92:95]
	v_mfma_f32_16x16x32_bf16 v[88:91], v[184:187], v[208:211], v[88:91]
	v_mfma_f32_16x16x32_bf16 v[76:79], v[176:179], v[216:219], v[76:79]
	v_mfma_f32_16x16x32_bf16 v[72:75], v[184:187], v[216:219], v[72:75]
	v_mfma_f32_16x16x32_bf16 v[124:127], v[180:183], v[196:199], v[124:127]
	v_mfma_f32_16x16x32_bf16 v[120:123], v[188:191], v[196:199], v[120:123]
	v_mfma_f32_16x16x32_bf16 v[108:111], v[180:183], v[204:207], v[108:111]
	v_mfma_f32_16x16x32_bf16 v[104:107], v[188:191], v[204:207], v[104:107]
	v_mfma_f32_16x16x32_bf16 v[92:95], v[180:183], v[212:215], v[92:95]
	v_mfma_f32_16x16x32_bf16 v[88:91], v[188:191], v[212:215], v[88:91]
	v_mfma_f32_16x16x32_bf16 v[76:79], v[180:183], v[220:223], v[76:79]
	v_mfma_f32_16x16x32_bf16 v[72:75], v[188:191], v[220:223], v[72:75]
	s_setprio 0
	s_barrier
	s_add_i32 s0, s0, s47
	s_add_i32 m0, s0, 0xffffff80
	ds_read_b128 v[192:195], v161 offset:49152
	ds_read_b128 v[196:199], v161 offset:50176
	ds_read_b128 v[200:203], v161 offset:51200
	ds_read_b128 v[204:207], v161 offset:52224
	ds_read_b128 v[208:211], v161 offset:53248
	ds_read_b128 v[212:215], v161 offset:54272
	ds_read_b128 v[216:219], v161 offset:55296
	ds_read_b128 v[220:223], v161 offset:56320
	global_load_lds_dwordx4 v142, s[56:57] offset:128
	s_add_i32 m0, s0, 0x1f80
	s_add_i32 s0, s76, s47
	global_load_lds_dwordx4 v146, s[56:57] offset:128
	s_add_u32 s56, s56, 0x100080
	s_addc_u32 s57, s57, 0
	s_mov_b32 m0, s0
	s_nop 0
	global_load_lds_dwordx4 v142, s[56:57]
	s_add_i32 m0, s0, 0x2000
	s_nop 0
	global_load_lds_dwordx4 v146, s[56:57]
	s_add_i32 m0, s62, 0xffffff80
	s_nop 0
	global_load_lds_dwordx4 v140, s[58:59] offset:128
	s_add_i32 m0, s63, 0xffffff80
	s_nop 0
	global_load_lds_dwordx4 v144, s[58:59] offset:128
	s_waitcnt vmcnt(8)
	s_waitcnt lgkmcnt(0)
	s_setprio 1
	s_barrier
	v_mfma_f32_16x16x32_bf16 v[68:71], v[132:135], v[192:195], v[68:71]
	v_mfma_f32_16x16x32_bf16 v[64:67], v[168:171], v[192:195], v[64:67]
	v_mfma_f32_16x16x32_bf16 v[52:55], v[132:135], v[200:203], v[52:55]
	v_mfma_f32_16x16x32_bf16 v[48:51], v[168:171], v[200:203], v[48:51]
	v_mfma_f32_16x16x32_bf16 v[36:39], v[132:135], v[208:211], v[36:39]
	v_mfma_f32_16x16x32_bf16 v[32:35], v[168:171], v[208:211], v[32:35]
	v_mfma_f32_16x16x32_bf16 v[20:23], v[132:135], v[216:219], v[20:23]
	v_mfma_f32_16x16x32_bf16 v[16:19], v[168:171], v[216:219], v[16:19]
	v_mfma_f32_16x16x32_bf16 v[68:71], v[164:167], v[196:199], v[68:71]
	v_mfma_f32_16x16x32_bf16 v[64:67], v[172:175], v[196:199], v[64:67]
	v_mfma_f32_16x16x32_bf16 v[52:55], v[164:167], v[204:207], v[52:55]
	v_mfma_f32_16x16x32_bf16 v[48:51], v[172:175], v[204:207], v[48:51]
	v_mfma_f32_16x16x32_bf16 v[36:39], v[164:167], v[212:215], v[36:39]
	v_mfma_f32_16x16x32_bf16 v[32:35], v[172:175], v[212:215], v[32:35]
	v_mfma_f32_16x16x32_bf16 v[20:23], v[164:167], v[220:223], v[20:23]
	v_mfma_f32_16x16x32_bf16 v[16:19], v[172:175], v[220:223], v[16:19]
	s_setprio 0
	s_setprio 1
	v_mfma_f32_16x16x32_bf16 v[60:63], v[176:179], v[192:195], v[60:63]
	v_mfma_f32_16x16x32_bf16 v[56:59], v[184:187], v[192:195], v[56:59]
	v_mfma_f32_16x16x32_bf16 v[44:47], v[176:179], v[200:203], v[44:47]
	v_mfma_f32_16x16x32_bf16 v[40:43], v[184:187], v[200:203], v[40:43]
	v_mfma_f32_16x16x32_bf16 v[28:31], v[176:179], v[208:211], v[28:31]
	v_mfma_f32_16x16x32_bf16 v[24:27], v[184:187], v[208:211], v[24:27]
	v_mfma_f32_16x16x32_bf16 v[12:15], v[176:179], v[216:219], v[12:15]
	v_mfma_f32_16x16x32_bf16 v[8:11], v[184:187], v[216:219], v[8:11]
	v_mfma_f32_16x16x32_bf16 v[60:63], v[180:183], v[196:199], v[60:63]
	v_mfma_f32_16x16x32_bf16 v[56:59], v[188:191], v[196:199], v[56:59]
	v_mfma_f32_16x16x32_bf16 v[44:47], v[180:183], v[204:207], v[44:47]
	v_mfma_f32_16x16x32_bf16 v[40:43], v[188:191], v[204:207], v[40:43]
	v_mfma_f32_16x16x32_bf16 v[28:31], v[180:183], v[212:215], v[28:31]
	v_mfma_f32_16x16x32_bf16 v[24:27], v[188:191], v[212:215], v[24:27]
	v_mfma_f32_16x16x32_bf16 v[12:15], v[180:183], v[220:223], v[12:15]
	v_mfma_f32_16x16x32_bf16 v[8:11], v[188:191], v[220:223], v[8:11]
	s_setprio 0
	s_barrier
	s_add_i32 s75, s75, 2
	s_add_u32 s54, s54, 0x100
	s_addc_u32 s55, s55, 0
	s_add_u32 s73, s73, 0x100
	s_addc_u32 s74, s74, 0
	s_cmp_gt_u32 s75, 61
	s_cbranch_scc0 .LBB0_1503
	s_and_b64 vcc, exec, s[26:27]
	s_cbranch_vccz .LBB0_1506
	s_barrier

.LBB0_1672:
	ds_read_b128 v[132:135], v193
	ds_read_b128 v[136:139], v193 offset:1024
	ds_read_b128 v[140:143], v193 offset:2048
	ds_read_b128 v[144:147], v193 offset:3072
	ds_read_b128 v[148:151], v194
	ds_read_b128 v[152:155], v194 offset:1024
	ds_read_b128 v[172:175], v194 offset:2048
	ds_read_b128 v[176:179], v194 offset:3072
	s_add_u32 s0, s30, 0xffd50080
	s_addc_u32 s42, s31, -1
	s_cmpk_eq_i32 s66, 0xa8
	s_cselect_b32 s51, s7, s42
	s_cselect_b32 s50, s6, s0
	s_cselect_b32 s43, s29, s65
	s_cselect_b32 s42, s28, s64
	s_add_i32 m0, s46, 0xc000
	ds_read_b128 v[180:183], v195
	ds_read_b128 v[198:201], v195 offset:1024
	ds_read_b128 v[202:205], v195 offset:2048
	ds_read_b128 v[206:209], v195 offset:3072
	ds_read_b128 v[210:213], v195 offset:4096
	ds_read_b128 v[214:217], v195 offset:5120
	ds_read_b128 v[218:221], v195 offset:6144
	ds_read_b128 v[222:225], v195 offset:7168
	global_load_lds_dwordx4 v164, s[30:31]
	s_add_i32 m0, s46, 0xe000
	s_nop 0
	global_load_lds_dwordx4 v166, s[30:31]
	s_waitcnt vmcnt(8)
	s_waitcnt lgkmcnt(0)
	s_setprio 1
	s_barrier
	v_mfma_f32_16x16x32_bf16 v[128:131], v[132:135], v[180:183], v[128:131]
	v_mfma_f32_16x16x32_bf16 v[124:127], v[140:143], v[180:183], v[124:127]
	v_mfma_f32_16x16x32_bf16 v[112:115], v[132:135], v[202:205], v[112:115]
	v_mfma_f32_16x16x32_bf16 v[108:111], v[140:143], v[202:205], v[108:111]
	v_mfma_f32_16x16x32_bf16 v[96:99], v[132:135], v[210:213], v[96:99]
	v_mfma_f32_16x16x32_bf16 v[92:95], v[140:143], v[210:213], v[92:95]
	v_mfma_f32_16x16x32_bf16 v[80:83], v[132:135], v[218:221], v[80:83]
	v_mfma_f32_16x16x32_bf16 v[76:79], v[140:143], v[218:221], v[76:79]
	v_mfma_f32_16x16x32_bf16 v[128:131], v[136:139], v[198:201], v[128:131]
	v_mfma_f32_16x16x32_bf16 v[124:127], v[144:147], v[198:201], v[124:127]
	v_mfma_f32_16x16x32_bf16 v[112:115], v[136:139], v[206:209], v[112:115]
	v_mfma_f32_16x16x32_bf16 v[108:111], v[144:147], v[206:209], v[108:111]
	v_mfma_f32_16x16x32_bf16 v[96:99], v[136:139], v[214:217], v[96:99]
	v_mfma_f32_16x16x32_bf16 v[92:95], v[144:147], v[214:217], v[92:95]
	v_mfma_f32_16x16x32_bf16 v[80:83], v[136:139], v[222:225], v[80:83]
	v_mfma_f32_16x16x32_bf16 v[76:79], v[144:147], v[222:225], v[76:79]
	s_setprio 0
	s_setprio 1
	v_mfma_f32_16x16x32_bf16 v[120:123], v[148:151], v[180:183], v[120:123]
	v_mfma_f32_16x16x32_bf16 v[116:119], v[172:175], v[180:183], v[116:119]
	v_mfma_f32_16x16x32_bf16 v[104:107], v[148:151], v[202:205], v[104:107]
	v_mfma_f32_16x16x32_bf16 v[100:103], v[172:175], v[202:205], v[100:103]
	v_mfma_f32_16x16x32_bf16 v[88:91], v[148:151], v[210:213], v[88:91]
	v_mfma_f32_16x16x32_bf16 v[84:87], v[172:175], v[210:213], v[84:87]
	v_mfma_f32_16x16x32_bf16 v[72:75], v[148:151], v[218:221], v[72:75]
	v_mfma_f32_16x16x32_bf16 v[68:71], v[172:175], v[218:221], v[68:71]
	v_mfma_f32_16x16x32_bf16 v[120:123], v[152:155], v[198:201], v[120:123]
	v_mfma_f32_16x16x32_bf16 v[116:119], v[176:179], v[198:201], v[116:119]
	v_mfma_f32_16x16x32_bf16 v[104:107], v[152:155], v[206:209], v[104:107]
	v_mfma_f32_16x16x32_bf16 v[100:103], v[176:179], v[206:209], v[100:103]
	v_mfma_f32_16x16x32_bf16 v[88:91], v[152:155], v[214:217], v[88:91]
	v_mfma_f32_16x16x32_bf16 v[84:87], v[176:179], v[214:217], v[84:87]
	v_mfma_f32_16x16x32_bf16 v[72:75], v[152:155], v[222:225], v[72:75]
	v_mfma_f32_16x16x32_bf16 v[68:71], v[176:179], v[222:225], v[68:71]
	s_setprio 0
	s_barrier
	s_add_i32 s0, s57, s45
	s_mov_b32 m0, s0
	ds_read_b128 v[180:183], v195 offset:16384
	ds_read_b128 v[198:201], v195 offset:17408
	ds_read_b128 v[202:205], v195 offset:18432
	ds_read_b128 v[206:209], v195 offset:19456
	ds_read_b128 v[210:213], v195 offset:20480
	ds_read_b128 v[214:217], v195 offset:21504
	ds_read_b128 v[218:221], v195 offset:22528
	ds_read_b128 v[222:225], v195 offset:23552
	global_load_lds_dwordx4 v158, s[42:43]
	s_add_i32 m0, s0, 0x2000
	s_add_u32 s70, s42, 0x2b0000
	s_addc_u32 s71, s43, 0
	s_add_i32 s0, s58, s45
	global_load_lds_dwordx4 v162, s[42:43]
	s_mov_b32 m0, s0
	s_nop 0
	global_load_lds_dwordx4 v158, s[70:71]
	s_add_i32 m0, s0, 0x2000
	s_nop 0
	global_load_lds_dwordx4 v162, s[70:71]
	s_mov_b32 m0, s46
	s_nop 0
	global_load_lds_dwordx4 v156, s[50:51]
	s_mov_b32 m0, s47
	s_nop 0
	global_load_lds_dwordx4 v160, s[50:51]
	s_waitcnt vmcnt(8)
	s_waitcnt lgkmcnt(0)
	s_setprio 1
	s_barrier
	v_mfma_f32_16x16x32_bf16 v[64:67], v[132:135], v[180:183], v[64:67]
	v_mfma_f32_16x16x32_bf16 v[60:63], v[140:143], v[180:183], v[60:63]
	v_mfma_f32_16x16x32_bf16 v[48:51], v[132:135], v[202:205], v[48:51]
	v_mfma_f32_16x16x32_bf16 v[44:47], v[140:143], v[202:205], v[44:47]
	v_mfma_f32_16x16x32_bf16 v[32:35], v[132:135], v[210:213], v[32:35]
	v_mfma_f32_16x16x32_bf16 v[28:31], v[140:143], v[210:213], v[28:31]
	v_mfma_f32_16x16x32_bf16 v[16:19], v[132:135], v[218:221], v[16:19]
	v_mfma_f32_16x16x32_bf16 v[12:15], v[140:143], v[218:221], v[12:15]
	v_mfma_f32_16x16x32_bf16 v[64:67], v[136:139], v[198:201], v[64:67]
	v_mfma_f32_16x16x32_bf16 v[60:63], v[144:147], v[198:201], v[60:63]
	v_mfma_f32_16x16x32_bf16 v[48:51], v[136:139], v[206:209], v[48:51]
	v_mfma_f32_16x16x32_bf16 v[44:47], v[144:147], v[206:209], v[44:47]
	v_mfma_f32_16x16x32_bf16 v[32:35], v[136:139], v[214:217], v[32:35]
	v_mfma_f32_16x16x32_bf16 v[28:31], v[144:147], v[214:217], v[28:31]
	v_mfma_f32_16x16x32_bf16 v[16:19], v[136:139], v[222:225], v[16:19]
	v_mfma_f32_16x16x32_bf16 v[12:15], v[144:147], v[222:225], v[12:15]
	s_setprio 0
	s_setprio 1
	v_mfma_f32_16x16x32_bf16 v[56:59], v[148:151], v[180:183], v[56:59]
	v_mfma_f32_16x16x32_bf16 v[52:55], v[172:175], v[180:183], v[52:55]
	v_mfma_f32_16x16x32_bf16 v[40:43], v[148:151], v[202:205], v[40:43]
	v_mfma_f32_16x16x32_bf16 v[36:39], v[172:175], v[202:205], v[36:39]
	v_mfma_f32_16x16x32_bf16 v[24:27], v[148:151], v[210:213], v[24:27]
	v_mfma_f32_16x16x32_bf16 v[20:23], v[172:175], v[210:213], v[20:23]
	v_mfma_f32_16x16x32_bf16 v[8:11], v[148:151], v[218:221], v[8:11]
	v_mfma_f32_16x16x32_bf16 v[4:7], v[172:175], v[218:221], v[4:7]
	v_mfma_f32_16x16x32_bf16 v[56:59], v[152:155], v[198:201], v[56:59]
	v_mfma_f32_16x16x32_bf16 v[52:55], v[176:179], v[198:201], v[52:55]
	v_mfma_f32_16x16x32_bf16 v[40:43], v[152:155], v[206:209], v[40:43]
	v_mfma_f32_16x16x32_bf16 v[36:39], v[176:179], v[206:209], v[36:39]
	v_mfma_f32_16x16x32_bf16 v[24:27], v[152:155], v[214:217], v[24:27]
	v_mfma_f32_16x16x32_bf16 v[20:23], v[176:179], v[214:217], v[20:23]
	v_mfma_f32_16x16x32_bf16 v[8:11], v[152:155], v[222:225], v[8:11]
	v_mfma_f32_16x16x32_bf16 v[4:7], v[176:179], v[222:225], v[4:7]
	s_setprio 0
	s_barrier
	s_add_i32 s0, 0, 0x18000
	s_add_i32 s67, 0, 0x1c000
	v_add_u32_e32 v144, s0, v191
	v_add_u32_e32 v176, s67, v191
	ds_read_b128 v[132:135], v144
	ds_read_b128 v[136:139], v144 offset:1024
	ds_read_b128 v[140:143], v144 offset:2048
	ds_read_b128 v[144:147], v144 offset:3072
	ds_read_b128 v[148:151], v176
	ds_read_b128 v[152:155], v176 offset:1024
	ds_read_b128 v[172:175], v176 offset:2048
	ds_read_b128 v[176:179], v176 offset:3072
	s_add_u32 s98, s50, 0x2b0000
	s_addc_u32 s99, s51, 0
	s_mov_b32 m0, s48
	ds_read_b128 v[180:183], v195 offset:32768
	ds_read_b128 v[198:201], v195 offset:33792
	ds_read_b128 v[202:205], v195 offset:34816
	ds_read_b128 v[206:209], v195 offset:35840
	ds_read_b128 v[210:213], v195 offset:36864
	ds_read_b128 v[214:217], v195 offset:37888
	ds_read_b128 v[218:221], v195 offset:38912
	ds_read_b128 v[222:225], v195 offset:39936
	global_load_lds_dwordx4 v156, s[98:99]
	s_mov_b32 m0, s49
	s_nop 0
	global_load_lds_dwordx4 v160, s[98:99]
	s_waitcnt vmcnt(8)
	s_waitcnt lgkmcnt(0)
	s_setprio 1
	s_barrier
	v_mfma_f32_16x16x32_bf16 v[128:131], v[132:135], v[180:183], v[128:131]
	v_mfma_f32_16x16x32_bf16 v[124:127], v[140:143], v[180:183], v[124:127]
	v_mfma_f32_16x16x32_bf16 v[112:115], v[132:135], v[202:205], v[112:115]
	v_mfma_f32_16x16x32_bf16 v[108:111], v[140:143], v[202:205], v[108:111]
	v_mfma_f32_16x16x32_bf16 v[96:99], v[132:135], v[210:213], v[96:99]
	v_mfma_f32_16x16x32_bf16 v[92:95], v[140:143], v[210:213], v[92:95]
	v_mfma_f32_16x16x32_bf16 v[80:83], v[132:135], v[218:221], v[80:83]
	v_mfma_f32_16x16x32_bf16 v[76:79], v[140:143], v[218:221], v[76:79]
	v_mfma_f32_16x16x32_bf16 v[128:131], v[136:139], v[198:201], v[128:131]
	v_mfma_f32_16x16x32_bf16 v[124:127], v[144:147], v[198:201], v[124:127]
	v_mfma_f32_16x16x32_bf16 v[112:115], v[136:139], v[206:209], v[112:115]
	v_mfma_f32_16x16x32_bf16 v[108:111], v[144:147], v[206:209], v[108:111]
	v_mfma_f32_16x16x32_bf16 v[96:99], v[136:139], v[214:217], v[96:99]
	v_mfma_f32_16x16x32_bf16 v[92:95], v[144:147], v[214:217], v[92:95]
	v_mfma_f32_16x16x32_bf16 v[80:83], v[136:139], v[222:225], v[80:83]
	v_mfma_f32_16x16x32_bf16 v[76:79], v[144:147], v[222:225], v[76:79]
	s_setprio 0
	s_setprio 1
	v_mfma_f32_16x16x32_bf16 v[120:123], v[148:151], v[180:183], v[120:123]
	v_mfma_f32_16x16x32_bf16 v[116:119], v[172:175], v[180:183], v[116:119]
	v_mfma_f32_16x16x32_bf16 v[104:107], v[148:151], v[202:205], v[104:107]
	v_mfma_f32_16x16x32_bf16 v[100:103], v[172:175], v[202:205], v[100:103]
	v_mfma_f32_16x16x32_bf16 v[88:91], v[148:151], v[210:213], v[88:91]
	v_mfma_f32_16x16x32_bf16 v[84:87], v[172:175], v[210:213], v[84:87]
	v_mfma_f32_16x16x32_bf16 v[72:75], v[148:151], v[218:221], v[72:75]
	v_mfma_f32_16x16x32_bf16 v[68:71], v[172:175], v[218:221], v[68:71]
	v_mfma_f32_16x16x32_bf16 v[120:123], v[152:155], v[198:201], v[120:123]
	v_mfma_f32_16x16x32_bf16 v[116:119], v[176:179], v[198:201], v[116:119]
	v_mfma_f32_16x16x32_bf16 v[104:107], v[152:155], v[206:209], v[104:107]
	v_mfma_f32_16x16x32_bf16 v[100:103], v[176:179], v[206:209], v[100:103]
	v_mfma_f32_16x16x32_bf16 v[88:91], v[152:155], v[214:217], v[88:91]
	v_mfma_f32_16x16x32_bf16 v[84:87], v[176:179], v[214:217], v[84:87]
	v_mfma_f32_16x16x32_bf16 v[72:75], v[152:155], v[222:225], v[72:75]
	v_mfma_f32_16x16x32_bf16 v[68:71], v[176:179], v[222:225], v[68:71]
	s_setprio 0
	s_barrier
	s_add_i32 s0, s0, s45
	s_add_i32 m0, s0, 0xffffff80
	ds_read_b128 v[180:183], v195 offset:49152
	ds_read_b128 v[198:201], v195 offset:50176
	ds_read_b128 v[202:205], v195 offset:51200
	ds_read_b128 v[206:209], v195 offset:52224
	ds_read_b128 v[210:213], v195 offset:53248
	ds_read_b128 v[214:217], v195 offset:54272
	ds_read_b128 v[218:221], v195 offset:55296
	ds_read_b128 v[222:225], v195 offset:56320
	global_load_lds_dwordx4 v158, s[42:43] offset:128
	s_add_i32 m0, s0, 0x1f80
	s_add_i32 s0, s67, s45
	global_load_lds_dwordx4 v162, s[42:43] offset:128
	s_add_u32 s42, s42, 0x2b0080
	s_addc_u32 s43, s43, 0
	s_mov_b32 m0, s0
	s_nop 0
	global_load_lds_dwordx4 v158, s[42:43]
	s_add_i32 m0, s0, 0x2000
	s_nop 0
	global_load_lds_dwordx4 v162, s[42:43]
	s_add_i32 m0, s55, 0xffffff80
	s_nop 0
	global_load_lds_dwordx4 v156, s[50:51] offset:128
	s_add_i32 m0, s56, 0xffffff80
	s_nop 0
	global_load_lds_dwordx4 v160, s[50:51] offset:128
	s_waitcnt vmcnt(8)
	s_waitcnt lgkmcnt(0)
	s_setprio 1
	s_barrier
	v_mfma_f32_16x16x32_bf16 v[64:67], v[132:135], v[180:183], v[64:67]
	v_mfma_f32_16x16x32_bf16 v[60:63], v[140:143], v[180:183], v[60:63]
	v_mfma_f32_16x16x32_bf16 v[48:51], v[132:135], v[202:205], v[48:51]
	v_mfma_f32_16x16x32_bf16 v[44:47], v[140:143], v[202:205], v[44:47]
	v_mfma_f32_16x16x32_bf16 v[32:35], v[132:135], v[210:213], v[32:35]
	v_mfma_f32_16x16x32_bf16 v[28:31], v[140:143], v[210:213], v[28:31]
	v_mfma_f32_16x16x32_bf16 v[16:19], v[132:135], v[218:221], v[16:19]
	v_mfma_f32_16x16x32_bf16 v[12:15], v[140:143], v[218:221], v[12:15]
	v_mfma_f32_16x16x32_bf16 v[64:67], v[136:139], v[198:201], v[64:67]
	v_mfma_f32_16x16x32_bf16 v[60:63], v[144:147], v[198:201], v[60:63]
	v_mfma_f32_16x16x32_bf16 v[48:51], v[136:139], v[206:209], v[48:51]
	v_mfma_f32_16x16x32_bf16 v[44:47], v[144:147], v[206:209], v[44:47]
	v_mfma_f32_16x16x32_bf16 v[32:35], v[136:139], v[214:217], v[32:35]
	v_mfma_f32_16x16x32_bf16 v[28:31], v[144:147], v[214:217], v[28:31]
	v_mfma_f32_16x16x32_bf16 v[16:19], v[136:139], v[222:225], v[16:19]
	v_mfma_f32_16x16x32_bf16 v[12:15], v[144:147], v[222:225], v[12:15]
	s_setprio 0
	s_setprio 1
	v_mfma_f32_16x16x32_bf16 v[56:59], v[148:151], v[180:183], v[56:59]
	v_mfma_f32_16x16x32_bf16 v[52:55], v[172:175], v[180:183], v[52:55]
	v_mfma_f32_16x16x32_bf16 v[40:43], v[148:151], v[202:205], v[40:43]
	v_mfma_f32_16x16x32_bf16 v[36:39], v[172:175], v[202:205], v[36:39]
	v_mfma_f32_16x16x32_bf16 v[24:27], v[148:151], v[210:213], v[24:27]
	v_mfma_f32_16x16x32_bf16 v[20:23], v[172:175], v[210:213], v[20:23]
	v_mfma_f32_16x16x32_bf16 v[8:11], v[148:151], v[218:221], v[8:11]
	v_mfma_f32_16x16x32_bf16 v[4:7], v[172:175], v[218:221], v[4:7]
	v_mfma_f32_16x16x32_bf16 v[56:59], v[152:155], v[198:201], v[56:59]
	v_mfma_f32_16x16x32_bf16 v[52:55], v[176:179], v[198:201], v[52:55]
	v_mfma_f32_16x16x32_bf16 v[40:43], v[152:155], v[206:209], v[40:43]
	v_mfma_f32_16x16x32_bf16 v[36:39], v[176:179], v[206:209], v[36:39]
	v_mfma_f32_16x16x32_bf16 v[24:27], v[152:155], v[214:217], v[24:27]
	v_mfma_f32_16x16x32_bf16 v[20:23], v[176:179], v[214:217], v[20:23]
	v_mfma_f32_16x16x32_bf16 v[8:11], v[152:155], v[222:225], v[8:11]
	v_mfma_f32_16x16x32_bf16 v[4:7], v[176:179], v[222:225], v[4:7]
	s_setprio 0
	s_barrier
	s_add_i32 s66, s66, 2
	s_add_u32 s30, s30, 0x100
	s_addc_u32 s31, s31, 0
	s_add_u32 s64, s64, 0x100
	s_addc_u32 s65, s65, 0
	s_cmpk_gt_u32 s66, 0xa9
	s_cbranch_scc0 .LBB0_1672
	s_and_b64 vcc, exec, s[24:25]
	s_cbranch_vccz .LBB0_1675
	s_barrier

.LBB0_1703:
	ds_read_b128 v[136:139], v196
	ds_read_b128 v[140:143], v196 offset:1024
	ds_read_b128 v[144:147], v196 offset:2048
	ds_read_b128 v[148:151], v196 offset:3072
	ds_read_b128 v[152:155], v197
	ds_read_b128 v[176:179], v197 offset:1024
	ds_read_b128 v[180:183], v197 offset:2048
	ds_read_b128 v[184:187], v197 offset:3072
	s_add_u32 s8, s6, 0x100
	s_addc_u32 s9, s7, 0
	s_add_u32 s0, s65, s6
	s_addc_u32 s40, s66, s7
	s_cmpk_eq_i32 s67, 0xa8
	s_cselect_b32 s43, s50, s40
	s_cselect_b32 s40, 0, s8
	s_cselect_b32 s42, s51, s0
	s_cselect_b32 s0, 0, s9
	s_add_u32 s40, s16, s40
	s_addc_u32 s41, s17, s0
	s_mov_b32 m0, s58
	v_lshl_add_u64 v[226:227], v[132:133], 0, s[6:7]
	ds_read_b128 v[188:191], v198
	ds_read_b128 v[192:195], v198 offset:1024
	ds_read_b128 v[202:205], v198 offset:2048
	ds_read_b128 v[206:209], v198 offset:3072
	ds_read_b128 v[210:213], v198 offset:4096
	ds_read_b128 v[214:217], v198 offset:5120
	ds_read_b128 v[218:221], v198 offset:6144
	ds_read_b128 v[222:225], v198 offset:7168
	global_load_lds_dwordx4 v[226:227], off
	v_lshl_add_u64 v[226:227], v[134:135], 0, s[6:7]
	s_mov_b32 m0, s59
	s_nop 0
	global_load_lds_dwordx4 v[226:227], off
	s_waitcnt vmcnt(8)
	s_waitcnt lgkmcnt(0)
	s_setprio 1
	s_barrier
	v_mfma_f32_16x16x32_bf16 v[128:131], v[136:139], v[188:191], v[128:131]
	v_mfma_f32_16x16x32_bf16 v[124:127], v[144:147], v[188:191], v[124:127]
	v_mfma_f32_16x16x32_bf16 v[112:115], v[136:139], v[202:205], v[112:115]
	v_mfma_f32_16x16x32_bf16 v[108:111], v[144:147], v[202:205], v[108:111]
	v_mfma_f32_16x16x32_bf16 v[96:99], v[136:139], v[210:213], v[96:99]
	v_mfma_f32_16x16x32_bf16 v[92:95], v[144:147], v[210:213], v[92:95]
	v_mfma_f32_16x16x32_bf16 v[80:83], v[136:139], v[218:221], v[80:83]
	v_mfma_f32_16x16x32_bf16 v[76:79], v[144:147], v[218:221], v[76:79]
	v_mfma_f32_16x16x32_bf16 v[128:131], v[140:143], v[192:195], v[128:131]
	v_mfma_f32_16x16x32_bf16 v[124:127], v[148:151], v[192:195], v[124:127]
	v_mfma_f32_16x16x32_bf16 v[112:115], v[140:143], v[206:209], v[112:115]
	v_mfma_f32_16x16x32_bf16 v[108:111], v[148:151], v[206:209], v[108:111]
	v_mfma_f32_16x16x32_bf16 v[96:99], v[140:143], v[214:217], v[96:99]
	v_mfma_f32_16x16x32_bf16 v[92:95], v[148:151], v[214:217], v[92:95]
	v_mfma_f32_16x16x32_bf16 v[80:83], v[140:143], v[222:225], v[80:83]
	v_mfma_f32_16x16x32_bf16 v[76:79], v[148:151], v[222:225], v[76:79]
	s_setprio 0
	s_setprio 1
	v_mfma_f32_16x16x32_bf16 v[120:123], v[152:155], v[188:191], v[120:123]
	v_mfma_f32_16x16x32_bf16 v[116:119], v[180:183], v[188:191], v[116:119]
	v_mfma_f32_16x16x32_bf16 v[104:107], v[152:155], v[202:205], v[104:107]
	v_mfma_f32_16x16x32_bf16 v[100:103], v[180:183], v[202:205], v[100:103]
	v_mfma_f32_16x16x32_bf16 v[88:91], v[152:155], v[210:213], v[88:91]
	v_mfma_f32_16x16x32_bf16 v[84:87], v[180:183], v[210:213], v[84:87]
	v_mfma_f32_16x16x32_bf16 v[72:75], v[152:155], v[218:221], v[72:75]
	v_mfma_f32_16x16x32_bf16 v[68:71], v[180:183], v[218:221], v[68:71]
	v_mfma_f32_16x16x32_bf16 v[120:123], v[176:179], v[192:195], v[120:123]
	v_mfma_f32_16x16x32_bf16 v[116:119], v[184:187], v[192:195], v[116:119]
	v_mfma_f32_16x16x32_bf16 v[104:107], v[176:179], v[206:209], v[104:107]
	v_mfma_f32_16x16x32_bf16 v[100:103], v[184:187], v[206:209], v[100:103]
	v_mfma_f32_16x16x32_bf16 v[88:91], v[176:179], v[214:217], v[88:91]
	v_mfma_f32_16x16x32_bf16 v[84:87], v[184:187], v[214:217], v[84:87]
	v_mfma_f32_16x16x32_bf16 v[72:75], v[176:179], v[222:225], v[72:75]
	v_mfma_f32_16x16x32_bf16 v[68:71], v[184:187], v[222:225], v[68:71]
	s_setprio 0
	s_barrier
	s_mov_b32 m0, s60
	v_lshl_add_u64 v[226:227], s[40:41], 0, v[158:159]
	s_add_u32 s6, s40, 0x2b0000
	ds_read_b128 v[188:191], v198 offset:16384
	ds_read_b128 v[192:195], v198 offset:17408
	ds_read_b128 v[202:205], v198 offset:18432
	ds_read_b128 v[206:209], v198 offset:19456
	ds_read_b128 v[210:213], v198 offset:20480
	ds_read_b128 v[214:217], v198 offset:21504
	ds_read_b128 v[218:221], v198 offset:22528
	ds_read_b128 v[222:225], v198 offset:23552
	global_load_lds_dwordx4 v[226:227], off
	v_lshl_add_u64 v[228:229], s[40:41], 0, v[162:163]
	s_mov_b32 m0, s61
	s_addc_u32 s7, s41, 0
	global_load_lds_dwordx4 v[228:229], off
	v_lshl_add_u64 v[230:231], s[6:7], 0, v[158:159]
	s_mov_b32 m0, s62
	v_lshl_add_u64 v[232:233], s[42:43], 0, v[160:161]
	global_load_lds_dwordx4 v[230:231], off
	v_lshl_add_u64 v[230:231], s[6:7], 0, v[162:163]
	s_mov_b32 m0, s63
	s_nop 0
	global_load_lds_dwordx4 v[230:231], off
	v_lshl_add_u64 v[230:231], s[42:43], 0, v[156:157]
	s_mov_b32 m0, s46
	s_nop 0
	global_load_lds_dwordx4 v[230:231], off
	s_mov_b32 m0, s47
	s_nop 0
	global_load_lds_dwordx4 v[232:233], off
	s_waitcnt vmcnt(8)
	s_waitcnt lgkmcnt(0)
	s_setprio 1
	s_barrier
	v_mfma_f32_16x16x32_bf16 v[64:67], v[136:139], v[188:191], v[64:67]
	v_mfma_f32_16x16x32_bf16 v[60:63], v[144:147], v[188:191], v[60:63]
	v_mfma_f32_16x16x32_bf16 v[48:51], v[136:139], v[202:205], v[48:51]
	v_mfma_f32_16x16x32_bf16 v[44:47], v[144:147], v[202:205], v[44:47]
	v_mfma_f32_16x16x32_bf16 v[32:35], v[136:139], v[210:213], v[32:35]
	v_mfma_f32_16x16x32_bf16 v[28:31], v[144:147], v[210:213], v[28:31]
	v_mfma_f32_16x16x32_bf16 v[16:19], v[136:139], v[218:221], v[16:19]
	v_mfma_f32_16x16x32_bf16 v[12:15], v[144:147], v[218:221], v[12:15]
	v_mfma_f32_16x16x32_bf16 v[64:67], v[140:143], v[192:195], v[64:67]
	v_mfma_f32_16x16x32_bf16 v[60:63], v[148:151], v[192:195], v[60:63]
	v_mfma_f32_16x16x32_bf16 v[48:51], v[140:143], v[206:209], v[48:51]
	v_mfma_f32_16x16x32_bf16 v[44:47], v[148:151], v[206:209], v[44:47]
	v_mfma_f32_16x16x32_bf16 v[32:35], v[140:143], v[214:217], v[32:35]
	v_mfma_f32_16x16x32_bf16 v[28:31], v[148:151], v[214:217], v[28:31]
	v_mfma_f32_16x16x32_bf16 v[16:19], v[140:143], v[222:225], v[16:19]
	v_mfma_f32_16x16x32_bf16 v[12:15], v[148:151], v[222:225], v[12:15]
	s_setprio 0
	s_setprio 1
	v_mfma_f32_16x16x32_bf16 v[56:59], v[152:155], v[188:191], v[56:59]
	v_mfma_f32_16x16x32_bf16 v[52:55], v[180:183], v[188:191], v[52:55]
	v_mfma_f32_16x16x32_bf16 v[40:43], v[152:155], v[202:205], v[40:43]
	v_mfma_f32_16x16x32_bf16 v[36:39], v[180:183], v[202:205], v[36:39]
	v_mfma_f32_16x16x32_bf16 v[24:27], v[152:155], v[210:213], v[24:27]
	v_mfma_f32_16x16x32_bf16 v[20:23], v[180:183], v[210:213], v[20:23]
	v_mfma_f32_16x16x32_bf16 v[8:11], v[152:155], v[218:221], v[8:11]
	v_mfma_f32_16x16x32_bf16 v[4:7], v[180:183], v[218:221], v[4:7]
	v_mfma_f32_16x16x32_bf16 v[56:59], v[176:179], v[192:195], v[56:59]
	v_mfma_f32_16x16x32_bf16 v[52:55], v[184:187], v[192:195], v[52:55]
	v_mfma_f32_16x16x32_bf16 v[40:43], v[176:179], v[206:209], v[40:43]
	v_mfma_f32_16x16x32_bf16 v[36:39], v[184:187], v[206:209], v[36:39]
	v_mfma_f32_16x16x32_bf16 v[24:27], v[176:179], v[214:217], v[24:27]
	v_mfma_f32_16x16x32_bf16 v[20:23], v[184:187], v[214:217], v[20:23]
	v_mfma_f32_16x16x32_bf16 v[8:11], v[176:179], v[222:225], v[8:11]
	v_mfma_f32_16x16x32_bf16 v[4:7], v[184:187], v[222:225], v[4:7]
	s_setprio 0
	s_barrier
	s_add_i32 s0, 0, 0x18000
	s_add_i32 s68, 0, 0x1c000
	v_add_u32_e32 v148, s0, v3
	v_add_u32_e32 v170, s68, v3
	ds_read_b128 v[136:139], v148
	ds_read_b128 v[140:143], v148 offset:1024
	ds_read_b128 v[144:147], v148 offset:2048
	ds_read_b128 v[148:151], v148 offset:3072
	ds_read_b128 v[152:155], v170
	ds_read_b128 v[176:179], v170 offset:1024
	ds_read_b128 v[180:183], v170 offset:2048
	ds_read_b128 v[184:187], v170 offset:3072
	s_add_u32 s6, s42, 0x2b0000
	s_addc_u32 s7, s43, 0
	s_mov_b32 m0, s48
	v_lshl_add_u64 v[234:235], s[6:7], 0, v[156:157]
	ds_read_b128 v[188:191], v198 offset:32768
	ds_read_b128 v[192:195], v198 offset:33792
	ds_read_b128 v[202:205], v198 offset:34816
	ds_read_b128 v[206:209], v198 offset:35840
	ds_read_b128 v[210:213], v198 offset:36864
	ds_read_b128 v[214:217], v198 offset:37888
	ds_read_b128 v[218:221], v198 offset:38912
	ds_read_b128 v[222:225], v198 offset:39936
	global_load_lds_dwordx4 v[234:235], off
	v_lshl_add_u64 v[234:235], s[6:7], 0, v[160:161]
	s_mov_b32 m0, s49
	s_nop 0
	global_load_lds_dwordx4 v[234:235], off
	s_waitcnt vmcnt(8)
	s_waitcnt lgkmcnt(0)
	s_setprio 1
	s_barrier
	v_mfma_f32_16x16x32_bf16 v[128:131], v[136:139], v[188:191], v[128:131]
	v_mfma_f32_16x16x32_bf16 v[124:127], v[144:147], v[188:191], v[124:127]
	v_mfma_f32_16x16x32_bf16 v[112:115], v[136:139], v[202:205], v[112:115]
	v_mfma_f32_16x16x32_bf16 v[108:111], v[144:147], v[202:205], v[108:111]
	v_mfma_f32_16x16x32_bf16 v[96:99], v[136:139], v[210:213], v[96:99]
	v_mfma_f32_16x16x32_bf16 v[92:95], v[144:147], v[210:213], v[92:95]
	v_mfma_f32_16x16x32_bf16 v[80:83], v[136:139], v[218:221], v[80:83]
	v_mfma_f32_16x16x32_bf16 v[76:79], v[144:147], v[218:221], v[76:79]
	v_mfma_f32_16x16x32_bf16 v[128:131], v[140:143], v[192:195], v[128:131]
	v_mfma_f32_16x16x32_bf16 v[124:127], v[148:151], v[192:195], v[124:127]
	v_mfma_f32_16x16x32_bf16 v[112:115], v[140:143], v[206:209], v[112:115]
	v_mfma_f32_16x16x32_bf16 v[108:111], v[148:151], v[206:209], v[108:111]
	v_mfma_f32_16x16x32_bf16 v[96:99], v[140:143], v[214:217], v[96:99]
	v_mfma_f32_16x16x32_bf16 v[92:95], v[148:151], v[214:217], v[92:95]
	v_mfma_f32_16x16x32_bf16 v[80:83], v[140:143], v[222:225], v[80:83]
	v_mfma_f32_16x16x32_bf16 v[76:79], v[148:151], v[222:225], v[76:79]
	s_setprio 0
	s_setprio 1
	v_mfma_f32_16x16x32_bf16 v[120:123], v[152:155], v[188:191], v[120:123]
	v_mfma_f32_16x16x32_bf16 v[116:119], v[180:183], v[188:191], v[116:119]
	v_mfma_f32_16x16x32_bf16 v[104:107], v[152:155], v[202:205], v[104:107]
	v_mfma_f32_16x16x32_bf16 v[100:103], v[180:183], v[202:205], v[100:103]
	v_mfma_f32_16x16x32_bf16 v[88:91], v[152:155], v[210:213], v[88:91]
	v_mfma_f32_16x16x32_bf16 v[84:87], v[180:183], v[210:213], v[84:87]
	v_mfma_f32_16x16x32_bf16 v[72:75], v[152:155], v[218:221], v[72:75]
	v_mfma_f32_16x16x32_bf16 v[68:71], v[180:183], v[218:221], v[68:71]
	v_mfma_f32_16x16x32_bf16 v[120:123], v[176:179], v[192:195], v[120:123]
	v_mfma_f32_16x16x32_bf16 v[116:119], v[184:187], v[192:195], v[116:119]
	v_mfma_f32_16x16x32_bf16 v[104:107], v[176:179], v[206:209], v[104:107]
	v_mfma_f32_16x16x32_bf16 v[100:103], v[184:187], v[206:209], v[100:103]
	v_mfma_f32_16x16x32_bf16 v[88:91], v[176:179], v[214:217], v[88:91]
	v_mfma_f32_16x16x32_bf16 v[84:87], v[184:187], v[214:217], v[84:87]
	v_mfma_f32_16x16x32_bf16 v[72:75], v[176:179], v[222:225], v[72:75]
	v_mfma_f32_16x16x32_bf16 v[68:71], v[184:187], v[222:225], v[68:71]
	s_setprio 0
	s_barrier
	s_add_i32 s0, s0, s45
	v_lshl_add_u64 v[226:227], v[226:227], 0, s[28:29]
	s_mov_b32 m0, s0
	ds_read_b128 v[188:191], v198 offset:49152
	ds_read_b128 v[192:195], v198 offset:50176
	ds_read_b128 v[202:205], v198 offset:51200
	ds_read_b128 v[206:209], v198 offset:52224
	ds_read_b128 v[210:213], v198 offset:53248
	ds_read_b128 v[214:217], v198 offset:54272
	ds_read_b128 v[218:221], v198 offset:55296
	ds_read_b128 v[222:225], v198 offset:56320
	global_load_lds_dwordx4 v[226:227], off
	s_add_i32 m0, s0, 0x2000
	s_add_u32 s6, s40, 0x2b0080
	v_lshl_add_u64 v[226:227], v[228:229], 0, s[28:29]
	s_addc_u32 s7, s41, 0
	s_add_i32 s0, s68, s45
	global_load_lds_dwordx4 v[226:227], off
	v_lshl_add_u64 v[226:227], s[6:7], 0, v[158:159]
	s_mov_b32 m0, s0
	s_nop 0
	global_load_lds_dwordx4 v[226:227], off
	v_lshl_add_u64 v[226:227], s[6:7], 0, v[162:163]
	s_add_i32 m0, s0, 0x2000
	s_nop 0
	global_load_lds_dwordx4 v[226:227], off
	v_lshl_add_u64 v[226:227], v[230:231], 0, s[28:29]
	s_mov_b32 m0, s54
	s_nop 0
	global_load_lds_dwordx4 v[226:227], off
	v_lshl_add_u64 v[226:227], v[232:233], 0, s[28:29]
	s_mov_b32 m0, s55
	s_nop 0
	global_load_lds_dwordx4 v[226:227], off
	s_waitcnt vmcnt(8)
	s_waitcnt lgkmcnt(0)
	s_setprio 1
	s_barrier
	v_mfma_f32_16x16x32_bf16 v[64:67], v[136:139], v[188:191], v[64:67]
	v_mfma_f32_16x16x32_bf16 v[60:63], v[144:147], v[188:191], v[60:63]
	v_mfma_f32_16x16x32_bf16 v[48:51], v[136:139], v[202:205], v[48:51]
	v_mfma_f32_16x16x32_bf16 v[44:47], v[144:147], v[202:205], v[44:47]
	v_mfma_f32_16x16x32_bf16 v[32:35], v[136:139], v[210:213], v[32:35]
	v_mfma_f32_16x16x32_bf16 v[28:31], v[144:147], v[210:213], v[28:31]
	v_mfma_f32_16x16x32_bf16 v[16:19], v[136:139], v[218:221], v[16:19]
	v_mfma_f32_16x16x32_bf16 v[12:15], v[144:147], v[218:221], v[12:15]
	v_mfma_f32_16x16x32_bf16 v[64:67], v[140:143], v[192:195], v[64:67]
	v_mfma_f32_16x16x32_bf16 v[60:63], v[148:151], v[192:195], v[60:63]
	v_mfma_f32_16x16x32_bf16 v[48:51], v[140:143], v[206:209], v[48:51]
	v_mfma_f32_16x16x32_bf16 v[44:47], v[148:151], v[206:209], v[44:47]
	v_mfma_f32_16x16x32_bf16 v[32:35], v[140:143], v[214:217], v[32:35]
	v_mfma_f32_16x16x32_bf16 v[28:31], v[148:151], v[214:217], v[28:31]
	v_mfma_f32_16x16x32_bf16 v[16:19], v[140:143], v[222:225], v[16:19]
	v_mfma_f32_16x16x32_bf16 v[12:15], v[148:151], v[222:225], v[12:15]
	s_setprio 0
	s_setprio 1
	v_mfma_f32_16x16x32_bf16 v[56:59], v[152:155], v[188:191], v[56:59]
	v_mfma_f32_16x16x32_bf16 v[52:55], v[180:183], v[188:191], v[52:55]
	v_mfma_f32_16x16x32_bf16 v[40:43], v[152:155], v[202:205], v[40:43]
	v_mfma_f32_16x16x32_bf16 v[36:39], v[180:183], v[202:205], v[36:39]
	v_mfma_f32_16x16x32_bf16 v[24:27], v[152:155], v[210:213], v[24:27]
	v_mfma_f32_16x16x32_bf16 v[20:23], v[180:183], v[210:213], v[20:23]
	v_mfma_f32_16x16x32_bf16 v[8:11], v[152:155], v[218:221], v[8:11]
	v_mfma_f32_16x16x32_bf16 v[4:7], v[180:183], v[218:221], v[4:7]
	v_mfma_f32_16x16x32_bf16 v[56:59], v[176:179], v[192:195], v[56:59]
	v_mfma_f32_16x16x32_bf16 v[52:55], v[184:187], v[192:195], v[52:55]
	v_mfma_f32_16x16x32_bf16 v[40:43], v[176:179], v[206:209], v[40:43]
	v_mfma_f32_16x16x32_bf16 v[36:39], v[184:187], v[206:209], v[36:39]
	v_mfma_f32_16x16x32_bf16 v[24:27], v[176:179], v[214:217], v[24:27]
	v_mfma_f32_16x16x32_bf16 v[20:23], v[184:187], v[214:217], v[20:23]
	v_mfma_f32_16x16x32_bf16 v[8:11], v[176:179], v[222:225], v[8:11]
	v_mfma_f32_16x16x32_bf16 v[4:7], v[184:187], v[222:225], v[4:7]
	s_setprio 0
	s_barrier
	s_add_i32 s67, s67, 2
	s_cmpk_gt_u32 s67, 0xa9
	s_mov_b64 s[6:7], s[8:9]
	s_cbranch_scc0 .LBB0_1703
	s_and_b64 vcc, exec, s[30:31]
	s_cbranch_vccz .LBB0_1706
	s_barrier
